# gdn1 forward substitution: four per-wave unrolled variants replaced by one shared stream with ring-prefetched broadcast L reads
# speedup vs baseline: 1.0077x; 1.0077x over previous
.LBB0_684:
	s_or_b64 exec, exec, s[10:11]
	v_and_b32_e32 v6, 48, v46
	v_and_b32_e32 v0, 15, v47
	v_add_u32_e32 v51, 0, v6
	s_movk_i32 s3, 0x90
	v_or_b32_e32 v50, v48, v0
	v_mad_u32_u24 v0, v0, s3, v51
	s_waitcnt lgkmcnt(0)
	s_barrier
	ds_read_b128 v[2:5], v0 offset:9216
	v_mul_lo_u32 v7, v50, s3
	v_add_u32_e32 v48, 0, v7
	v_add_u32_e32 v22, v48, v6
	ds_read_b128 v[6:9], v22 offset:9216
	ds_read_b128 v[38:41], v22 offset:9280
	ds_read_b128 v[10:13], v0 offset:9280
	ds_read_b128 v[18:21], v22
	ds_read_b128 v[42:45], v22 offset:64
	ds_read_b128 v[22:25], v0 offset:11520
	ds_read_b128 v[26:29], v0 offset:13824
	ds_read_b128 v[52:55], v0 offset:11584
	v_lshlrev_b32_e32 v30, 4, v47
	v_and_b32_e32 v88, 48, v30
	v_ashrrev_i32_e32 v49, 2, v47
	v_mul_u32_u24_e32 v31, 0x48, v88
	v_lshlrev_b32_e32 v30, 1, v49
	v_lshlrev_b32_e32 v31, 1, v31
	s_waitcnt lgkmcnt(1)
	v_mfma_f32_16x16x32_bf16 v[68:71], v[26:29], v[6:9], 0
	s_lshl_b64 s[8:9], s[16:17], 12
	v_add3_u32 v87, 0, v31, v30
	s_lshl_b64 s[8:9], s[8:9], 1
	v_mfma_f32_16x16x32_bf16 v[72:75], v[26:29], v[18:21], 0
	v_add3_u32 v26, 0, v30, v31
	s_add_u32 s8, s4, s8
	s_addc_u32 s9, s5, s9
	v_mfma_f32_16x16x32_bf16 v[56:59], v[22:25], v[6:9], 0
	s_mov_b32 s3, 0xc427000
	v_mfma_f32_16x16x32_bf16 v[60:63], v[22:25], v[18:21], 0
	ds_read_b128 v[22:25], v0 offset:16128
	ds_read_b128 v[64:67], v0 offset:13888
	ds_read_b128 v[76:79], v0 offset:16192
	ds_read_u16 v0, v26 offset:9216
	ds_read_u16 v27, v26 offset:9504
	ds_read_u16 v28, v26 offset:9792
	v_mfma_f32_16x16x32_bf16 v[14:17], v[2:5], v[6:9], 0
	v_mfma_f32_16x16x32_bf16 v[2:5], v[2:5], v[18:21], 0
	s_waitcnt lgkmcnt(5)
	v_mfma_f32_16x16x32_bf16 v[6:9], v[22:25], v[6:9], 0
	v_mfma_f32_16x16x32_bf16 v[80:83], v[22:25], v[18:21], 0
	ds_read_u16 v18, v87 offset:9360
	ds_read_u16 v19, v87 offset:9648
	ds_read_u16 v20, v87 offset:9936
	ds_read_u16 v21, v26 offset:10080
	ds_read_u16 v22, v26 offset:10368
	ds_read_u16 v89, v26 offset:10656
	ds_read_u16 v90, v26 offset:10944
	ds_read_u16 v91, v26 offset:11232
	ds_read_b128 v[34:37], v51 offset:60416
	s_waitcnt lgkmcnt(8)
	v_lshl_or_b32 v84, v18, 16, v0
	v_mfma_f32_16x16x32_bf16 v[30:33], v[10:13], v[38:41], v[14:17]
	s_waitcnt lgkmcnt(7)
	v_lshl_or_b32 v85, v19, 16, v27
	s_waitcnt lgkmcnt(6)
	v_lshl_or_b32 v86, v20, 16, v28
	v_mfma_f32_16x16x32_bf16 v[26:29], v[10:13], v[42:45], v[2:5]
	ds_read_u16 v0, v87 offset:10224
	s_nop 1
	ds_read_u16 v2, v87 offset:10512
	ds_read_u16 v3, v87 offset:10800
	ds_read_u16 v4, v87 offset:11088
	ds_read_u16 v5, v87 offset:11376
	v_lshlrev_b32_e32 v10, 6, v49
	v_ashrrev_i32_e32 v11, 31, v10
	s_waitcnt lgkmcnt(4)
	v_lshl_or_b32 v87, v0, 16, v21
	s_waitcnt lgkmcnt(3)
	v_lshl_or_b32 v2, v2, 16, v22
	v_mfma_f32_16x16x32_bf16 v[22:25], v[52:55], v[38:41], v[56:59]
	v_lshlrev_b32_e32 v0, 1, v88
	s_waitcnt lgkmcnt(2)
	v_lshl_or_b32 v3, v3, 16, v89
	s_waitcnt lgkmcnt(1)
	v_lshl_or_b32 v4, v4, 16, v90
	v_mfma_f32_16x16x32_bf16 v[18:21], v[52:55], v[42:45], v[60:63]
	v_lshl_add_u64 v[52:53], v[10:11], 1, s[8:9]
	v_lshl_add_u64 v[52:53], v[52:53], 0, v[0:1]
	s_mov_b64 s[8:9], 0xc427800
	v_mfma_f32_16x16x32_bf16 v[14:17], v[64:67], v[38:41], v[68:71]
	s_waitcnt lgkmcnt(0)
	v_lshl_or_b32 v5, v5, 16, v91
	v_lshl_add_u64 v[54:55], v[52:53], 0, s[8:9]
	v_lshlrev_b32_e32 v0, 2, v50
	v_mfma_f32_16x16x32_bf16 v[6:9], v[76:79], v[38:41], v[6:9]
	v_add_co_u32_e32 v38, vcc, s3, v52
	s_movk_i32 s3, 0xff74
	s_nop 0
	v_addc_co_u32_e32 v39, vcc, 0, v53, vcc
	global_store_dwordx4 v[38:39], v[84:87], off offset:2048
	global_store_dwordx4 v[54:55], v[2:5], off offset:16
	v_mad_u64_u32 v[38:39], s[8:9], v50, s3, v[48:49]
	v_mfma_f32_16x16x32_bf16 v[10:13], v[64:67], v[42:45], v[72:75]
	v_sub_u32_e32 v0, 0, v0
	v_add_u32_e32 v0, 0xfc, v0
	v_lshl_add_u32 v52, v50, 8, 0
	v_mfma_f32_16x16x32_bf16 v[2:5], v[76:79], v[42:45], v[80:83]
	ds_read2st64_b32 v[44:45], v38 offset0:236 offset1:238
	ds_read2st64_b32 v[42:43], v0 offset0:237 offset1:239
	v_lshrrev_b32_e32 v0, 2, v46
	v_and_b32_e32 v46, 12, v0
	v_sub_co_u32_e32 v48, vcc, 0, v46
	s_waitcnt lgkmcnt(1)
	v_sub_f32_e32 v0, v44, v34
	v_mul_f32_e32 v0, 0x3fb8aa3b, v0
	v_lshl_add_u32 v34, v48, 2, 0
	v_exp_f32_e32 v0, v0
	ds_read_b128 v[38:41], v34 offset:60912
	v_subb_co_u32_e64 v49, s[8:9], 0, 0, vcc
	v_cmp_gt_i32_e64 s[10:11], v46, v50
	v_cmp_ge_i32_e32 vcc, v46, v50
	v_cmp_lt_i32_e64 s[8:9], v46, v50
	v_cndmask_b32_e64 v0, v0, 0, s[10:11]
	v_lshl_add_u32 v52, v46, 2, v52
	s_and_saveexec_b64 s[20:21], s[8:9]
	v_mul_f32_e32 v34, v30, v45
	v_mul_f32_e32 v34, v34, v0
	ds_write_b32 v52, v34 offset:27648
	s_or_b64 exec, exec, s[20:21]
	s_waitcnt lgkmcnt(0)
	v_sub_f32_e32 v34, v42, v41
	v_mul_f32_e32 v34, 0x3fb8aa3b, v34
	v_exp_f32_e32 v41, v34
	v_lshlrev_b32_e32 v34, 6, v50
	v_cndmask_b32_e64 v41, v41, 0, s[8:9]
	s_and_saveexec_b64 s[20:21], s[10:11]
	v_mul_f32_e32 v30, v30, v43
	v_add_lshl_u32 v53, v34, v46, 2
	v_mul_f32_e32 v30, v30, v41
	v_sub_u32_e32 v53, 0, v53
	ds_write_b32 v53, v30 offset:60412
	s_or_b64 exec, exec, s[20:21]
	v_sub_f32_e32 v30, v44, v35
	v_mul_f32_e32 v30, 0x3fb8aa3b, v30
	v_exp_f32_e32 v30, v30
	v_or_b32_e32 v53, 1, v46
	v_cndmask_b32_e64 v30, 0, v30, s[8:9]
	v_cmp_lt_i32_e64 s[8:9], v53, v50
	s_and_saveexec_b64 s[10:11], s[8:9]
	v_mul_f32_e32 v35, v31, v45
	v_mul_f32_e32 v35, v35, v30
	ds_write_b32 v52, v35 offset:27652
	s_or_b64 exec, exec, s[10:11]
	v_sub_f32_e32 v35, v42, v40
	v_mul_f32_e32 v35, 0x3fb8aa3b, v35
	v_exp_f32_e32 v35, v35
	s_nop 0
	v_cndmask_b32_e64 v35, v35, 0, s[8:9]
	s_and_saveexec_b64 s[8:9], vcc
	v_mul_f32_e32 v31, v31, v43
	v_add_lshl_u32 v40, v34, v53, 2
	v_mul_f32_e32 v31, v31, v35
	v_sub_u32_e32 v40, 0, v40
	ds_write_b32 v40, v31 offset:60412
	s_or_b64 exec, exec, s[8:9]
	v_sub_f32_e32 v31, v44, v36
	v_mul_f32_e32 v31, 0x3fb8aa3b, v31
	v_exp_f32_e32 v31, v31
	v_or_b32_e32 v40, 2, v46
	v_cmp_gt_i32_e32 vcc, v40, v50
	v_cmp_lt_i32_e64 s[8:9], v40, v50
	s_nop 0
	v_cndmask_b32_e64 v31, v31, 0, vcc
	s_and_saveexec_b64 s[10:11], s[8:9]
	v_mul_f32_e32 v36, v32, v45
	v_mul_f32_e32 v36, v36, v31
	ds_write_b32 v52, v36 offset:27656
	s_or_b64 exec, exec, s[10:11]
	v_sub_f32_e32 v36, v42, v39
	v_mul_f32_e32 v36, 0x3fb8aa3b, v36
	v_exp_f32_e32 v36, v36
	s_nop 0
	v_cndmask_b32_e64 v36, v36, 0, s[8:9]
	s_and_saveexec_b64 s[8:9], vcc
	v_mul_f32_e32 v32, v32, v43
	v_add_lshl_u32 v39, v34, v40, 2
	v_mul_f32_e32 v32, v32, v36
	v_sub_u32_e32 v39, 0, v39
	ds_write_b32 v39, v32 offset:60412
	s_or_b64 exec, exec, s[8:9]
	v_sub_f32_e32 v32, v44, v37
	v_mul_f32_e32 v32, 0x3fb8aa3b, v32
	v_exp_f32_e32 v32, v32
	v_or_b32_e32 v39, 3, v46
	v_cmp_gt_i32_e32 vcc, v39, v50
	v_cmp_lt_i32_e64 s[8:9], v39, v50
	s_nop 0
	v_cndmask_b32_e64 v32, v32, 0, vcc
	s_and_saveexec_b64 s[10:11], s[8:9]
	v_mul_f32_e32 v37, v33, v45
	v_mul_f32_e32 v37, v37, v32
	ds_write_b32 v52, v37 offset:27660
	s_or_b64 exec, exec, s[10:11]
	v_sub_f32_e32 v37, v42, v38
	v_mul_f32_e32 v37, 0x3fb8aa3b, v37
	v_exp_f32_e32 v37, v37
	s_nop 0
	v_cndmask_b32_e64 v37, v37, 0, s[8:9]
	s_and_saveexec_b64 s[8:9], vcc
	v_mul_f32_e32 v33, v33, v43
	v_add_lshl_u32 v38, v34, v39, 2
	v_mul_f32_e32 v33, v33, v37
	v_sub_u32_e32 v38, 0, v38
	ds_write_b32 v38, v33 offset:60412
	s_or_b64 exec, exec, s[8:9]
	s_add_u32 s3, s4, 0xec27800
	s_addc_u32 s17, s5, 0
	s_ashr_i32 s19, s18, 31
	s_lshl_b64 s[8:9], s[18:19], 13
	s_add_u32 s8, s3, s8
	v_mul_f32_e32 v53, v27, v35
	s_addc_u32 s9, s17, s9
	v_ashrrev_i32_e32 v35, 31, v34
	v_mul_f32_e32 v33, v28, v31
	v_mul_f32_e32 v40, v28, v36
	v_mul_f32_e32 v28, v27, v30
	v_mul_f32_e32 v38, v26, v0
	v_lshl_add_u64 v[30:31], v[34:35], 1, s[8:9]
	v_mul_f32_e32 v32, v29, v32
	v_lshlrev_b32_e32 v0, 1, v46
	v_mul_f32_e32 v35, v29, v37
	v_lshl_add_u64 v[36:37], v[30:31], 0, v[0:1]
	v_cvt_pk_bf16_f32 v29, v33, v32
	ds_read_b128 v[30:33], v51 offset:60480
	s_or_b32 s10, s18, 1
	s_ashr_i32 s11, s10, 31
	s_lshl_b64 s[10:11], s[10:11], 13
	v_mul_f32_e32 v41, v26, v41
	s_add_u32 s10, s3, s10
	v_sub_u32_e32 v26, 0xfc0, v34
	s_addc_u32 s11, s17, s11
	v_ashrrev_i32_e32 v27, 31, v26
	v_lshlrev_b32_e32 v0, 2, v46
	s_waitcnt lgkmcnt(0)
	v_sub_f32_e32 v30, v44, v30
	v_lshl_add_u64 v[26:27], v[26:27], 1, s[10:11]
	v_cvt_pk_bf16_f32 v28, v38, v28
	v_sub_u32_e32 v0, 0, v0
	v_mul_f32_e32 v30, 0x3fb8aa3b, v30
	global_store_dwordx2 v[36:37], v[28:29], off
	v_lshl_add_u64 v[38:39], v[48:49], 1, v[26:27]
	ds_read_b128 v[26:29], v0 offset:60848
	v_exp_f32_e32 v30, v30
	v_cvt_pk_bf16_f32 v40, v35, v40
	v_or_b32_e32 v35, 16, v46
	v_cmp_gt_i32_e32 vcc, v35, v50
	v_cvt_pk_bf16_f32 v41, v53, v41
	v_cmp_lt_i32_e64 s[8:9], v35, v50
	v_cndmask_b32_e64 v30, v30, 0, vcc
	global_store_dwordx2 v[38:39], v[40:41], off offset:120
	s_and_saveexec_b64 s[10:11], s[8:9]
	v_mul_f32_e32 v40, v22, v45
	v_mul_f32_e32 v40, v40, v30
	ds_write_b32 v52, v40 offset:27712
	s_or_b64 exec, exec, s[10:11]
	s_waitcnt lgkmcnt(0)
	v_sub_f32_e32 v29, v42, v29
	v_mul_f32_e32 v29, 0x3fb8aa3b, v29
	v_exp_f32_e32 v29, v29
	s_nop 0
	v_cndmask_b32_e64 v29, v29, 0, s[8:9]
	s_and_saveexec_b64 s[8:9], vcc
	v_mul_f32_e32 v22, v22, v43
	v_add_lshl_u32 v35, v34, v35, 2
	v_mul_f32_e32 v22, v22, v29
	v_sub_u32_e32 v35, 0, v35
	ds_write_b32 v35, v22 offset:60412
	s_or_b64 exec, exec, s[8:9]
	v_sub_f32_e32 v22, v44, v31
	v_mul_f32_e32 v22, 0x3fb8aa3b, v22
	v_exp_f32_e32 v22, v22
	v_or_b32_e32 v31, 17, v46
	v_cmp_gt_i32_e32 vcc, v31, v50
	v_cmp_lt_i32_e64 s[8:9], v31, v50
	s_nop 0
	v_cndmask_b32_e64 v22, v22, 0, vcc
	s_and_saveexec_b64 s[10:11], s[8:9]
	v_mul_f32_e32 v35, v23, v45
	v_mul_f32_e32 v35, v35, v22
	ds_write_b32 v52, v35 offset:27716
	s_or_b64 exec, exec, s[10:11]
	v_sub_f32_e32 v28, v42, v28
	v_mul_f32_e32 v28, 0x3fb8aa3b, v28
	v_exp_f32_e32 v28, v28
	s_nop 0
	v_cndmask_b32_e64 v28, v28, 0, s[8:9]
	s_and_saveexec_b64 s[8:9], vcc
	v_mul_f32_e32 v23, v23, v43
	v_add_lshl_u32 v31, v34, v31, 2
	v_mul_f32_e32 v23, v23, v28
	v_sub_u32_e32 v31, 0, v31
	ds_write_b32 v31, v23 offset:60412
	s_or_b64 exec, exec, s[8:9]
	v_sub_f32_e32 v23, v44, v32
	v_mul_f32_e32 v23, 0x3fb8aa3b, v23
	v_exp_f32_e32 v23, v23
	v_or_b32_e32 v31, 18, v46
	v_cmp_gt_i32_e32 vcc, v31, v50
	v_cmp_lt_i32_e64 s[8:9], v31, v50
	s_nop 0
	v_cndmask_b32_e64 v23, v23, 0, vcc
	s_and_saveexec_b64 s[10:11], s[8:9]
	v_mul_f32_e32 v32, v24, v45
	v_mul_f32_e32 v32, v32, v23
	ds_write_b32 v52, v32 offset:27720
	s_or_b64 exec, exec, s[10:11]
	v_sub_f32_e32 v27, v42, v27
	v_mul_f32_e32 v27, 0x3fb8aa3b, v27
	v_exp_f32_e32 v27, v27
	s_nop 0
	v_cndmask_b32_e64 v27, v27, 0, s[8:9]
	s_and_saveexec_b64 s[8:9], vcc
	v_mul_f32_e32 v24, v24, v43
	v_add_lshl_u32 v31, v34, v31, 2
	v_mul_f32_e32 v24, v24, v27
	v_sub_u32_e32 v31, 0, v31
	ds_write_b32 v31, v24 offset:60412
	s_or_b64 exec, exec, s[8:9]
	v_sub_f32_e32 v24, v44, v33
	v_mul_f32_e32 v24, 0x3fb8aa3b, v24
	v_exp_f32_e32 v24, v24
	v_or_b32_e32 v31, 19, v46
	v_cmp_gt_i32_e32 vcc, v31, v50
	v_cmp_lt_i32_e64 s[8:9], v31, v50
	s_nop 0
	v_cndmask_b32_e64 v24, v24, 0, vcc
	s_and_saveexec_b64 s[10:11], s[8:9]
	v_mul_f32_e32 v32, v25, v45
	v_mul_f32_e32 v32, v32, v24
	ds_write_b32 v52, v32 offset:27724
	s_or_b64 exec, exec, s[10:11]
	v_sub_f32_e32 v26, v42, v26
	v_mul_f32_e32 v26, 0x3fb8aa3b, v26
	v_exp_f32_e32 v26, v26
	s_nop 0
	v_cndmask_b32_e64 v26, v26, 0, s[8:9]
	s_and_saveexec_b64 s[8:9], vcc
	v_mul_f32_e32 v25, v25, v43
	v_add_lshl_u32 v31, v34, v31, 2
	v_mul_f32_e32 v25, v25, v26
	v_sub_u32_e32 v31, 0, v31
	ds_write_b32 v31, v25 offset:60412
	s_or_b64 exec, exec, s[8:9]
	v_mul_f32_e32 v23, v20, v23
	v_mul_f32_e32 v20, v20, v27
	v_mul_f32_e32 v22, v19, v22
	v_mul_f32_e32 v27, v19, v28
	v_mul_f32_e32 v25, v18, v30
	v_mul_f32_e32 v28, v18, v29
	v_mul_f32_e32 v18, v21, v24
	v_cvt_pk_bf16_f32 v19, v23, v18
	v_cvt_pk_bf16_f32 v18, v25, v22
	ds_read_b128 v[22:25], v51 offset:60544
	v_mul_f32_e32 v21, v21, v26
	global_store_dwordx2 v[36:37], v[18:19], off offset:32
	v_cvt_pk_bf16_f32 v26, v21, v20
	ds_read_b128 v[18:21], v0 offset:60784
	s_waitcnt lgkmcnt(1)
	v_sub_f32_e32 v22, v44, v22
	v_mul_f32_e32 v22, 0x3fb8aa3b, v22
	v_exp_f32_e32 v22, v22
	v_cvt_pk_bf16_f32 v27, v27, v28
	global_store_dwordx2 v[38:39], v[26:27], off offset:88
	v_or_b32_e32 v26, 32, v46
	v_cmp_gt_i32_e32 vcc, v26, v50
	v_cmp_lt_i32_e64 s[8:9], v26, v50
	s_nop 0
	v_cndmask_b32_e64 v22, v22, 0, vcc
	s_and_saveexec_b64 s[10:11], s[8:9]
	v_mul_f32_e32 v27, v14, v45
	v_mul_f32_e32 v27, v27, v22
	ds_write_b32 v52, v27 offset:27776
	s_or_b64 exec, exec, s[10:11]
	s_waitcnt lgkmcnt(0)
	v_sub_f32_e32 v21, v42, v21
	v_mul_f32_e32 v21, 0x3fb8aa3b, v21
	v_exp_f32_e32 v21, v21
	s_nop 0
	v_cndmask_b32_e64 v21, v21, 0, s[8:9]
	s_and_saveexec_b64 s[8:9], vcc
	v_mul_f32_e32 v14, v14, v43
	v_add_lshl_u32 v26, v34, v26, 2
	v_mul_f32_e32 v14, v14, v21
	v_sub_u32_e32 v26, 0, v26
	ds_write_b32 v26, v14 offset:60412
	s_or_b64 exec, exec, s[8:9]
	v_sub_f32_e32 v14, v44, v23
	v_mul_f32_e32 v14, 0x3fb8aa3b, v14
	v_exp_f32_e32 v14, v14
	v_or_b32_e32 v23, 33, v46
	v_cmp_gt_i32_e32 vcc, v23, v50
	v_cmp_lt_i32_e64 s[8:9], v23, v50
	s_nop 0
	v_cndmask_b32_e64 v14, v14, 0, vcc
	s_and_saveexec_b64 s[10:11], s[8:9]
	v_mul_f32_e32 v26, v15, v45
	v_mul_f32_e32 v26, v26, v14
	ds_write_b32 v52, v26 offset:27780
	s_or_b64 exec, exec, s[10:11]
	v_sub_f32_e32 v20, v42, v20
	v_mul_f32_e32 v20, 0x3fb8aa3b, v20
	v_exp_f32_e32 v20, v20
	s_nop 0
	v_cndmask_b32_e64 v20, v20, 0, s[8:9]
	s_and_saveexec_b64 s[8:9], vcc
	v_mul_f32_e32 v15, v15, v43
	v_add_lshl_u32 v23, v34, v23, 2
	v_mul_f32_e32 v15, v15, v20
	v_sub_u32_e32 v23, 0, v23
	ds_write_b32 v23, v15 offset:60412
	s_or_b64 exec, exec, s[8:9]
	v_sub_f32_e32 v15, v44, v24
	v_mul_f32_e32 v15, 0x3fb8aa3b, v15
	v_exp_f32_e32 v15, v15
	v_or_b32_e32 v23, 34, v46
	v_cmp_gt_i32_e32 vcc, v23, v50
	v_cmp_lt_i32_e64 s[8:9], v23, v50
	s_nop 0
	v_cndmask_b32_e64 v15, v15, 0, vcc
	s_and_saveexec_b64 s[10:11], s[8:9]
	v_mul_f32_e32 v24, v16, v45
	v_mul_f32_e32 v24, v24, v15
	ds_write_b32 v52, v24 offset:27784
	s_or_b64 exec, exec, s[10:11]
	v_sub_f32_e32 v19, v42, v19
	v_mul_f32_e32 v19, 0x3fb8aa3b, v19
	v_exp_f32_e32 v19, v19
	s_nop 0
	v_cndmask_b32_e64 v19, v19, 0, s[8:9]
	s_and_saveexec_b64 s[8:9], vcc
	v_mul_f32_e32 v16, v16, v43
	v_add_lshl_u32 v23, v34, v23, 2
	v_mul_f32_e32 v16, v16, v19
	v_sub_u32_e32 v23, 0, v23
	ds_write_b32 v23, v16 offset:60412
	s_or_b64 exec, exec, s[8:9]
	v_sub_f32_e32 v16, v44, v25
	v_mul_f32_e32 v16, 0x3fb8aa3b, v16
	v_exp_f32_e32 v16, v16
	v_or_b32_e32 v23, 35, v46
	v_cmp_gt_i32_e32 vcc, v23, v50
	v_cmp_lt_i32_e64 s[8:9], v23, v50
	s_nop 0
	v_cndmask_b32_e64 v16, v16, 0, vcc
	s_and_saveexec_b64 s[10:11], s[8:9]
	v_mul_f32_e32 v24, v17, v45
	v_mul_f32_e32 v24, v24, v16
	ds_write_b32 v52, v24 offset:27788
	s_or_b64 exec, exec, s[10:11]
	v_sub_f32_e32 v18, v42, v18
	v_mul_f32_e32 v18, 0x3fb8aa3b, v18
	v_exp_f32_e32 v18, v18
	s_nop 0
	v_cndmask_b32_e64 v18, v18, 0, s[8:9]
	s_and_saveexec_b64 s[8:9], vcc
	v_mul_f32_e32 v17, v17, v43
	v_add_lshl_u32 v23, v34, v23, 2
	v_mul_f32_e32 v17, v17, v18
	v_sub_u32_e32 v23, 0, v23
	ds_write_b32 v23, v17 offset:60412
	s_or_b64 exec, exec, s[8:9]
	v_mul_f32_e32 v15, v12, v15
	v_mul_f32_e32 v12, v12, v19
	v_mul_f32_e32 v14, v11, v14
	v_mul_f32_e32 v19, v11, v20
	v_mul_f32_e32 v17, v10, v22
	v_mul_f32_e32 v20, v10, v21
	v_mul_f32_e32 v10, v13, v16
	v_cvt_pk_bf16_f32 v11, v15, v10
	v_cvt_pk_bf16_f32 v10, v17, v14
	ds_read_b128 v[14:17], v51 offset:60608
	v_mul_f32_e32 v13, v13, v18
	global_store_dwordx2 v[36:37], v[10:11], off offset:64
	v_cvt_pk_bf16_f32 v18, v13, v12
	ds_read_b128 v[10:13], v0 offset:60720
	s_waitcnt lgkmcnt(1)
	v_sub_f32_e32 v0, v44, v14
	v_mul_f32_e32 v0, 0x3fb8aa3b, v0
	v_exp_f32_e32 v0, v0
	v_or_b32_e32 v14, 48, v46
	v_cmp_gt_i32_e32 vcc, v14, v50
	v_cvt_pk_bf16_f32 v19, v19, v20
	v_cmp_lt_i32_e64 s[8:9], v14, v50
	v_cndmask_b32_e64 v0, v0, 0, vcc
	global_store_dwordx2 v[38:39], v[18:19], off offset:56
	s_and_saveexec_b64 s[10:11], s[8:9]
	v_mul_f32_e32 v18, v6, v45
	v_mul_f32_e32 v18, v18, v0
	ds_write_b32 v52, v18 offset:27840
	s_or_b64 exec, exec, s[10:11]
	s_waitcnt lgkmcnt(0)
	v_sub_f32_e32 v13, v42, v13
	v_mul_f32_e32 v13, 0x3fb8aa3b, v13
	v_exp_f32_e32 v13, v13
	s_nop 0
	v_cndmask_b32_e64 v13, v13, 0, s[8:9]
	s_and_saveexec_b64 s[8:9], vcc
	v_mul_f32_e32 v6, v6, v43
	v_add_lshl_u32 v14, v34, v14, 2
	v_mul_f32_e32 v6, v6, v13
	v_sub_u32_e32 v14, 0, v14
	ds_write_b32 v14, v6 offset:60412
	s_or_b64 exec, exec, s[8:9]
	v_sub_f32_e32 v6, v44, v15
	v_mul_f32_e32 v6, 0x3fb8aa3b, v6
	v_exp_f32_e32 v6, v6
	v_or_b32_e32 v14, 49, v46
	v_cmp_gt_i32_e32 vcc, v14, v50
	v_cmp_lt_i32_e64 s[8:9], v14, v50
	s_nop 0
	v_cndmask_b32_e64 v6, v6, 0, vcc
	s_and_saveexec_b64 s[10:11], s[8:9]
	v_mul_f32_e32 v15, v7, v45
	v_mul_f32_e32 v15, v15, v6
	ds_write_b32 v52, v15 offset:27844
	s_or_b64 exec, exec, s[10:11]
	v_sub_f32_e32 v12, v42, v12
	v_mul_f32_e32 v12, 0x3fb8aa3b, v12
	v_exp_f32_e32 v12, v12
	s_nop 0
	v_cndmask_b32_e64 v12, v12, 0, s[8:9]
	s_and_saveexec_b64 s[8:9], vcc
	v_mul_f32_e32 v7, v7, v43
	v_add_lshl_u32 v14, v34, v14, 2
	v_mul_f32_e32 v7, v7, v12
	v_sub_u32_e32 v14, 0, v14
	ds_write_b32 v14, v7 offset:60412
	s_or_b64 exec, exec, s[8:9]
	v_sub_f32_e32 v7, v44, v16
	v_mul_f32_e32 v7, 0x3fb8aa3b, v7
	v_exp_f32_e32 v7, v7
	v_or_b32_e32 v14, 50, v46
	v_cmp_gt_i32_e32 vcc, v14, v50
	v_cmp_lt_i32_e64 s[8:9], v14, v50
	s_nop 0
	v_cndmask_b32_e64 v7, v7, 0, vcc
	s_and_saveexec_b64 s[10:11], s[8:9]
	v_mul_f32_e32 v15, v8, v45
	v_mul_f32_e32 v15, v15, v7
	ds_write_b32 v52, v15 offset:27848
	s_or_b64 exec, exec, s[10:11]
	v_sub_f32_e32 v11, v42, v11
	v_mul_f32_e32 v11, 0x3fb8aa3b, v11
	v_exp_f32_e32 v11, v11
	s_nop 0
	v_cndmask_b32_e64 v11, v11, 0, s[8:9]
	s_and_saveexec_b64 s[8:9], vcc
	v_mul_f32_e32 v8, v8, v43
	v_add_lshl_u32 v14, v34, v14, 2
	v_mul_f32_e32 v8, v8, v11
	v_sub_u32_e32 v14, 0, v14
	ds_write_b32 v14, v8 offset:60412
	s_or_b64 exec, exec, s[8:9]
	v_sub_f32_e32 v8, v44, v17
	v_mul_f32_e32 v8, 0x3fb8aa3b, v8
	v_exp_f32_e32 v8, v8
	v_or_b32_e32 v14, 51, v46
	v_cmp_gt_i32_e32 vcc, v14, v50
	v_cmp_lt_i32_e64 s[8:9], v14, v50
	s_nop 0
	v_cndmask_b32_e64 v8, v8, 0, vcc
	s_and_saveexec_b64 s[10:11], s[8:9]
	v_mul_f32_e32 v15, v9, v45
	v_mul_f32_e32 v15, v15, v8
	ds_write_b32 v52, v15 offset:27852
	s_or_b64 exec, exec, s[10:11]
	v_sub_f32_e32 v10, v42, v10
	v_mul_f32_e32 v10, 0x3fb8aa3b, v10
	v_exp_f32_e32 v10, v10
	s_nop 0
	v_cndmask_b32_e64 v10, v10, 0, s[8:9]
	s_and_saveexec_b64 s[8:9], vcc
	v_mul_f32_e32 v9, v9, v43
	v_add_lshl_u32 v14, v34, v14, 2
	v_mul_f32_e32 v9, v9, v10
	v_sub_u32_e32 v14, 0, v14
	ds_write_b32 v14, v9 offset:60412
	s_or_b64 exec, exec, s[8:9]
	v_ashrrev_i32_e32 v9, 7, v47
	v_add_u32_e32 v14, s18, v9
	v_ashrrev_i32_e32 v15, 31, v14
	v_mul_f32_e32 v7, v4, v7
	v_mul_f32_e32 v4, v4, v11
	v_mul_f32_e32 v6, v3, v6
	v_mul_f32_e32 v0, v2, v0
	v_mul_f32_e32 v11, v2, v13
	v_mul_f32_e32 v2, v5, v8
	v_lshlrev_b64 v[14:15], 14, v[14:15]
	v_mul_f32_e32 v9, v3, v12
	v_mul_f32_e32 v5, v5, v10
	v_cvt_pk_bf16_f32 v3, v7, v2
	v_cvt_pk_bf16_f32 v2, v0, v6
	v_and_b32_e32 v100, 0x7f, v47
	v_lshl_add_u64 v[14:15], s[4:5], 0, v[14:15]
	global_store_dwordx2 v[36:37], v[2:3], off offset:96
	v_cvt_pk_bf16_f32 v3, v9, v11
	v_cvt_pk_bf16_f32 v2, v5, v4
	v_lshlrev_b32_e32 v0, 1, v100
	global_store_dwordx2 v[38:39], v[2:3], off offset:24
	s_load_dwordx2 s[4:5], s[0:1], 0x130
	v_and_b32_e32 v215, 0x7f, v133
	v_lshrrev_b32_e32 v216, 7, v133
	v_lshlrev_b32_e32 v217, 1, v215
	v_cmp_lt_u32_e32 vcc, 63, v215
	v_mov_b32_e32 v225, 0x4800
	v_mov_b32_e32 v226, 0x2380
	v_cndmask_b32_e32 v225, v225, v226, vcc
	v_lshl_add_u32 v220, v216, 14, v217
	v_add_u32_e32 v217, v217, v225
	v_lshlrev_b32_e32 v218, 8, v216
	v_lshlrev_b32_e32 v219, 14, v216
	s_lshl_b32 s3, s16, 15
	v_add_u32_e32 v220, s3, v220
	v_readfirstlane_b32 s6, v216
	v_readfirstlane_b32 s7, v215
	s_waitcnt lgkmcnt(0)
	s_add_u32 s4, s4, 0xcc27800
	s_addc_u32 s5, s5, 0
	s_barrier
	ds_read_u16 v134, v217 offset:0
	ds_read_u16 v135, v217 offset:144
	ds_read_u16 v136, v217 offset:288
	ds_read_u16 v137, v217 offset:432
	ds_read_u16 v138, v217 offset:576
	ds_read_u16 v139, v217 offset:720
	ds_read_u16 v140, v217 offset:864
	ds_read_u16 v141, v217 offset:1008
	ds_read_u16 v142, v217 offset:1152
	ds_read_u16 v143, v217 offset:1296
	ds_read_u16 v144, v217 offset:1440
	ds_read_u16 v145, v217 offset:1584
	s_waitcnt lgkmcnt(0)
	ds_read_u16 v146, v217 offset:1728
	ds_read_u16 v147, v217 offset:1872
	ds_read_u16 v148, v217 offset:2016
	ds_read_u16 v149, v217 offset:2160
	ds_read_u16 v150, v217 offset:2304
	ds_read_u16 v151, v217 offset:2448
	ds_read_u16 v152, v217 offset:2592
	ds_read_u16 v153, v217 offset:2736
	ds_read_u16 v154, v217 offset:2880
	ds_read_u16 v155, v217 offset:3024
	ds_read_u16 v156, v217 offset:3168
	ds_read_u16 v157, v217 offset:3312
	s_waitcnt lgkmcnt(0)
	ds_read_u16 v158, v217 offset:3456
	ds_read_u16 v159, v217 offset:3600
	ds_read_u16 v160, v217 offset:3744
	ds_read_u16 v161, v217 offset:3888
	ds_read_u16 v162, v217 offset:4032
	ds_read_u16 v163, v217 offset:4176
	ds_read_u16 v164, v217 offset:4320
	ds_read_u16 v165, v217 offset:4464
	ds_read_u16 v166, v217 offset:4608
	ds_read_u16 v167, v217 offset:4752
	ds_read_u16 v168, v217 offset:4896
	ds_read_u16 v169, v217 offset:5040
	s_waitcnt lgkmcnt(0)
	ds_read_u16 v170, v217 offset:5184
	ds_read_u16 v171, v217 offset:5328
	ds_read_u16 v172, v217 offset:5472
	ds_read_u16 v173, v217 offset:5616
	ds_read_u16 v174, v217 offset:5760
	ds_read_u16 v175, v217 offset:5904
	ds_read_u16 v176, v217 offset:6048
	ds_read_u16 v177, v217 offset:6192
	ds_read_u16 v178, v217 offset:6336
	ds_read_u16 v179, v217 offset:6480
	ds_read_u16 v180, v217 offset:6624
	ds_read_u16 v181, v217 offset:6768
	s_waitcnt lgkmcnt(0)
	ds_read_u16 v195, v217 offset:6912
	ds_read_u16 v196, v217 offset:7056
	ds_read_u16 v197, v217 offset:7200
	ds_read_u16 v198, v217 offset:7344
	ds_read_u16 v199, v217 offset:7488
	ds_read_u16 v200, v217 offset:7632
	ds_read_u16 v201, v217 offset:7776
	ds_read_u16 v202, v217 offset:7920
	ds_read_u16 v203, v217 offset:8064
	ds_read_u16 v204, v217 offset:8208
	ds_read_u16 v205, v217 offset:8352
	ds_read_u16 v206, v217 offset:8496
	s_waitcnt lgkmcnt(0)
	ds_read_u16 v207, v217 offset:8640
	ds_read_u16 v212, v217 offset:8784
	ds_read_u16 v213, v217 offset:8928
	ds_read_u16 v214, v217 offset:9072
	ds_read_b128 v[2:5], v218 offset:60928
	ds_read_b128 v[6:9], v218 offset:60944
	ds_read_b128 v[10:13], v218 offset:60960
	ds_read_b128 v[14:17], v218 offset:60976
	ds_read_b128 v[18:21], v218 offset:60992
	ds_read_b128 v[22:25], v218 offset:61008
	ds_read_b128 v[26:29], v218 offset:61024
	ds_read_b128 v[30:33], v218 offset:61040
	s_waitcnt lgkmcnt(0)
	ds_read_b128 v[34:37], v218 offset:61056
	ds_read_b128 v[38:41], v218 offset:61072
	ds_read_b128 v[42:45], v218 offset:61088
	ds_read_b128 v[46:49], v218 offset:61104
	ds_read_b128 v[50:53], v218 offset:61120
	ds_read_b128 v[54:57], v218 offset:61136
	ds_read_b128 v[58:61], v218 offset:61152
	ds_read_b128 v[62:65], v218 offset:61168
	ds_read_b128 v[66:69], v218 offset:61440
	ds_read_b128 v[70:73], v218 offset:61456
	ds_read_b128 v[74:77], v218 offset:61472
	ds_read_b128 v[78:81], v218 offset:61488
	s_waitcnt lgkmcnt(0)
	ds_read_b128 v[82:85], v218 offset:61504
	ds_read_b128 v[86:89], v218 offset:61520
	ds_read_b128 v[90:93], v218 offset:61536
	ds_read_b128 v[94:97], v218 offset:61552
	ds_read_b128 v[98:101], v218 offset:61568
	ds_read_b128 v[102:105], v218 offset:61584
	ds_read_b128 v[106:109], v218 offset:61600
	ds_read_b128 v[110:113], v218 offset:61616
	ds_read_b128 v[114:117], v218 offset:61632
	ds_read_b128 v[118:121], v218 offset:61648
	ds_read_b128 v[122:125], v218 offset:61664
	ds_read_b128 v[126:129], v218 offset:61680
	s_waitcnt lgkmcnt(0)
	s_waitcnt lgkmcnt(0)
	v_lshlrev_b32_e32 v134, 16, v134
	v_lshlrev_b32_e32 v135, 16, v135
	v_lshlrev_b32_e32 v136, 16, v136
	v_lshlrev_b32_e32 v137, 16, v137
	v_lshlrev_b32_e32 v138, 16, v138
	v_lshlrev_b32_e32 v139, 16, v139
	v_lshlrev_b32_e32 v140, 16, v140
	v_lshlrev_b32_e32 v141, 16, v141
	v_lshlrev_b32_e32 v142, 16, v142
	v_lshlrev_b32_e32 v143, 16, v143
	v_lshlrev_b32_e32 v144, 16, v144
	v_lshlrev_b32_e32 v145, 16, v145
	v_lshlrev_b32_e32 v146, 16, v146
	v_lshlrev_b32_e32 v147, 16, v147
	v_lshlrev_b32_e32 v148, 16, v148
	v_lshlrev_b32_e32 v149, 16, v149
	v_lshlrev_b32_e32 v150, 16, v150
	v_lshlrev_b32_e32 v151, 16, v151
	v_lshlrev_b32_e32 v152, 16, v152
	v_lshlrev_b32_e32 v153, 16, v153
	v_lshlrev_b32_e32 v154, 16, v154
	v_lshlrev_b32_e32 v155, 16, v155
	v_lshlrev_b32_e32 v156, 16, v156
	v_lshlrev_b32_e32 v157, 16, v157
	v_lshlrev_b32_e32 v158, 16, v158
	v_lshlrev_b32_e32 v159, 16, v159
	v_lshlrev_b32_e32 v160, 16, v160
	v_lshlrev_b32_e32 v161, 16, v161
	v_lshlrev_b32_e32 v162, 16, v162
	v_lshlrev_b32_e32 v163, 16, v163
	v_lshlrev_b32_e32 v164, 16, v164
	v_lshlrev_b32_e32 v165, 16, v165
	v_lshlrev_b32_e32 v166, 16, v166
	v_lshlrev_b32_e32 v167, 16, v167
	v_lshlrev_b32_e32 v168, 16, v168
	v_lshlrev_b32_e32 v169, 16, v169
	v_lshlrev_b32_e32 v170, 16, v170
	v_lshlrev_b32_e32 v171, 16, v171
	v_lshlrev_b32_e32 v172, 16, v172
	v_lshlrev_b32_e32 v173, 16, v173
	v_lshlrev_b32_e32 v174, 16, v174
	v_lshlrev_b32_e32 v175, 16, v175
	v_lshlrev_b32_e32 v176, 16, v176
	v_lshlrev_b32_e32 v177, 16, v177
	v_lshlrev_b32_e32 v178, 16, v178
	v_lshlrev_b32_e32 v179, 16, v179
	v_lshlrev_b32_e32 v180, 16, v180
	v_lshlrev_b32_e32 v181, 16, v181
	v_lshlrev_b32_e32 v195, 16, v195
	v_lshlrev_b32_e32 v196, 16, v196
	v_lshlrev_b32_e32 v197, 16, v197
	v_lshlrev_b32_e32 v198, 16, v198
	v_lshlrev_b32_e32 v199, 16, v199
	v_lshlrev_b32_e32 v200, 16, v200
	v_lshlrev_b32_e32 v201, 16, v201
	v_lshlrev_b32_e32 v202, 16, v202
	v_lshlrev_b32_e32 v203, 16, v203
	v_lshlrev_b32_e32 v204, 16, v204
	v_lshlrev_b32_e32 v205, 16, v205
	v_lshlrev_b32_e32 v206, 16, v206
	v_lshlrev_b32_e32 v207, 16, v207
	v_lshlrev_b32_e32 v212, 16, v212
	v_lshlrev_b32_e32 v213, 16, v213
	v_lshlrev_b32_e32 v214, 16, v214
	s_cmp_eq_u32 s6, 0
	s_cbranch_scc1 .Lgs_fwd
	v_swap_b32 v134, v214
	v_swap_b32 v135, v213
	v_swap_b32 v136, v212
	v_swap_b32 v137, v207
	v_swap_b32 v138, v206
	v_swap_b32 v139, v205
	v_swap_b32 v140, v204
	v_swap_b32 v141, v203
	v_swap_b32 v142, v202
	v_swap_b32 v143, v201
	v_swap_b32 v144, v200
	v_swap_b32 v145, v199
	v_swap_b32 v146, v198
	v_swap_b32 v147, v197
	v_swap_b32 v148, v196
	v_swap_b32 v149, v195
	v_swap_b32 v150, v181
	v_swap_b32 v151, v180
	v_swap_b32 v152, v179
	v_swap_b32 v153, v178
	v_swap_b32 v154, v177
	v_swap_b32 v155, v176
	v_swap_b32 v156, v175
	v_swap_b32 v157, v174
	v_swap_b32 v158, v173
	v_swap_b32 v159, v172
	v_swap_b32 v160, v171
	v_swap_b32 v161, v170
	v_swap_b32 v162, v169
	v_swap_b32 v163, v168
	v_swap_b32 v164, v167
	v_swap_b32 v165, v166
.Lgs_fwd:
	s_cmp_lt_u32 s7, 64
	s_cbranch_scc1 .Lgs_v
	v_mul_f32_e32 v2, v2, v134
	v_mul_f32_e32 v3, v3, v135
	v_mul_f32_e32 v4, v4, v136
	v_mul_f32_e32 v5, v5, v137
	v_mul_f32_e32 v6, v6, v138
	v_mul_f32_e32 v7, v7, v139
	v_mul_f32_e32 v8, v8, v140
	v_mul_f32_e32 v9, v9, v141
	v_mul_f32_e32 v10, v10, v142
	v_mul_f32_e32 v11, v11, v143
	v_mul_f32_e32 v12, v12, v144
	v_mul_f32_e32 v13, v13, v145
	v_mul_f32_e32 v14, v14, v146
	v_mul_f32_e32 v15, v15, v147
	v_mul_f32_e32 v16, v16, v148
	v_mul_f32_e32 v17, v17, v149
	v_mul_f32_e32 v18, v18, v150
	v_mul_f32_e32 v19, v19, v151
	v_mul_f32_e32 v20, v20, v152
	v_mul_f32_e32 v21, v21, v153
	v_mul_f32_e32 v22, v22, v154
	v_mul_f32_e32 v23, v23, v155
	v_mul_f32_e32 v24, v24, v156
	v_mul_f32_e32 v25, v25, v157
	v_mul_f32_e32 v26, v26, v158
	v_mul_f32_e32 v27, v27, v159
	v_mul_f32_e32 v28, v28, v160
	v_mul_f32_e32 v29, v29, v161
	v_mul_f32_e32 v30, v30, v162
	v_mul_f32_e32 v31, v31, v163
	v_mul_f32_e32 v32, v32, v164
	v_mul_f32_e32 v33, v33, v165
	v_mul_f32_e32 v34, v34, v166
	v_mul_f32_e32 v35, v35, v167
	v_mul_f32_e32 v36, v36, v168
	v_mul_f32_e32 v37, v37, v169
	v_mul_f32_e32 v38, v38, v170
	v_mul_f32_e32 v39, v39, v171
	v_mul_f32_e32 v40, v40, v172
	v_mul_f32_e32 v41, v41, v173
	v_mul_f32_e32 v42, v42, v174
	v_mul_f32_e32 v43, v43, v175
	v_mul_f32_e32 v44, v44, v176
	v_mul_f32_e32 v45, v45, v177
	v_mul_f32_e32 v46, v46, v178
	v_mul_f32_e32 v47, v47, v179
	v_mul_f32_e32 v48, v48, v180
	v_mul_f32_e32 v49, v49, v181
	v_mul_f32_e32 v50, v50, v195
	v_mul_f32_e32 v51, v51, v196
	v_mul_f32_e32 v52, v52, v197
	v_mul_f32_e32 v53, v53, v198
	v_mul_f32_e32 v54, v54, v199
	v_mul_f32_e32 v55, v55, v200
	v_mul_f32_e32 v56, v56, v201
	v_mul_f32_e32 v57, v57, v202
	v_mul_f32_e32 v58, v58, v203
	v_mul_f32_e32 v59, v59, v204
	v_mul_f32_e32 v60, v60, v205
	v_mul_f32_e32 v61, v61, v206
	v_mul_f32_e32 v62, v62, v207
	v_mul_f32_e32 v63, v63, v212
	v_mul_f32_e32 v64, v64, v213
	v_mul_f32_e32 v65, v65, v214
	s_branch .Lgs_go
.Lgs_v:
	v_mov_b32_e32 v66, v134
	v_mov_b32_e32 v67, v135
	v_mov_b32_e32 v68, v136
	v_mov_b32_e32 v69, v137
	v_mov_b32_e32 v70, v138
	v_mov_b32_e32 v71, v139
	v_mov_b32_e32 v72, v140
	v_mov_b32_e32 v73, v141
	v_mov_b32_e32 v74, v142
	v_mov_b32_e32 v75, v143
	v_mov_b32_e32 v76, v144
	v_mov_b32_e32 v77, v145
	v_mov_b32_e32 v78, v146
	v_mov_b32_e32 v79, v147
	v_mov_b32_e32 v80, v148
	v_mov_b32_e32 v81, v149
	v_mov_b32_e32 v82, v150
	v_mov_b32_e32 v83, v151
	v_mov_b32_e32 v84, v152
	v_mov_b32_e32 v85, v153
	v_mov_b32_e32 v86, v154
	v_mov_b32_e32 v87, v155
	v_mov_b32_e32 v88, v156
	v_mov_b32_e32 v89, v157
	v_mov_b32_e32 v90, v158
	v_mov_b32_e32 v91, v159
	v_mov_b32_e32 v92, v160
	v_mov_b32_e32 v93, v161
	v_mov_b32_e32 v94, v162
	v_mov_b32_e32 v95, v163
	v_mov_b32_e32 v96, v164
	v_mov_b32_e32 v97, v165
	v_mov_b32_e32 v98, v166
	v_mov_b32_e32 v99, v167
	v_mov_b32_e32 v100, v168
	v_mov_b32_e32 v101, v169
	v_mov_b32_e32 v102, v170
	v_mov_b32_e32 v103, v171
	v_mov_b32_e32 v104, v172
	v_mov_b32_e32 v105, v173
	v_mov_b32_e32 v106, v174
	v_mov_b32_e32 v107, v175
	v_mov_b32_e32 v108, v176
	v_mov_b32_e32 v109, v177
	v_mov_b32_e32 v110, v178
	v_mov_b32_e32 v111, v179
	v_mov_b32_e32 v112, v180
	v_mov_b32_e32 v113, v181
	v_mov_b32_e32 v114, v195
	v_mov_b32_e32 v115, v196
	v_mov_b32_e32 v116, v197
	v_mov_b32_e32 v117, v198
	v_mov_b32_e32 v118, v199
	v_mov_b32_e32 v119, v200
	v_mov_b32_e32 v120, v201
	v_mov_b32_e32 v121, v202
	v_mov_b32_e32 v122, v203
	v_mov_b32_e32 v123, v204
	v_mov_b32_e32 v124, v205
	v_mov_b32_e32 v125, v206
	v_mov_b32_e32 v126, v207
	v_mov_b32_e32 v127, v212
	v_mov_b32_e32 v128, v213
	v_mov_b32_e32 v129, v214
.Lgs_go:
	s_nop 0
	ds_read_b128 v[134:137], v219 offset:27904
	ds_read_b128 v[138:141], v219 offset:28160
	ds_read_b128 v[142:145], v219 offset:28416
	ds_read_b128 v[146:149], v219 offset:28672
	ds_read_b128 v[150:153], v219 offset:28928
	ds_read_b128 v[154:157], v219 offset:28944
	ds_read_b128 v[158:161], v219 offset:29184
	ds_read_b128 v[162:165], v219 offset:29200
	ds_read_b128 v[166:169], v219 offset:29440
	ds_read_b128 v[170:173], v219 offset:29456
	ds_read_b128 v[174:177], v219 offset:29696
	ds_read_b128 v[178:181], v219 offset:29712
	v_mul_f32_e32 v2, v66, v2
	v_cvt_pk_bf16_f32 v227, v2, v2
	global_store_short v220, v227, s[4:5]
	s_waitcnt lgkmcnt(11)
	v_mul_f32_e32 v221, v2, v134
	ds_read_b128 v[134:137], v219 offset:29952
	v_fma_f32 v3, v67, v3, -v221
	v_cvt_pk_bf16_f32 v228, v3, v3
	global_store_short v220, v228, s[4:5] offset:256
	s_waitcnt lgkmcnt(11)
	v_mul_f32_e32 v221, v2, v138
	v_mul_f32_e32 v222, v3, v139
	ds_read_b128 v[138:141], v219 offset:29968
	v_add_f32_e32 v225, v222, v221
	v_fma_f32 v4, v68, v4, -v225
	v_cvt_pk_bf16_f32 v229, v4, v4
	global_store_short v220, v229, s[4:5] offset:512
	s_waitcnt lgkmcnt(11)
	v_mul_f32_e32 v221, v2, v142
	v_mul_f32_e32 v222, v3, v143
	v_mul_f32_e32 v223, v4, v144
	ds_read_b128 v[142:145], v219 offset:29984
	v_add_f32_e32 v225, v222, v221
	v_add_f32_e32 v225, v223, v225
	v_fma_f32 v5, v69, v5, -v225
	v_cvt_pk_bf16_f32 v230, v5, v5
	global_store_short v220, v230, s[4:5] offset:768
	s_waitcnt lgkmcnt(11)
	v_mul_f32_e32 v221, v2, v146
	v_mul_f32_e32 v222, v3, v147
	v_mul_f32_e32 v223, v4, v148
	v_mul_f32_e32 v224, v5, v149
	ds_read_b128 v[146:149], v219 offset:30208
	v_add_f32_e32 v225, v222, v221
	v_add_f32_e32 v226, v223, v224
	v_add_f32_e32 v225, v226, v225
	v_fma_f32 v6, v70, v6, -v225
	v_cvt_pk_bf16_f32 v227, v6, v6
	global_store_short v220, v227, s[4:5] offset:1024
	s_waitcnt lgkmcnt(11)
	v_mul_f32_e32 v221, v2, v150
	v_mul_f32_e32 v222, v3, v151
	v_mul_f32_e32 v223, v4, v152
	v_mul_f32_e32 v224, v5, v153
	ds_read_b128 v[150:153], v219 offset:30224
	s_waitcnt lgkmcnt(11)
	v_fmac_f32_e32 v221, v6, v154
	ds_read_b128 v[154:157], v219 offset:30240
	v_add_f32_e32 v225, v222, v221
	v_add_f32_e32 v226, v223, v224
	v_add_f32_e32 v225, v226, v225
	v_fma_f32 v7, v71, v7, -v225
	v_cvt_pk_bf16_f32 v228, v7, v7
	global_store_short v220, v228, s[4:5] offset:1280
	s_waitcnt lgkmcnt(11)
	v_mul_f32_e32 v221, v2, v158
	v_mul_f32_e32 v222, v3, v159
	v_mul_f32_e32 v223, v4, v160
	v_mul_f32_e32 v224, v5, v161
	ds_read_b128 v[158:161], v219 offset:30464
	s_waitcnt lgkmcnt(11)
	v_fmac_f32_e32 v221, v6, v162
	v_fmac_f32_e32 v222, v7, v163
	ds_read_b128 v[162:165], v219 offset:30480
	v_add_f32_e32 v225, v222, v221
	v_add_f32_e32 v226, v223, v224
	v_add_f32_e32 v225, v226, v225
	v_fma_f32 v8, v72, v8, -v225
	v_cvt_pk_bf16_f32 v229, v8, v8
	global_store_short v220, v229, s[4:5] offset:1536
	s_waitcnt lgkmcnt(11)
	v_mul_f32_e32 v221, v2, v166
	v_mul_f32_e32 v222, v3, v167
	v_mul_f32_e32 v223, v4, v168
	v_mul_f32_e32 v224, v5, v169
	ds_read_b128 v[166:169], v219 offset:30496
	s_waitcnt lgkmcnt(11)
	v_fmac_f32_e32 v221, v6, v170
	v_fmac_f32_e32 v222, v7, v171
	v_fmac_f32_e32 v223, v8, v172
	ds_read_b128 v[170:173], v219 offset:30720
	v_add_f32_e32 v225, v222, v221
	v_add_f32_e32 v226, v223, v224
	v_add_f32_e32 v225, v226, v225
	v_fma_f32 v9, v73, v9, -v225
	v_cvt_pk_bf16_f32 v230, v9, v9
	global_store_short v220, v230, s[4:5] offset:1792
	s_waitcnt lgkmcnt(11)
	v_mul_f32_e32 v221, v2, v174
	v_mul_f32_e32 v222, v3, v175
	v_mul_f32_e32 v223, v4, v176
	v_mul_f32_e32 v224, v5, v177
	ds_read_b128 v[174:177], v219 offset:30736
	s_waitcnt lgkmcnt(11)
	v_fmac_f32_e32 v221, v6, v178
	v_fmac_f32_e32 v222, v7, v179
	v_fmac_f32_e32 v223, v8, v180
	v_fmac_f32_e32 v224, v9, v181
	ds_read_b128 v[178:181], v219 offset:30752
	v_add_f32_e32 v225, v222, v221
	v_add_f32_e32 v226, v223, v224
	v_add_f32_e32 v225, v226, v225
	v_fma_f32 v10, v74, v10, -v225
	v_cvt_pk_bf16_f32 v227, v10, v10
	global_store_short v220, v227, s[4:5] offset:2048
	s_waitcnt lgkmcnt(11)
	v_mul_f32_e32 v221, v2, v134
	v_mul_f32_e32 v222, v3, v135
	v_mul_f32_e32 v223, v4, v136
	v_mul_f32_e32 v224, v5, v137
	ds_read_b128 v[134:137], v219 offset:30976
	s_waitcnt lgkmcnt(11)
	v_fmac_f32_e32 v221, v6, v138
	v_fmac_f32_e32 v222, v7, v139
	v_fmac_f32_e32 v223, v8, v140
	v_fmac_f32_e32 v224, v9, v141
	ds_read_b128 v[138:141], v219 offset:30992
	s_waitcnt lgkmcnt(11)
	v_fmac_f32_e32 v221, v10, v142
	ds_read_b128 v[142:145], v219 offset:31008
	v_add_f32_e32 v225, v222, v221
	v_add_f32_e32 v226, v223, v224
	v_add_f32_e32 v225, v226, v225
	v_fma_f32 v11, v75, v11, -v225
	v_cvt_pk_bf16_f32 v228, v11, v11
	global_store_short v220, v228, s[4:5] offset:2304
	s_waitcnt lgkmcnt(11)
	v_mul_f32_e32 v221, v2, v146
	v_mul_f32_e32 v222, v3, v147
	v_mul_f32_e32 v223, v4, v148
	v_mul_f32_e32 v224, v5, v149
	ds_read_b128 v[146:149], v219 offset:31024
	s_waitcnt lgkmcnt(11)
	v_fmac_f32_e32 v221, v6, v150
	v_fmac_f32_e32 v222, v7, v151
	v_fmac_f32_e32 v223, v8, v152
	v_fmac_f32_e32 v224, v9, v153
	ds_read_b128 v[150:153], v219 offset:31232
	s_waitcnt lgkmcnt(11)
	v_fmac_f32_e32 v221, v10, v154
	v_fmac_f32_e32 v222, v11, v155
	ds_read_b128 v[154:157], v219 offset:31248
	v_add_f32_e32 v225, v222, v221
	v_add_f32_e32 v226, v223, v224
	v_add_f32_e32 v225, v226, v225
	v_fma_f32 v12, v76, v12, -v225
	v_cvt_pk_bf16_f32 v229, v12, v12
	global_store_short v220, v229, s[4:5] offset:2560
	s_waitcnt lgkmcnt(11)
	v_mul_f32_e32 v221, v2, v158
	v_mul_f32_e32 v222, v3, v159
	v_mul_f32_e32 v223, v4, v160
	v_mul_f32_e32 v224, v5, v161
	ds_read_b128 v[158:161], v219 offset:31264
	s_waitcnt lgkmcnt(11)
	v_fmac_f32_e32 v221, v6, v162
	v_fmac_f32_e32 v222, v7, v163
	v_fmac_f32_e32 v223, v8, v164
	v_fmac_f32_e32 v224, v9, v165
	ds_read_b128 v[162:165], v219 offset:31280
	s_waitcnt lgkmcnt(11)
	v_fmac_f32_e32 v221, v10, v166
	v_fmac_f32_e32 v222, v11, v167
	v_fmac_f32_e32 v223, v12, v168
	ds_read_b128 v[166:169], v219 offset:31488
	v_add_f32_e32 v225, v222, v221
	v_add_f32_e32 v226, v223, v224
	v_add_f32_e32 v225, v226, v225
	v_fma_f32 v13, v77, v13, -v225
	v_cvt_pk_bf16_f32 v230, v13, v13
	global_store_short v220, v230, s[4:5] offset:2816
	s_waitcnt lgkmcnt(11)
	v_mul_f32_e32 v221, v2, v170
	v_mul_f32_e32 v222, v3, v171
	v_mul_f32_e32 v223, v4, v172
	v_mul_f32_e32 v224, v5, v173
	ds_read_b128 v[170:173], v219 offset:31504
	s_waitcnt lgkmcnt(11)
	v_fmac_f32_e32 v221, v6, v174
	v_fmac_f32_e32 v222, v7, v175
	v_fmac_f32_e32 v223, v8, v176
	v_fmac_f32_e32 v224, v9, v177
	ds_read_b128 v[174:177], v219 offset:31520
	s_waitcnt lgkmcnt(11)
	v_fmac_f32_e32 v221, v10, v178
	v_fmac_f32_e32 v222, v11, v179
	v_fmac_f32_e32 v223, v12, v180
	v_fmac_f32_e32 v224, v13, v181
	ds_read_b128 v[178:181], v219 offset:31536
	v_add_f32_e32 v225, v222, v221
	v_add_f32_e32 v226, v223, v224
	v_add_f32_e32 v225, v226, v225
	v_fma_f32 v14, v78, v14, -v225
	v_cvt_pk_bf16_f32 v227, v14, v14
	global_store_short v220, v227, s[4:5] offset:3072
	s_waitcnt lgkmcnt(11)
	v_mul_f32_e32 v221, v2, v134
	v_mul_f32_e32 v222, v3, v135
	v_mul_f32_e32 v223, v4, v136
	v_mul_f32_e32 v224, v5, v137
	ds_read_b128 v[134:137], v219 offset:31744
	s_waitcnt lgkmcnt(11)
	v_fmac_f32_e32 v221, v6, v138
	v_fmac_f32_e32 v222, v7, v139
	v_fmac_f32_e32 v223, v8, v140
	v_fmac_f32_e32 v224, v9, v141
	ds_read_b128 v[138:141], v219 offset:31760
	s_waitcnt lgkmcnt(11)
	v_fmac_f32_e32 v221, v10, v142
	v_fmac_f32_e32 v222, v11, v143
	v_fmac_f32_e32 v223, v12, v144
	v_fmac_f32_e32 v224, v13, v145
	ds_read_b128 v[142:145], v219 offset:31776
	s_waitcnt lgkmcnt(11)
	v_fmac_f32_e32 v221, v14, v146
	ds_read_b128 v[146:149], v219 offset:31792
	v_add_f32_e32 v225, v222, v221
	v_add_f32_e32 v226, v223, v224
	v_add_f32_e32 v225, v226, v225
	v_fma_f32 v15, v79, v15, -v225
	v_cvt_pk_bf16_f32 v228, v15, v15
	global_store_short v220, v228, s[4:5] offset:3328
	s_waitcnt lgkmcnt(11)
	v_mul_f32_e32 v221, v2, v150
	v_mul_f32_e32 v222, v3, v151
	v_mul_f32_e32 v223, v4, v152
	v_mul_f32_e32 v224, v5, v153
	ds_read_b128 v[150:153], v219 offset:32000
	s_waitcnt lgkmcnt(11)
	v_fmac_f32_e32 v221, v6, v154
	v_fmac_f32_e32 v222, v7, v155
	v_fmac_f32_e32 v223, v8, v156
	v_fmac_f32_e32 v224, v9, v157
	ds_read_b128 v[154:157], v219 offset:32016
	s_waitcnt lgkmcnt(11)
	v_fmac_f32_e32 v221, v10, v158
	v_fmac_f32_e32 v222, v11, v159
	v_fmac_f32_e32 v223, v12, v160
	v_fmac_f32_e32 v224, v13, v161
	ds_read_b128 v[158:161], v219 offset:32032
	s_waitcnt lgkmcnt(11)
	v_fmac_f32_e32 v221, v14, v162
	v_fmac_f32_e32 v222, v15, v163
	ds_read_b128 v[162:165], v219 offset:32048
	v_add_f32_e32 v225, v222, v221
	v_add_f32_e32 v226, v223, v224
	v_add_f32_e32 v225, v226, v225
	v_fma_f32 v16, v80, v16, -v225
	v_cvt_pk_bf16_f32 v229, v16, v16
	global_store_short v220, v229, s[4:5] offset:3584
	s_waitcnt lgkmcnt(11)
	v_mul_f32_e32 v221, v2, v166
	v_mul_f32_e32 v222, v3, v167
	v_mul_f32_e32 v223, v4, v168
	v_mul_f32_e32 v224, v5, v169
	ds_read_b128 v[166:169], v219 offset:32064
	s_waitcnt lgkmcnt(11)
	v_fmac_f32_e32 v221, v6, v170
	v_fmac_f32_e32 v222, v7, v171
	v_fmac_f32_e32 v223, v8, v172
	v_fmac_f32_e32 v224, v9, v173
	ds_read_b128 v[170:173], v219 offset:32256
	s_waitcnt lgkmcnt(11)
	v_fmac_f32_e32 v221, v10, v174
	v_fmac_f32_e32 v222, v11, v175
	v_fmac_f32_e32 v223, v12, v176
	v_fmac_f32_e32 v224, v13, v177
	ds_read_b128 v[174:177], v219 offset:32272
	s_waitcnt lgkmcnt(11)
	v_fmac_f32_e32 v221, v14, v178
	v_fmac_f32_e32 v222, v15, v179
	v_fmac_f32_e32 v223, v16, v180
	ds_read_b128 v[178:181], v219 offset:32288
	v_add_f32_e32 v225, v222, v221
	v_add_f32_e32 v226, v223, v224
	v_add_f32_e32 v225, v226, v225
	v_fma_f32 v17, v81, v17, -v225
	v_cvt_pk_bf16_f32 v230, v17, v17
	global_store_short v220, v230, s[4:5] offset:3840
	s_waitcnt lgkmcnt(11)
	v_mul_f32_e32 v221, v2, v134
	v_mul_f32_e32 v222, v3, v135
	v_mul_f32_e32 v223, v4, v136
	v_mul_f32_e32 v224, v5, v137
	ds_read_b128 v[134:137], v219 offset:32304
	s_waitcnt lgkmcnt(11)
	v_fmac_f32_e32 v221, v6, v138
	v_fmac_f32_e32 v222, v7, v139
	v_fmac_f32_e32 v223, v8, v140
	v_fmac_f32_e32 v224, v9, v141
	ds_read_b128 v[138:141], v219 offset:32320
	s_waitcnt lgkmcnt(11)
	v_fmac_f32_e32 v221, v10, v142
	v_fmac_f32_e32 v222, v11, v143
	v_fmac_f32_e32 v223, v12, v144
	v_fmac_f32_e32 v224, v13, v145
	ds_read_b128 v[142:145], v219 offset:32512
	s_waitcnt lgkmcnt(11)
	v_fmac_f32_e32 v221, v14, v146
	v_fmac_f32_e32 v222, v15, v147
	v_fmac_f32_e32 v223, v16, v148
	v_fmac_f32_e32 v224, v17, v149
	ds_read_b128 v[146:149], v219 offset:32528
	v_add_f32_e32 v225, v222, v221
	v_add_f32_e32 v226, v223, v224
	v_add_f32_e32 v225, v226, v225
	v_fma_f32 v18, v82, v18, -v225
	v_add_u32_e32 v220, 0x1000, v220
	v_cvt_pk_bf16_f32 v227, v18, v18
	global_store_short v220, v227, s[4:5]
	s_waitcnt lgkmcnt(11)
	v_mul_f32_e32 v221, v2, v150
	v_mul_f32_e32 v222, v3, v151
	v_mul_f32_e32 v223, v4, v152
	v_mul_f32_e32 v224, v5, v153
	ds_read_b128 v[150:153], v219 offset:32544
	s_waitcnt lgkmcnt(11)
	v_fmac_f32_e32 v221, v6, v154
	v_fmac_f32_e32 v222, v7, v155
	v_fmac_f32_e32 v223, v8, v156
	v_fmac_f32_e32 v224, v9, v157
	ds_read_b128 v[154:157], v219 offset:32560
	s_waitcnt lgkmcnt(11)
	v_fmac_f32_e32 v221, v10, v158
	v_fmac_f32_e32 v222, v11, v159
	v_fmac_f32_e32 v223, v12, v160
	v_fmac_f32_e32 v224, v13, v161
	ds_read_b128 v[158:161], v219 offset:32576
	s_waitcnt lgkmcnt(11)
	v_fmac_f32_e32 v221, v14, v162
	v_fmac_f32_e32 v222, v15, v163
	v_fmac_f32_e32 v223, v16, v164
	v_fmac_f32_e32 v224, v17, v165
	ds_read_b128 v[162:165], v219 offset:32768
	s_waitcnt lgkmcnt(11)
	v_fmac_f32_e32 v221, v18, v166
	ds_read_b128 v[166:169], v219 offset:32784
	v_add_f32_e32 v225, v222, v221
	v_add_f32_e32 v226, v223, v224
	v_add_f32_e32 v225, v226, v225
	v_fma_f32 v19, v83, v19, -v225
	v_cvt_pk_bf16_f32 v228, v19, v19
	global_store_short v220, v228, s[4:5] offset:256
	s_waitcnt lgkmcnt(11)
	v_mul_f32_e32 v221, v2, v170
	v_mul_f32_e32 v222, v3, v171
	v_mul_f32_e32 v223, v4, v172
	v_mul_f32_e32 v224, v5, v173
	ds_read_b128 v[170:173], v219 offset:32800
	s_waitcnt lgkmcnt(11)
	v_fmac_f32_e32 v221, v6, v174
	v_fmac_f32_e32 v222, v7, v175
	v_fmac_f32_e32 v223, v8, v176
	v_fmac_f32_e32 v224, v9, v177
	ds_read_b128 v[174:177], v219 offset:32816
	s_waitcnt lgkmcnt(11)
	v_fmac_f32_e32 v221, v10, v178
	v_fmac_f32_e32 v222, v11, v179
	v_fmac_f32_e32 v223, v12, v180
	v_fmac_f32_e32 v224, v13, v181
	ds_read_b128 v[178:181], v219 offset:32832
	s_waitcnt lgkmcnt(11)
	v_fmac_f32_e32 v221, v14, v134
	v_fmac_f32_e32 v222, v15, v135
	v_fmac_f32_e32 v223, v16, v136
	v_fmac_f32_e32 v224, v17, v137
	ds_read_b128 v[134:137], v219 offset:33024
	s_waitcnt lgkmcnt(11)
	v_fmac_f32_e32 v221, v18, v138
	v_fmac_f32_e32 v222, v19, v139
	ds_read_b128 v[138:141], v219 offset:33040
	v_add_f32_e32 v225, v222, v221
	v_add_f32_e32 v226, v223, v224
	v_add_f32_e32 v225, v226, v225
	v_fma_f32 v20, v84, v20, -v225
	v_cvt_pk_bf16_f32 v229, v20, v20
	global_store_short v220, v229, s[4:5] offset:512
	s_waitcnt lgkmcnt(11)
	v_mul_f32_e32 v221, v2, v142
	v_mul_f32_e32 v222, v3, v143
	v_mul_f32_e32 v223, v4, v144
	v_mul_f32_e32 v224, v5, v145
	ds_read_b128 v[142:145], v219 offset:33056
	s_waitcnt lgkmcnt(11)
	v_fmac_f32_e32 v221, v6, v146
	v_fmac_f32_e32 v222, v7, v147
	v_fmac_f32_e32 v223, v8, v148
	v_fmac_f32_e32 v224, v9, v149
	ds_read_b128 v[146:149], v219 offset:33072
	s_waitcnt lgkmcnt(11)
	v_fmac_f32_e32 v221, v10, v150
	v_fmac_f32_e32 v222, v11, v151
	v_fmac_f32_e32 v223, v12, v152
	v_fmac_f32_e32 v224, v13, v153
	ds_read_b128 v[150:153], v219 offset:33088
	s_waitcnt lgkmcnt(11)
	v_fmac_f32_e32 v221, v14, v154
	v_fmac_f32_e32 v222, v15, v155
	v_fmac_f32_e32 v223, v16, v156
	v_fmac_f32_e32 v224, v17, v157
	ds_read_b128 v[154:157], v219 offset:33104
	s_waitcnt lgkmcnt(11)
	v_fmac_f32_e32 v221, v18, v158
	v_fmac_f32_e32 v222, v19, v159
	v_fmac_f32_e32 v223, v20, v160
	ds_read_b128 v[158:161], v219 offset:33280
	v_add_f32_e32 v225, v222, v221
	v_add_f32_e32 v226, v223, v224
	v_add_f32_e32 v225, v226, v225
	v_fma_f32 v21, v85, v21, -v225
	v_cvt_pk_bf16_f32 v230, v21, v21
	global_store_short v220, v230, s[4:5] offset:768
	s_waitcnt lgkmcnt(11)
	v_mul_f32_e32 v221, v2, v162
	v_mul_f32_e32 v222, v3, v163
	v_mul_f32_e32 v223, v4, v164
	v_mul_f32_e32 v224, v5, v165
	ds_read_b128 v[162:165], v219 offset:33296
	s_waitcnt lgkmcnt(11)
	v_fmac_f32_e32 v221, v6, v166
	v_fmac_f32_e32 v222, v7, v167
	v_fmac_f32_e32 v223, v8, v168
	v_fmac_f32_e32 v224, v9, v169
	ds_read_b128 v[166:169], v219 offset:33312
	s_waitcnt lgkmcnt(11)
	v_fmac_f32_e32 v221, v10, v170
	v_fmac_f32_e32 v222, v11, v171
	v_fmac_f32_e32 v223, v12, v172
	v_fmac_f32_e32 v224, v13, v173
	ds_read_b128 v[170:173], v219 offset:33328
	s_waitcnt lgkmcnt(11)
	v_fmac_f32_e32 v221, v14, v174
	v_fmac_f32_e32 v222, v15, v175
	v_fmac_f32_e32 v223, v16, v176
	v_fmac_f32_e32 v224, v17, v177
	ds_read_b128 v[174:177], v219 offset:33344
	s_waitcnt lgkmcnt(11)
	v_fmac_f32_e32 v221, v18, v178
	v_fmac_f32_e32 v222, v19, v179
	v_fmac_f32_e32 v223, v20, v180
	v_fmac_f32_e32 v224, v21, v181
	ds_read_b128 v[178:181], v219 offset:33360
	v_add_f32_e32 v225, v222, v221
	v_add_f32_e32 v226, v223, v224
	v_add_f32_e32 v225, v226, v225
	v_fma_f32 v22, v86, v22, -v225
	v_cvt_pk_bf16_f32 v227, v22, v22
	global_store_short v220, v227, s[4:5] offset:1024
	s_waitcnt lgkmcnt(11)
	v_mul_f32_e32 v221, v2, v134
	v_mul_f32_e32 v222, v3, v135
	v_mul_f32_e32 v223, v4, v136
	v_mul_f32_e32 v224, v5, v137
	ds_read_b128 v[134:137], v219 offset:33536
	s_waitcnt lgkmcnt(11)
	v_fmac_f32_e32 v221, v6, v138
	v_fmac_f32_e32 v222, v7, v139
	v_fmac_f32_e32 v223, v8, v140
	v_fmac_f32_e32 v224, v9, v141
	ds_read_b128 v[138:141], v219 offset:33552
	s_waitcnt lgkmcnt(11)
	v_fmac_f32_e32 v221, v10, v142
	v_fmac_f32_e32 v222, v11, v143
	v_fmac_f32_e32 v223, v12, v144
	v_fmac_f32_e32 v224, v13, v145
	ds_read_b128 v[142:145], v219 offset:33568
	s_waitcnt lgkmcnt(11)
	v_fmac_f32_e32 v221, v14, v146
	v_fmac_f32_e32 v222, v15, v147
	v_fmac_f32_e32 v223, v16, v148
	v_fmac_f32_e32 v224, v17, v149
	ds_read_b128 v[146:149], v219 offset:33584
	s_waitcnt lgkmcnt(11)
	v_fmac_f32_e32 v221, v18, v150
	v_fmac_f32_e32 v222, v19, v151
	v_fmac_f32_e32 v223, v20, v152
	v_fmac_f32_e32 v224, v21, v153
	ds_read_b128 v[150:153], v219 offset:33600
	s_waitcnt lgkmcnt(11)
	v_fmac_f32_e32 v221, v22, v154
	ds_read_b128 v[154:157], v219 offset:33616
	v_add_f32_e32 v225, v222, v221
	v_add_f32_e32 v226, v223, v224
	v_add_f32_e32 v225, v226, v225
	v_fma_f32 v23, v87, v23, -v225
	v_cvt_pk_bf16_f32 v228, v23, v23
	global_store_short v220, v228, s[4:5] offset:1280
	s_waitcnt lgkmcnt(11)
	v_mul_f32_e32 v221, v2, v158
	v_mul_f32_e32 v222, v3, v159
	v_mul_f32_e32 v223, v4, v160
	v_mul_f32_e32 v224, v5, v161
	ds_read_b128 v[158:161], v219 offset:33792
	s_waitcnt lgkmcnt(11)
	v_fmac_f32_e32 v221, v6, v162
	v_fmac_f32_e32 v222, v7, v163
	v_fmac_f32_e32 v223, v8, v164
	v_fmac_f32_e32 v224, v9, v165
	ds_read_b128 v[162:165], v219 offset:33808
	s_waitcnt lgkmcnt(11)
	v_fmac_f32_e32 v221, v10, v166
	v_fmac_f32_e32 v222, v11, v167
	v_fmac_f32_e32 v223, v12, v168
	v_fmac_f32_e32 v224, v13, v169
	ds_read_b128 v[166:169], v219 offset:33824
	s_waitcnt lgkmcnt(11)
	v_fmac_f32_e32 v221, v14, v170
	v_fmac_f32_e32 v222, v15, v171
	v_fmac_f32_e32 v223, v16, v172
	v_fmac_f32_e32 v224, v17, v173
	ds_read_b128 v[170:173], v219 offset:33840
	s_waitcnt lgkmcnt(11)
	v_fmac_f32_e32 v221, v18, v174
	v_fmac_f32_e32 v222, v19, v175
	v_fmac_f32_e32 v223, v20, v176
	v_fmac_f32_e32 v224, v21, v177
	ds_read_b128 v[174:177], v219 offset:33856
	s_waitcnt lgkmcnt(11)
	v_fmac_f32_e32 v221, v22, v178
	v_fmac_f32_e32 v222, v23, v179
	ds_read_b128 v[178:181], v219 offset:33872
	v_add_f32_e32 v225, v222, v221
	v_add_f32_e32 v226, v223, v224
	v_add_f32_e32 v225, v226, v225
	v_fma_f32 v24, v88, v24, -v225
	v_cvt_pk_bf16_f32 v229, v24, v24
	global_store_short v220, v229, s[4:5] offset:1536
	s_waitcnt lgkmcnt(11)
	v_mul_f32_e32 v221, v2, v134
	v_mul_f32_e32 v222, v3, v135
	v_mul_f32_e32 v223, v4, v136
	v_mul_f32_e32 v224, v5, v137
	ds_read_b128 v[134:137], v219 offset:34048
	s_waitcnt lgkmcnt(11)
	v_fmac_f32_e32 v221, v6, v138
	v_fmac_f32_e32 v222, v7, v139
	v_fmac_f32_e32 v223, v8, v140
	v_fmac_f32_e32 v224, v9, v141
	ds_read_b128 v[138:141], v219 offset:34064
	s_waitcnt lgkmcnt(11)
	v_fmac_f32_e32 v221, v10, v142
	v_fmac_f32_e32 v222, v11, v143
	v_fmac_f32_e32 v223, v12, v144
	v_fmac_f32_e32 v224, v13, v145
	ds_read_b128 v[142:145], v219 offset:34080
	s_waitcnt lgkmcnt(11)
	v_fmac_f32_e32 v221, v14, v146
	v_fmac_f32_e32 v222, v15, v147
	v_fmac_f32_e32 v223, v16, v148
	v_fmac_f32_e32 v224, v17, v149
	ds_read_b128 v[146:149], v219 offset:34096
	s_waitcnt lgkmcnt(11)
	v_fmac_f32_e32 v221, v18, v150
	v_fmac_f32_e32 v222, v19, v151
	v_fmac_f32_e32 v223, v20, v152
	v_fmac_f32_e32 v224, v21, v153
	ds_read_b128 v[150:153], v219 offset:34112
	s_waitcnt lgkmcnt(11)
	v_fmac_f32_e32 v221, v22, v154
	v_fmac_f32_e32 v222, v23, v155
	v_fmac_f32_e32 v223, v24, v156
	ds_read_b128 v[154:157], v219 offset:34128
	v_add_f32_e32 v225, v222, v221
	v_add_f32_e32 v226, v223, v224
	v_add_f32_e32 v225, v226, v225
	v_fma_f32 v25, v89, v25, -v225
	v_cvt_pk_bf16_f32 v230, v25, v25
	global_store_short v220, v230, s[4:5] offset:1792
	s_waitcnt lgkmcnt(11)
	v_mul_f32_e32 v221, v2, v158
	v_mul_f32_e32 v222, v3, v159
	v_mul_f32_e32 v223, v4, v160
	v_mul_f32_e32 v224, v5, v161
	ds_read_b128 v[158:161], v219 offset:34144
	s_waitcnt lgkmcnt(11)
	v_fmac_f32_e32 v221, v6, v162
	v_fmac_f32_e32 v222, v7, v163
	v_fmac_f32_e32 v223, v8, v164
	v_fmac_f32_e32 v224, v9, v165
	ds_read_b128 v[162:165], v219 offset:34304
	s_waitcnt lgkmcnt(11)
	v_fmac_f32_e32 v221, v10, v166
	v_fmac_f32_e32 v222, v11, v167
	v_fmac_f32_e32 v223, v12, v168
	v_fmac_f32_e32 v224, v13, v169
	ds_read_b128 v[166:169], v219 offset:34320
	s_waitcnt lgkmcnt(11)
	v_fmac_f32_e32 v221, v14, v170
	v_fmac_f32_e32 v222, v15, v171
	v_fmac_f32_e32 v223, v16, v172
	v_fmac_f32_e32 v224, v17, v173
	ds_read_b128 v[170:173], v219 offset:34336
	s_waitcnt lgkmcnt(11)
	v_fmac_f32_e32 v221, v18, v174
	v_fmac_f32_e32 v222, v19, v175
	v_fmac_f32_e32 v223, v20, v176
	v_fmac_f32_e32 v224, v21, v177
	ds_read_b128 v[174:177], v219 offset:34352
	s_waitcnt lgkmcnt(11)
	v_fmac_f32_e32 v221, v22, v178
	v_fmac_f32_e32 v222, v23, v179
	v_fmac_f32_e32 v223, v24, v180
	v_fmac_f32_e32 v224, v25, v181
	ds_read_b128 v[178:181], v219 offset:34368
	v_add_f32_e32 v225, v222, v221
	v_add_f32_e32 v226, v223, v224
	v_add_f32_e32 v225, v226, v225
	v_fma_f32 v26, v90, v26, -v225
	v_cvt_pk_bf16_f32 v227, v26, v26
	global_store_short v220, v227, s[4:5] offset:2048
	s_waitcnt lgkmcnt(11)
	v_mul_f32_e32 v221, v2, v134
	v_mul_f32_e32 v222, v3, v135
	v_mul_f32_e32 v223, v4, v136
	v_mul_f32_e32 v224, v5, v137
	ds_read_b128 v[134:137], v219 offset:34384
	s_waitcnt lgkmcnt(11)
	v_fmac_f32_e32 v221, v6, v138
	v_fmac_f32_e32 v222, v7, v139
	v_fmac_f32_e32 v223, v8, v140
	v_fmac_f32_e32 v224, v9, v141
	ds_read_b128 v[138:141], v219 offset:34400
	s_waitcnt lgkmcnt(11)
	v_fmac_f32_e32 v221, v10, v142
	v_fmac_f32_e32 v222, v11, v143
	v_fmac_f32_e32 v223, v12, v144
	v_fmac_f32_e32 v224, v13, v145
	ds_read_b128 v[142:145], v219 offset:34560
	s_waitcnt lgkmcnt(11)
	v_fmac_f32_e32 v221, v14, v146
	v_fmac_f32_e32 v222, v15, v147
	v_fmac_f32_e32 v223, v16, v148
	v_fmac_f32_e32 v224, v17, v149
	ds_read_b128 v[146:149], v219 offset:34576
	s_waitcnt lgkmcnt(11)
	v_fmac_f32_e32 v221, v18, v150
	v_fmac_f32_e32 v222, v19, v151
	v_fmac_f32_e32 v223, v20, v152
	v_fmac_f32_e32 v224, v21, v153
	ds_read_b128 v[150:153], v219 offset:34592
	s_waitcnt lgkmcnt(11)
	v_fmac_f32_e32 v221, v22, v154
	v_fmac_f32_e32 v222, v23, v155
	v_fmac_f32_e32 v223, v24, v156
	v_fmac_f32_e32 v224, v25, v157
	ds_read_b128 v[154:157], v219 offset:34608
	s_waitcnt lgkmcnt(11)
	v_fmac_f32_e32 v221, v26, v158
	ds_read_b128 v[158:161], v219 offset:34624
	v_add_f32_e32 v225, v222, v221
	v_add_f32_e32 v226, v223, v224
	v_add_f32_e32 v225, v226, v225
	v_fma_f32 v27, v91, v27, -v225
	v_cvt_pk_bf16_f32 v228, v27, v27
	global_store_short v220, v228, s[4:5] offset:2304
	s_waitcnt lgkmcnt(11)
	v_mul_f32_e32 v221, v2, v162
	v_mul_f32_e32 v222, v3, v163
	v_mul_f32_e32 v223, v4, v164
	v_mul_f32_e32 v224, v5, v165
	ds_read_b128 v[162:165], v219 offset:34640
	s_waitcnt lgkmcnt(11)
	v_fmac_f32_e32 v221, v6, v166
	v_fmac_f32_e32 v222, v7, v167
	v_fmac_f32_e32 v223, v8, v168
	v_fmac_f32_e32 v224, v9, v169
	ds_read_b128 v[166:169], v219 offset:34656
	s_waitcnt lgkmcnt(11)
	v_fmac_f32_e32 v221, v10, v170
	v_fmac_f32_e32 v222, v11, v171
	v_fmac_f32_e32 v223, v12, v172
	v_fmac_f32_e32 v224, v13, v173
	ds_read_b128 v[170:173], v219 offset:34816
	s_waitcnt lgkmcnt(11)
	v_fmac_f32_e32 v221, v14, v174
	v_fmac_f32_e32 v222, v15, v175
	v_fmac_f32_e32 v223, v16, v176
	v_fmac_f32_e32 v224, v17, v177
	ds_read_b128 v[174:177], v219 offset:34832
	s_waitcnt lgkmcnt(11)
	v_fmac_f32_e32 v221, v18, v178
	v_fmac_f32_e32 v222, v19, v179
	v_fmac_f32_e32 v223, v20, v180
	v_fmac_f32_e32 v224, v21, v181
	ds_read_b128 v[178:181], v219 offset:34848
	s_waitcnt lgkmcnt(11)
	v_fmac_f32_e32 v221, v22, v134
	v_fmac_f32_e32 v222, v23, v135
	v_fmac_f32_e32 v223, v24, v136
	v_fmac_f32_e32 v224, v25, v137
	ds_read_b128 v[134:137], v219 offset:34864
	s_waitcnt lgkmcnt(11)
	v_fmac_f32_e32 v221, v26, v138
	v_fmac_f32_e32 v222, v27, v139
	ds_read_b128 v[138:141], v219 offset:34880
	v_add_f32_e32 v225, v222, v221
	v_add_f32_e32 v226, v223, v224
	v_add_f32_e32 v225, v226, v225
	v_fma_f32 v28, v92, v28, -v225
	v_cvt_pk_bf16_f32 v229, v28, v28
	global_store_short v220, v229, s[4:5] offset:2560
	s_waitcnt lgkmcnt(11)
	v_mul_f32_e32 v221, v2, v142
	v_mul_f32_e32 v222, v3, v143
	v_mul_f32_e32 v223, v4, v144
	v_mul_f32_e32 v224, v5, v145
	ds_read_b128 v[142:145], v219 offset:34896
	s_waitcnt lgkmcnt(11)
	v_fmac_f32_e32 v221, v6, v146
	v_fmac_f32_e32 v222, v7, v147
	v_fmac_f32_e32 v223, v8, v148
	v_fmac_f32_e32 v224, v9, v149
	ds_read_b128 v[146:149], v219 offset:34912
	s_waitcnt lgkmcnt(11)
	v_fmac_f32_e32 v221, v10, v150
	v_fmac_f32_e32 v222, v11, v151
	v_fmac_f32_e32 v223, v12, v152
	v_fmac_f32_e32 v224, v13, v153
	ds_read_b128 v[150:153], v219 offset:35072
	s_waitcnt lgkmcnt(11)
	v_fmac_f32_e32 v221, v14, v154
	v_fmac_f32_e32 v222, v15, v155
	v_fmac_f32_e32 v223, v16, v156
	v_fmac_f32_e32 v224, v17, v157
	ds_read_b128 v[154:157], v219 offset:35088
	s_waitcnt lgkmcnt(11)
	v_fmac_f32_e32 v221, v18, v158
	v_fmac_f32_e32 v222, v19, v159
	v_fmac_f32_e32 v223, v20, v160
	v_fmac_f32_e32 v224, v21, v161
	ds_read_b128 v[158:161], v219 offset:35104
	s_waitcnt lgkmcnt(11)
	v_fmac_f32_e32 v221, v22, v162
	v_fmac_f32_e32 v222, v23, v163
	v_fmac_f32_e32 v223, v24, v164
	v_fmac_f32_e32 v224, v25, v165
	ds_read_b128 v[162:165], v219 offset:35120
	s_waitcnt lgkmcnt(11)
	v_fmac_f32_e32 v221, v26, v166
	v_fmac_f32_e32 v222, v27, v167
	v_fmac_f32_e32 v223, v28, v168
	ds_read_b128 v[166:169], v219 offset:35136
	v_add_f32_e32 v225, v222, v221
	v_add_f32_e32 v226, v223, v224
	v_add_f32_e32 v225, v226, v225
	v_fma_f32 v29, v93, v29, -v225
	v_cvt_pk_bf16_f32 v230, v29, v29
	global_store_short v220, v230, s[4:5] offset:2816
	s_waitcnt lgkmcnt(11)
	v_mul_f32_e32 v221, v2, v170
	v_mul_f32_e32 v222, v3, v171
	v_mul_f32_e32 v223, v4, v172
	v_mul_f32_e32 v224, v5, v173
	ds_read_b128 v[170:173], v219 offset:35152
	s_waitcnt lgkmcnt(11)
	v_fmac_f32_e32 v221, v6, v174
	v_fmac_f32_e32 v222, v7, v175
	v_fmac_f32_e32 v223, v8, v176
	v_fmac_f32_e32 v224, v9, v177
	ds_read_b128 v[174:177], v219 offset:35168
	s_waitcnt lgkmcnt(11)
	v_fmac_f32_e32 v221, v10, v178
	v_fmac_f32_e32 v222, v11, v179
	v_fmac_f32_e32 v223, v12, v180
	v_fmac_f32_e32 v224, v13, v181
	ds_read_b128 v[178:181], v219 offset:35184
	s_waitcnt lgkmcnt(11)
	v_fmac_f32_e32 v221, v14, v134
	v_fmac_f32_e32 v222, v15, v135
	v_fmac_f32_e32 v223, v16, v136
	v_fmac_f32_e32 v224, v17, v137
	ds_read_b128 v[134:137], v219 offset:35328
	s_waitcnt lgkmcnt(11)
	v_fmac_f32_e32 v221, v18, v138
	v_fmac_f32_e32 v222, v19, v139
	v_fmac_f32_e32 v223, v20, v140
	v_fmac_f32_e32 v224, v21, v141
	ds_read_b128 v[138:141], v219 offset:35344
	s_waitcnt lgkmcnt(11)
	v_fmac_f32_e32 v221, v22, v142
	v_fmac_f32_e32 v222, v23, v143
	v_fmac_f32_e32 v223, v24, v144
	v_fmac_f32_e32 v224, v25, v145
	ds_read_b128 v[142:145], v219 offset:35360
	s_waitcnt lgkmcnt(11)
	v_fmac_f32_e32 v221, v26, v146
	v_fmac_f32_e32 v222, v27, v147
	v_fmac_f32_e32 v223, v28, v148
	v_fmac_f32_e32 v224, v29, v149
	ds_read_b128 v[146:149], v219 offset:35376
	v_add_f32_e32 v225, v222, v221
	v_add_f32_e32 v226, v223, v224
	v_add_f32_e32 v225, v226, v225
	v_fma_f32 v30, v94, v30, -v225
	v_cvt_pk_bf16_f32 v227, v30, v30
	global_store_short v220, v227, s[4:5] offset:3072
	s_waitcnt lgkmcnt(11)
	v_mul_f32_e32 v221, v2, v150
	v_mul_f32_e32 v222, v3, v151
	v_mul_f32_e32 v223, v4, v152
	v_mul_f32_e32 v224, v5, v153
	ds_read_b128 v[150:153], v219 offset:35392
	s_waitcnt lgkmcnt(11)
	v_fmac_f32_e32 v221, v6, v154
	v_fmac_f32_e32 v222, v7, v155
	v_fmac_f32_e32 v223, v8, v156
	v_fmac_f32_e32 v224, v9, v157
	ds_read_b128 v[154:157], v219 offset:35408
	s_waitcnt lgkmcnt(11)
	v_fmac_f32_e32 v221, v10, v158
	v_fmac_f32_e32 v222, v11, v159
	v_fmac_f32_e32 v223, v12, v160
	v_fmac_f32_e32 v224, v13, v161
	ds_read_b128 v[158:161], v219 offset:35424
	s_waitcnt lgkmcnt(11)
	v_fmac_f32_e32 v221, v14, v162
	v_fmac_f32_e32 v222, v15, v163
	v_fmac_f32_e32 v223, v16, v164
	v_fmac_f32_e32 v224, v17, v165
	ds_read_b128 v[162:165], v219 offset:35440
	s_waitcnt lgkmcnt(11)
	v_fmac_f32_e32 v221, v18, v166
	v_fmac_f32_e32 v222, v19, v167
	v_fmac_f32_e32 v223, v20, v168
	v_fmac_f32_e32 v224, v21, v169
	ds_read_b128 v[166:169], v219 offset:35584
	s_waitcnt lgkmcnt(11)
	v_fmac_f32_e32 v221, v22, v170
	v_fmac_f32_e32 v222, v23, v171
	v_fmac_f32_e32 v223, v24, v172
	v_fmac_f32_e32 v224, v25, v173
	ds_read_b128 v[170:173], v219 offset:35600
	s_waitcnt lgkmcnt(11)
	v_fmac_f32_e32 v221, v26, v174
	v_fmac_f32_e32 v222, v27, v175
	v_fmac_f32_e32 v223, v28, v176
	v_fmac_f32_e32 v224, v29, v177
	ds_read_b128 v[174:177], v219 offset:35616
	s_waitcnt lgkmcnt(11)
	v_fmac_f32_e32 v221, v30, v178
	ds_read_b128 v[178:181], v219 offset:35632
	v_add_f32_e32 v225, v222, v221
	v_add_f32_e32 v226, v223, v224
	v_add_f32_e32 v225, v226, v225
	v_fma_f32 v31, v95, v31, -v225
	v_cvt_pk_bf16_f32 v228, v31, v31
	global_store_short v220, v228, s[4:5] offset:3328
	s_waitcnt lgkmcnt(11)
	v_mul_f32_e32 v221, v2, v134
	v_mul_f32_e32 v222, v3, v135
	v_mul_f32_e32 v223, v4, v136
	v_mul_f32_e32 v224, v5, v137
	ds_read_b128 v[134:137], v219 offset:35648
	s_waitcnt lgkmcnt(11)
	v_fmac_f32_e32 v221, v6, v138
	v_fmac_f32_e32 v222, v7, v139
	v_fmac_f32_e32 v223, v8, v140
	v_fmac_f32_e32 v224, v9, v141
	ds_read_b128 v[138:141], v219 offset:35664
	s_waitcnt lgkmcnt(11)
	v_fmac_f32_e32 v221, v10, v142
	v_fmac_f32_e32 v222, v11, v143
	v_fmac_f32_e32 v223, v12, v144
	v_fmac_f32_e32 v224, v13, v145
	ds_read_b128 v[142:145], v219 offset:35680
	s_waitcnt lgkmcnt(11)
	v_fmac_f32_e32 v221, v14, v146
	v_fmac_f32_e32 v222, v15, v147
	v_fmac_f32_e32 v223, v16, v148
	v_fmac_f32_e32 v224, v17, v149
	ds_read_b128 v[146:149], v219 offset:35696
	s_waitcnt lgkmcnt(11)
	v_fmac_f32_e32 v221, v18, v150
	v_fmac_f32_e32 v222, v19, v151
	v_fmac_f32_e32 v223, v20, v152
	v_fmac_f32_e32 v224, v21, v153
	ds_read_b128 v[150:153], v219 offset:35840
	s_waitcnt lgkmcnt(11)
	v_fmac_f32_e32 v221, v22, v154
	v_fmac_f32_e32 v222, v23, v155
	v_fmac_f32_e32 v223, v24, v156
	v_fmac_f32_e32 v224, v25, v157
	ds_read_b128 v[154:157], v219 offset:35856
	s_waitcnt lgkmcnt(11)
	v_fmac_f32_e32 v221, v26, v158
	v_fmac_f32_e32 v222, v27, v159
	v_fmac_f32_e32 v223, v28, v160
	v_fmac_f32_e32 v224, v29, v161
	ds_read_b128 v[158:161], v219 offset:35872
	s_waitcnt lgkmcnt(11)
	v_fmac_f32_e32 v221, v30, v162
	v_fmac_f32_e32 v222, v31, v163
	ds_read_b128 v[162:165], v219 offset:35888
	v_add_f32_e32 v225, v222, v221
	v_add_f32_e32 v226, v223, v224
	v_add_f32_e32 v225, v226, v225
	v_fma_f32 v32, v96, v32, -v225
	v_cvt_pk_bf16_f32 v229, v32, v32
	global_store_short v220, v229, s[4:5] offset:3584
	s_waitcnt lgkmcnt(11)
	v_mul_f32_e32 v221, v2, v166
	v_mul_f32_e32 v222, v3, v167
	v_mul_f32_e32 v223, v4, v168
	v_mul_f32_e32 v224, v5, v169
	ds_read_b128 v[166:169], v219 offset:35904
	s_waitcnt lgkmcnt(11)
	v_fmac_f32_e32 v221, v6, v170
	v_fmac_f32_e32 v222, v7, v171
	v_fmac_f32_e32 v223, v8, v172
	v_fmac_f32_e32 v224, v9, v173
	ds_read_b128 v[170:173], v219 offset:35920
	s_waitcnt lgkmcnt(11)
	v_fmac_f32_e32 v221, v10, v174
	v_fmac_f32_e32 v222, v11, v175
	v_fmac_f32_e32 v223, v12, v176
	v_fmac_f32_e32 v224, v13, v177
	ds_read_b128 v[174:177], v219 offset:35936
	s_waitcnt lgkmcnt(11)
	v_fmac_f32_e32 v221, v14, v178
	v_fmac_f32_e32 v222, v15, v179
	v_fmac_f32_e32 v223, v16, v180
	v_fmac_f32_e32 v224, v17, v181
	ds_read_b128 v[178:181], v219 offset:35952
	s_waitcnt lgkmcnt(11)
	v_fmac_f32_e32 v221, v18, v134
	v_fmac_f32_e32 v222, v19, v135
	v_fmac_f32_e32 v223, v20, v136
	v_fmac_f32_e32 v224, v21, v137
	ds_read_b128 v[134:137], v219 offset:36096
	s_waitcnt lgkmcnt(11)
	v_fmac_f32_e32 v221, v22, v138
	v_fmac_f32_e32 v222, v23, v139
	v_fmac_f32_e32 v223, v24, v140
	v_fmac_f32_e32 v224, v25, v141
	ds_read_b128 v[138:141], v219 offset:36112
	s_waitcnt lgkmcnt(11)
	v_fmac_f32_e32 v221, v26, v142
	v_fmac_f32_e32 v222, v27, v143
	v_fmac_f32_e32 v223, v28, v144
	v_fmac_f32_e32 v224, v29, v145
	ds_read_b128 v[142:145], v219 offset:36128
	s_waitcnt lgkmcnt(11)
	v_fmac_f32_e32 v221, v30, v146
	v_fmac_f32_e32 v222, v31, v147
	v_fmac_f32_e32 v223, v32, v148
	ds_read_b128 v[146:149], v219 offset:36144
	v_add_f32_e32 v225, v222, v221
	v_add_f32_e32 v226, v223, v224
	v_add_f32_e32 v225, v226, v225
	v_fma_f32 v33, v97, v33, -v225
	v_cvt_pk_bf16_f32 v230, v33, v33
	global_store_short v220, v230, s[4:5] offset:3840
	s_waitcnt lgkmcnt(11)
	v_mul_f32_e32 v221, v2, v150
	v_mul_f32_e32 v222, v3, v151
	v_mul_f32_e32 v223, v4, v152
	v_mul_f32_e32 v224, v5, v153
	ds_read_b128 v[150:153], v219 offset:36160
	s_waitcnt lgkmcnt(11)
	v_fmac_f32_e32 v221, v6, v154
	v_fmac_f32_e32 v222, v7, v155
	v_fmac_f32_e32 v223, v8, v156
	v_fmac_f32_e32 v224, v9, v157
	ds_read_b128 v[154:157], v219 offset:36176
	s_waitcnt lgkmcnt(11)
	v_fmac_f32_e32 v221, v10, v158
	v_fmac_f32_e32 v222, v11, v159
	v_fmac_f32_e32 v223, v12, v160
	v_fmac_f32_e32 v224, v13, v161
	ds_read_b128 v[158:161], v219 offset:36192
	s_waitcnt lgkmcnt(11)
	v_fmac_f32_e32 v221, v14, v162
	v_fmac_f32_e32 v222, v15, v163
	v_fmac_f32_e32 v223, v16, v164
	v_fmac_f32_e32 v224, v17, v165
	ds_read_b128 v[162:165], v219 offset:36208
	s_waitcnt lgkmcnt(11)
	v_fmac_f32_e32 v221, v18, v166
	v_fmac_f32_e32 v222, v19, v167
	v_fmac_f32_e32 v223, v20, v168
	v_fmac_f32_e32 v224, v21, v169
	ds_read_b128 v[166:169], v219 offset:36224
	s_waitcnt lgkmcnt(11)
	v_fmac_f32_e32 v221, v22, v170
	v_fmac_f32_e32 v222, v23, v171
	v_fmac_f32_e32 v223, v24, v172
	v_fmac_f32_e32 v224, v25, v173
	ds_read_b128 v[170:173], v219 offset:36352
	s_waitcnt lgkmcnt(11)
	v_fmac_f32_e32 v221, v26, v174
	v_fmac_f32_e32 v222, v27, v175
	v_fmac_f32_e32 v223, v28, v176
	v_fmac_f32_e32 v224, v29, v177
	ds_read_b128 v[174:177], v219 offset:36368
	s_waitcnt lgkmcnt(11)
	v_fmac_f32_e32 v221, v30, v178
	v_fmac_f32_e32 v222, v31, v179
	v_fmac_f32_e32 v223, v32, v180
	v_fmac_f32_e32 v224, v33, v181
	ds_read_b128 v[178:181], v219 offset:36384
	v_add_f32_e32 v225, v222, v221
	v_add_f32_e32 v226, v223, v224
	v_add_f32_e32 v225, v226, v225
	v_fma_f32 v34, v98, v34, -v225
	v_add_u32_e32 v220, 0x1000, v220
	v_cvt_pk_bf16_f32 v227, v34, v34
	global_store_short v220, v227, s[4:5]
	s_waitcnt lgkmcnt(11)
	v_mul_f32_e32 v221, v2, v134
	v_mul_f32_e32 v222, v3, v135
	v_mul_f32_e32 v223, v4, v136
	v_mul_f32_e32 v224, v5, v137
	ds_read_b128 v[134:137], v219 offset:36400
	s_waitcnt lgkmcnt(11)
	v_fmac_f32_e32 v221, v6, v138
	v_fmac_f32_e32 v222, v7, v139
	v_fmac_f32_e32 v223, v8, v140
	v_fmac_f32_e32 v224, v9, v141
	ds_read_b128 v[138:141], v219 offset:36416
	s_waitcnt lgkmcnt(11)
	v_fmac_f32_e32 v221, v10, v142
	v_fmac_f32_e32 v222, v11, v143
	v_fmac_f32_e32 v223, v12, v144
	v_fmac_f32_e32 v224, v13, v145
	ds_read_b128 v[142:145], v219 offset:36432
	s_waitcnt lgkmcnt(11)
	v_fmac_f32_e32 v221, v14, v146
	v_fmac_f32_e32 v222, v15, v147
	v_fmac_f32_e32 v223, v16, v148
	v_fmac_f32_e32 v224, v17, v149
	ds_read_b128 v[146:149], v219 offset:36448
	s_waitcnt lgkmcnt(11)
	v_fmac_f32_e32 v221, v18, v150
	v_fmac_f32_e32 v222, v19, v151
	v_fmac_f32_e32 v223, v20, v152
	v_fmac_f32_e32 v224, v21, v153
	ds_read_b128 v[150:153], v219 offset:36464
	s_waitcnt lgkmcnt(11)
	v_fmac_f32_e32 v221, v22, v154
	v_fmac_f32_e32 v222, v23, v155
	v_fmac_f32_e32 v223, v24, v156
	v_fmac_f32_e32 v224, v25, v157
	ds_read_b128 v[154:157], v219 offset:36480
	s_waitcnt lgkmcnt(11)
	v_fmac_f32_e32 v221, v26, v158
	v_fmac_f32_e32 v222, v27, v159
	v_fmac_f32_e32 v223, v28, v160
	v_fmac_f32_e32 v224, v29, v161
	ds_read_b128 v[158:161], v219 offset:36608
	s_waitcnt lgkmcnt(11)
	v_fmac_f32_e32 v221, v30, v162
	v_fmac_f32_e32 v222, v31, v163
	v_fmac_f32_e32 v223, v32, v164
	v_fmac_f32_e32 v224, v33, v165
	ds_read_b128 v[162:165], v219 offset:36624
	s_waitcnt lgkmcnt(11)
	v_fmac_f32_e32 v221, v34, v166
	ds_read_b128 v[166:169], v219 offset:36640
	v_add_f32_e32 v225, v222, v221
	v_add_f32_e32 v226, v223, v224
	v_add_f32_e32 v225, v226, v225
	v_fma_f32 v35, v99, v35, -v225
	v_cvt_pk_bf16_f32 v228, v35, v35
	global_store_short v220, v228, s[4:5] offset:256
	s_waitcnt lgkmcnt(11)
	v_mul_f32_e32 v221, v2, v170
	v_mul_f32_e32 v222, v3, v171
	v_mul_f32_e32 v223, v4, v172
	v_mul_f32_e32 v224, v5, v173
	ds_read_b128 v[170:173], v219 offset:36656
	s_waitcnt lgkmcnt(11)
	v_fmac_f32_e32 v221, v6, v174
	v_fmac_f32_e32 v222, v7, v175
	v_fmac_f32_e32 v223, v8, v176
	v_fmac_f32_e32 v224, v9, v177
	ds_read_b128 v[174:177], v219 offset:36672
	s_waitcnt lgkmcnt(11)
	v_fmac_f32_e32 v221, v10, v178
	v_fmac_f32_e32 v222, v11, v179
	v_fmac_f32_e32 v223, v12, v180
	v_fmac_f32_e32 v224, v13, v181
	ds_read_b128 v[178:181], v219 offset:36688
	s_waitcnt lgkmcnt(11)
	v_fmac_f32_e32 v221, v14, v134
	v_fmac_f32_e32 v222, v15, v135
	v_fmac_f32_e32 v223, v16, v136
	v_fmac_f32_e32 v224, v17, v137
	ds_read_b128 v[134:137], v219 offset:36704
	s_waitcnt lgkmcnt(11)
	v_fmac_f32_e32 v221, v18, v138
	v_fmac_f32_e32 v222, v19, v139
	v_fmac_f32_e32 v223, v20, v140
	v_fmac_f32_e32 v224, v21, v141
	ds_read_b128 v[138:141], v219 offset:36720
	s_waitcnt lgkmcnt(11)
	v_fmac_f32_e32 v221, v22, v142
	v_fmac_f32_e32 v222, v23, v143
	v_fmac_f32_e32 v223, v24, v144
	v_fmac_f32_e32 v224, v25, v145
	ds_read_b128 v[142:145], v219 offset:36736
	s_waitcnt lgkmcnt(11)
	v_fmac_f32_e32 v221, v26, v146
	v_fmac_f32_e32 v222, v27, v147
	v_fmac_f32_e32 v223, v28, v148
	v_fmac_f32_e32 v224, v29, v149
	ds_read_b128 v[146:149], v219 offset:36864
	s_waitcnt lgkmcnt(11)
	v_fmac_f32_e32 v221, v30, v150
	v_fmac_f32_e32 v222, v31, v151
	v_fmac_f32_e32 v223, v32, v152
	v_fmac_f32_e32 v224, v33, v153
	ds_read_b128 v[150:153], v219 offset:36880
	s_waitcnt lgkmcnt(11)
	v_fmac_f32_e32 v221, v34, v154
	v_fmac_f32_e32 v222, v35, v155
	ds_read_b128 v[154:157], v219 offset:36896
	v_add_f32_e32 v225, v222, v221
	v_add_f32_e32 v226, v223, v224
	v_add_f32_e32 v225, v226, v225
	v_fma_f32 v36, v100, v36, -v225
	v_cvt_pk_bf16_f32 v229, v36, v36
	global_store_short v220, v229, s[4:5] offset:512
	s_waitcnt lgkmcnt(11)
	v_mul_f32_e32 v221, v2, v158
	v_mul_f32_e32 v222, v3, v159
	v_mul_f32_e32 v223, v4, v160
	v_mul_f32_e32 v224, v5, v161
	ds_read_b128 v[158:161], v219 offset:36912
	s_waitcnt lgkmcnt(11)
	v_fmac_f32_e32 v221, v6, v162
	v_fmac_f32_e32 v222, v7, v163
	v_fmac_f32_e32 v223, v8, v164
	v_fmac_f32_e32 v224, v9, v165
	ds_read_b128 v[162:165], v219 offset:36928
	s_waitcnt lgkmcnt(11)
	v_fmac_f32_e32 v221, v10, v166
	v_fmac_f32_e32 v222, v11, v167
	v_fmac_f32_e32 v223, v12, v168
	v_fmac_f32_e32 v224, v13, v169
	ds_read_b128 v[166:169], v219 offset:36944
	s_waitcnt lgkmcnt(11)
	v_fmac_f32_e32 v221, v14, v170
	v_fmac_f32_e32 v222, v15, v171
	v_fmac_f32_e32 v223, v16, v172
	v_fmac_f32_e32 v224, v17, v173
	ds_read_b128 v[170:173], v219 offset:36960
	s_waitcnt lgkmcnt(11)
	v_fmac_f32_e32 v221, v18, v174
	v_fmac_f32_e32 v222, v19, v175
	v_fmac_f32_e32 v223, v20, v176
	v_fmac_f32_e32 v224, v21, v177
	ds_read_b128 v[174:177], v219 offset:36976
	s_waitcnt lgkmcnt(11)
	v_fmac_f32_e32 v221, v22, v178
	v_fmac_f32_e32 v222, v23, v179
	v_fmac_f32_e32 v223, v24, v180
	v_fmac_f32_e32 v224, v25, v181
	ds_read_b128 v[178:181], v219 offset:36992
	s_waitcnt lgkmcnt(11)
	v_fmac_f32_e32 v221, v26, v134
	v_fmac_f32_e32 v222, v27, v135
	v_fmac_f32_e32 v223, v28, v136
	v_fmac_f32_e32 v224, v29, v137
	ds_read_b128 v[134:137], v219 offset:37120
	s_waitcnt lgkmcnt(11)
	v_fmac_f32_e32 v221, v30, v138
	v_fmac_f32_e32 v222, v31, v139
	v_fmac_f32_e32 v223, v32, v140
	v_fmac_f32_e32 v224, v33, v141
	ds_read_b128 v[138:141], v219 offset:37136
	s_waitcnt lgkmcnt(11)
	v_fmac_f32_e32 v221, v34, v142
	v_fmac_f32_e32 v222, v35, v143
	v_fmac_f32_e32 v223, v36, v144
	ds_read_b128 v[142:145], v219 offset:37152
	v_add_f32_e32 v225, v222, v221
	v_add_f32_e32 v226, v223, v224
	v_add_f32_e32 v225, v226, v225
	v_fma_f32 v37, v101, v37, -v225
	v_cvt_pk_bf16_f32 v230, v37, v37
	global_store_short v220, v230, s[4:5] offset:768
	s_waitcnt lgkmcnt(11)
	v_mul_f32_e32 v221, v2, v146
	v_mul_f32_e32 v222, v3, v147
	v_mul_f32_e32 v223, v4, v148
	v_mul_f32_e32 v224, v5, v149
	ds_read_b128 v[146:149], v219 offset:37168
	s_waitcnt lgkmcnt(11)
	v_fmac_f32_e32 v221, v6, v150
	v_fmac_f32_e32 v222, v7, v151
	v_fmac_f32_e32 v223, v8, v152
	v_fmac_f32_e32 v224, v9, v153
	ds_read_b128 v[150:153], v219 offset:37184
	s_waitcnt lgkmcnt(11)
	v_fmac_f32_e32 v221, v10, v154
	v_fmac_f32_e32 v222, v11, v155
	v_fmac_f32_e32 v223, v12, v156
	v_fmac_f32_e32 v224, v13, v157
	ds_read_b128 v[154:157], v219 offset:37200
	s_waitcnt lgkmcnt(11)
	v_fmac_f32_e32 v221, v14, v158
	v_fmac_f32_e32 v222, v15, v159
	v_fmac_f32_e32 v223, v16, v160
	v_fmac_f32_e32 v224, v17, v161
	ds_read_b128 v[158:161], v219 offset:37216
	s_waitcnt lgkmcnt(11)
	v_fmac_f32_e32 v221, v18, v162
	v_fmac_f32_e32 v222, v19, v163
	v_fmac_f32_e32 v223, v20, v164
	v_fmac_f32_e32 v224, v21, v165
	ds_read_b128 v[162:165], v219 offset:37232
	s_waitcnt lgkmcnt(11)
	v_fmac_f32_e32 v221, v22, v166
	v_fmac_f32_e32 v222, v23, v167
	v_fmac_f32_e32 v223, v24, v168
	v_fmac_f32_e32 v224, v25, v169
	ds_read_b128 v[166:169], v219 offset:37248
	s_waitcnt lgkmcnt(11)
	v_fmac_f32_e32 v221, v26, v170
	v_fmac_f32_e32 v222, v27, v171
	v_fmac_f32_e32 v223, v28, v172
	v_fmac_f32_e32 v224, v29, v173
	ds_read_b128 v[170:173], v219 offset:37264
	s_waitcnt lgkmcnt(11)
	v_fmac_f32_e32 v221, v30, v174
	v_fmac_f32_e32 v222, v31, v175
	v_fmac_f32_e32 v223, v32, v176
	v_fmac_f32_e32 v224, v33, v177
	ds_read_b128 v[174:177], v219 offset:37376
	s_waitcnt lgkmcnt(11)
	v_fmac_f32_e32 v221, v34, v178
	v_fmac_f32_e32 v222, v35, v179
	v_fmac_f32_e32 v223, v36, v180
	v_fmac_f32_e32 v224, v37, v181
	ds_read_b128 v[178:181], v219 offset:37392
	v_add_f32_e32 v225, v222, v221
	v_add_f32_e32 v226, v223, v224
	v_add_f32_e32 v225, v226, v225
	v_fma_f32 v38, v102, v38, -v225
	v_cvt_pk_bf16_f32 v227, v38, v38
	global_store_short v220, v227, s[4:5] offset:1024
	s_waitcnt lgkmcnt(11)
	v_mul_f32_e32 v221, v2, v134
	v_mul_f32_e32 v222, v3, v135
	v_mul_f32_e32 v223, v4, v136
	v_mul_f32_e32 v224, v5, v137
	ds_read_b128 v[134:137], v219 offset:37408
	s_waitcnt lgkmcnt(11)
	v_fmac_f32_e32 v221, v6, v138
	v_fmac_f32_e32 v222, v7, v139
	v_fmac_f32_e32 v223, v8, v140
	v_fmac_f32_e32 v224, v9, v141
	ds_read_b128 v[138:141], v219 offset:37424
	s_waitcnt lgkmcnt(11)
	v_fmac_f32_e32 v221, v10, v142
	v_fmac_f32_e32 v222, v11, v143
	v_fmac_f32_e32 v223, v12, v144
	v_fmac_f32_e32 v224, v13, v145
	ds_read_b128 v[142:145], v219 offset:37440
	s_waitcnt lgkmcnt(11)
	v_fmac_f32_e32 v221, v14, v146
	v_fmac_f32_e32 v222, v15, v147
	v_fmac_f32_e32 v223, v16, v148
	v_fmac_f32_e32 v224, v17, v149
	ds_read_b128 v[146:149], v219 offset:37456
	s_waitcnt lgkmcnt(11)
	v_fmac_f32_e32 v221, v18, v150
	v_fmac_f32_e32 v222, v19, v151
	v_fmac_f32_e32 v223, v20, v152
	v_fmac_f32_e32 v224, v21, v153
	ds_read_b128 v[150:153], v219 offset:37472
	s_waitcnt lgkmcnt(11)
	v_fmac_f32_e32 v221, v22, v154
	v_fmac_f32_e32 v222, v23, v155
	v_fmac_f32_e32 v223, v24, v156
	v_fmac_f32_e32 v224, v25, v157
	ds_read_b128 v[154:157], v219 offset:37488
	s_waitcnt lgkmcnt(11)
	v_fmac_f32_e32 v221, v26, v158
	v_fmac_f32_e32 v222, v27, v159
	v_fmac_f32_e32 v223, v28, v160
	v_fmac_f32_e32 v224, v29, v161
	ds_read_b128 v[158:161], v219 offset:37504
	s_waitcnt lgkmcnt(11)
	v_fmac_f32_e32 v221, v30, v162
	v_fmac_f32_e32 v222, v31, v163
	v_fmac_f32_e32 v223, v32, v164
	v_fmac_f32_e32 v224, v33, v165
	ds_read_b128 v[162:165], v219 offset:37520
	s_waitcnt lgkmcnt(11)
	v_fmac_f32_e32 v221, v34, v166
	v_fmac_f32_e32 v222, v35, v167
	v_fmac_f32_e32 v223, v36, v168
	v_fmac_f32_e32 v224, v37, v169
	ds_read_b128 v[166:169], v219 offset:37632
	s_waitcnt lgkmcnt(11)
	v_fmac_f32_e32 v221, v38, v170
	ds_read_b128 v[170:173], v219 offset:37648
	v_add_f32_e32 v225, v222, v221
	v_add_f32_e32 v226, v223, v224
	v_add_f32_e32 v225, v226, v225
	v_fma_f32 v39, v103, v39, -v225
	v_cvt_pk_bf16_f32 v228, v39, v39
	global_store_short v220, v228, s[4:5] offset:1280
	s_waitcnt lgkmcnt(11)
	v_mul_f32_e32 v221, v2, v174
	v_mul_f32_e32 v222, v3, v175
	v_mul_f32_e32 v223, v4, v176
	v_mul_f32_e32 v224, v5, v177
	ds_read_b128 v[174:177], v219 offset:37664
	s_waitcnt lgkmcnt(11)
	v_fmac_f32_e32 v221, v6, v178
	v_fmac_f32_e32 v222, v7, v179
	v_fmac_f32_e32 v223, v8, v180
	v_fmac_f32_e32 v224, v9, v181
	ds_read_b128 v[178:181], v219 offset:37680
	s_waitcnt lgkmcnt(11)
	v_fmac_f32_e32 v221, v10, v134
	v_fmac_f32_e32 v222, v11, v135
	v_fmac_f32_e32 v223, v12, v136
	v_fmac_f32_e32 v224, v13, v137
	ds_read_b128 v[134:137], v219 offset:37696
	s_waitcnt lgkmcnt(11)
	v_fmac_f32_e32 v221, v14, v138
	v_fmac_f32_e32 v222, v15, v139
	v_fmac_f32_e32 v223, v16, v140
	v_fmac_f32_e32 v224, v17, v141
	ds_read_b128 v[138:141], v219 offset:37712
	s_waitcnt lgkmcnt(11)
	v_fmac_f32_e32 v221, v18, v142
	v_fmac_f32_e32 v222, v19, v143
	v_fmac_f32_e32 v223, v20, v144
	v_fmac_f32_e32 v224, v21, v145
	ds_read_b128 v[142:145], v219 offset:37728
	s_waitcnt lgkmcnt(11)
	v_fmac_f32_e32 v221, v22, v146
	v_fmac_f32_e32 v222, v23, v147
	v_fmac_f32_e32 v223, v24, v148
	v_fmac_f32_e32 v224, v25, v149
	ds_read_b128 v[146:149], v219 offset:37744
	s_waitcnt lgkmcnt(11)
	v_fmac_f32_e32 v221, v26, v150
	v_fmac_f32_e32 v222, v27, v151
	v_fmac_f32_e32 v223, v28, v152
	v_fmac_f32_e32 v224, v29, v153
	ds_read_b128 v[150:153], v219 offset:37760
	s_waitcnt lgkmcnt(11)
	v_fmac_f32_e32 v221, v30, v154
	v_fmac_f32_e32 v222, v31, v155
	v_fmac_f32_e32 v223, v32, v156
	v_fmac_f32_e32 v224, v33, v157
	ds_read_b128 v[154:157], v219 offset:37776
	s_waitcnt lgkmcnt(11)
	v_fmac_f32_e32 v221, v34, v158
	v_fmac_f32_e32 v222, v35, v159
	v_fmac_f32_e32 v223, v36, v160
	v_fmac_f32_e32 v224, v37, v161
	ds_read_b128 v[158:161], v219 offset:37888
	s_waitcnt lgkmcnt(11)
	v_fmac_f32_e32 v221, v38, v162
	v_fmac_f32_e32 v222, v39, v163
	ds_read_b128 v[162:165], v219 offset:37904
	v_add_f32_e32 v225, v222, v221
	v_add_f32_e32 v226, v223, v224
	v_add_f32_e32 v225, v226, v225
	v_fma_f32 v40, v104, v40, -v225
	v_cvt_pk_bf16_f32 v229, v40, v40
	global_store_short v220, v229, s[4:5] offset:1536
	s_waitcnt lgkmcnt(11)
	v_mul_f32_e32 v221, v2, v166
	v_mul_f32_e32 v222, v3, v167
	v_mul_f32_e32 v223, v4, v168
	v_mul_f32_e32 v224, v5, v169
	ds_read_b128 v[166:169], v219 offset:37920
	s_waitcnt lgkmcnt(11)
	v_fmac_f32_e32 v221, v6, v170
	v_fmac_f32_e32 v222, v7, v171
	v_fmac_f32_e32 v223, v8, v172
	v_fmac_f32_e32 v224, v9, v173
	ds_read_b128 v[170:173], v219 offset:37936
	s_waitcnt lgkmcnt(11)
	v_fmac_f32_e32 v221, v10, v174
	v_fmac_f32_e32 v222, v11, v175
	v_fmac_f32_e32 v223, v12, v176
	v_fmac_f32_e32 v224, v13, v177
	ds_read_b128 v[174:177], v219 offset:37952
	s_waitcnt lgkmcnt(11)
	v_fmac_f32_e32 v221, v14, v178
	v_fmac_f32_e32 v222, v15, v179
	v_fmac_f32_e32 v223, v16, v180
	v_fmac_f32_e32 v224, v17, v181
	ds_read_b128 v[178:181], v219 offset:37968
	s_waitcnt lgkmcnt(11)
	v_fmac_f32_e32 v221, v18, v134
	v_fmac_f32_e32 v222, v19, v135
	v_fmac_f32_e32 v223, v20, v136
	v_fmac_f32_e32 v224, v21, v137
	ds_read_b128 v[134:137], v219 offset:37984
	s_waitcnt lgkmcnt(11)
	v_fmac_f32_e32 v221, v22, v138
	v_fmac_f32_e32 v222, v23, v139
	v_fmac_f32_e32 v223, v24, v140
	v_fmac_f32_e32 v224, v25, v141
	ds_read_b128 v[138:141], v219 offset:38000
	s_waitcnt lgkmcnt(11)
	v_fmac_f32_e32 v221, v26, v142
	v_fmac_f32_e32 v222, v27, v143
	v_fmac_f32_e32 v223, v28, v144
	v_fmac_f32_e32 v224, v29, v145
	ds_read_b128 v[142:145], v219 offset:38016
	s_waitcnt lgkmcnt(11)
	v_fmac_f32_e32 v221, v30, v146
	v_fmac_f32_e32 v222, v31, v147
	v_fmac_f32_e32 v223, v32, v148
	v_fmac_f32_e32 v224, v33, v149
	ds_read_b128 v[146:149], v219 offset:38032
	s_waitcnt lgkmcnt(11)
	v_fmac_f32_e32 v221, v34, v150
	v_fmac_f32_e32 v222, v35, v151
	v_fmac_f32_e32 v223, v36, v152
	v_fmac_f32_e32 v224, v37, v153
	ds_read_b128 v[150:153], v219 offset:38144
	s_waitcnt lgkmcnt(11)
	v_fmac_f32_e32 v221, v38, v154
	v_fmac_f32_e32 v222, v39, v155
	v_fmac_f32_e32 v223, v40, v156
	ds_read_b128 v[154:157], v219 offset:38160
	v_add_f32_e32 v225, v222, v221
	v_add_f32_e32 v226, v223, v224
	v_add_f32_e32 v225, v226, v225
	v_fma_f32 v41, v105, v41, -v225
	v_cvt_pk_bf16_f32 v230, v41, v41
	global_store_short v220, v230, s[4:5] offset:1792
	s_waitcnt lgkmcnt(11)
	v_mul_f32_e32 v221, v2, v158
	v_mul_f32_e32 v222, v3, v159
	v_mul_f32_e32 v223, v4, v160
	v_mul_f32_e32 v224, v5, v161
	ds_read_b128 v[158:161], v219 offset:38176
	s_waitcnt lgkmcnt(11)
	v_fmac_f32_e32 v221, v6, v162
	v_fmac_f32_e32 v222, v7, v163
	v_fmac_f32_e32 v223, v8, v164
	v_fmac_f32_e32 v224, v9, v165
	ds_read_b128 v[162:165], v219 offset:38192
	s_waitcnt lgkmcnt(11)
	v_fmac_f32_e32 v221, v10, v166
	v_fmac_f32_e32 v222, v11, v167
	v_fmac_f32_e32 v223, v12, v168
	v_fmac_f32_e32 v224, v13, v169
	ds_read_b128 v[166:169], v219 offset:38208
	s_waitcnt lgkmcnt(11)
	v_fmac_f32_e32 v221, v14, v170
	v_fmac_f32_e32 v222, v15, v171
	v_fmac_f32_e32 v223, v16, v172
	v_fmac_f32_e32 v224, v17, v173
	ds_read_b128 v[170:173], v219 offset:38224
	s_waitcnt lgkmcnt(11)
	v_fmac_f32_e32 v221, v18, v174
	v_fmac_f32_e32 v222, v19, v175
	v_fmac_f32_e32 v223, v20, v176
	v_fmac_f32_e32 v224, v21, v177
	ds_read_b128 v[174:177], v219 offset:38240
	s_waitcnt lgkmcnt(11)
	v_fmac_f32_e32 v221, v22, v178
	v_fmac_f32_e32 v222, v23, v179
	v_fmac_f32_e32 v223, v24, v180
	v_fmac_f32_e32 v224, v25, v181
	ds_read_b128 v[178:181], v219 offset:38256
	s_waitcnt lgkmcnt(11)
	v_fmac_f32_e32 v221, v26, v134
	v_fmac_f32_e32 v222, v27, v135
	v_fmac_f32_e32 v223, v28, v136
	v_fmac_f32_e32 v224, v29, v137
	ds_read_b128 v[134:137], v219 offset:38272
	s_waitcnt lgkmcnt(11)
	v_fmac_f32_e32 v221, v30, v138
	v_fmac_f32_e32 v222, v31, v139
	v_fmac_f32_e32 v223, v32, v140
	v_fmac_f32_e32 v224, v33, v141
	ds_read_b128 v[138:141], v219 offset:38288
	s_waitcnt lgkmcnt(11)
	v_fmac_f32_e32 v221, v34, v142
	v_fmac_f32_e32 v222, v35, v143
	v_fmac_f32_e32 v223, v36, v144
	v_fmac_f32_e32 v224, v37, v145
	ds_read_b128 v[142:145], v219 offset:38304
	s_waitcnt lgkmcnt(11)
	v_fmac_f32_e32 v221, v38, v146
	v_fmac_f32_e32 v222, v39, v147
	v_fmac_f32_e32 v223, v40, v148
	v_fmac_f32_e32 v224, v41, v149
	ds_read_b128 v[146:149], v219 offset:38400
	v_add_f32_e32 v225, v222, v221
	v_add_f32_e32 v226, v223, v224
	v_add_f32_e32 v225, v226, v225
	v_fma_f32 v42, v106, v42, -v225
	v_cvt_pk_bf16_f32 v227, v42, v42
	global_store_short v220, v227, s[4:5] offset:2048
	s_waitcnt lgkmcnt(11)
	v_mul_f32_e32 v221, v2, v150
	v_mul_f32_e32 v222, v3, v151
	v_mul_f32_e32 v223, v4, v152
	v_mul_f32_e32 v224, v5, v153
	ds_read_b128 v[150:153], v219 offset:38416
	s_waitcnt lgkmcnt(11)
	v_fmac_f32_e32 v221, v6, v154
	v_fmac_f32_e32 v222, v7, v155
	v_fmac_f32_e32 v223, v8, v156
	v_fmac_f32_e32 v224, v9, v157
	ds_read_b128 v[154:157], v219 offset:38432
	s_waitcnt lgkmcnt(11)
	v_fmac_f32_e32 v221, v10, v158
	v_fmac_f32_e32 v222, v11, v159
	v_fmac_f32_e32 v223, v12, v160
	v_fmac_f32_e32 v224, v13, v161
	ds_read_b128 v[158:161], v219 offset:38448
	s_waitcnt lgkmcnt(11)
	v_fmac_f32_e32 v221, v14, v162
	v_fmac_f32_e32 v222, v15, v163
	v_fmac_f32_e32 v223, v16, v164
	v_fmac_f32_e32 v224, v17, v165
	ds_read_b128 v[162:165], v219 offset:38464
	s_waitcnt lgkmcnt(11)
	v_fmac_f32_e32 v221, v18, v166
	v_fmac_f32_e32 v222, v19, v167
	v_fmac_f32_e32 v223, v20, v168
	v_fmac_f32_e32 v224, v21, v169
	ds_read_b128 v[166:169], v219 offset:38480
	s_waitcnt lgkmcnt(11)
	v_fmac_f32_e32 v221, v22, v170
	v_fmac_f32_e32 v222, v23, v171
	v_fmac_f32_e32 v223, v24, v172
	v_fmac_f32_e32 v224, v25, v173
	ds_read_b128 v[170:173], v219 offset:38496
	s_waitcnt lgkmcnt(11)
	v_fmac_f32_e32 v221, v26, v174
	v_fmac_f32_e32 v222, v27, v175
	v_fmac_f32_e32 v223, v28, v176
	v_fmac_f32_e32 v224, v29, v177
	ds_read_b128 v[174:177], v219 offset:38512
	s_waitcnt lgkmcnt(11)
	v_fmac_f32_e32 v221, v30, v178
	v_fmac_f32_e32 v222, v31, v179
	v_fmac_f32_e32 v223, v32, v180
	v_fmac_f32_e32 v224, v33, v181
	ds_read_b128 v[178:181], v219 offset:38528
	s_waitcnt lgkmcnt(11)
	v_fmac_f32_e32 v221, v34, v134
	v_fmac_f32_e32 v222, v35, v135
	v_fmac_f32_e32 v223, v36, v136
	v_fmac_f32_e32 v224, v37, v137
	ds_read_b128 v[134:137], v219 offset:38544
	s_waitcnt lgkmcnt(11)
	v_fmac_f32_e32 v221, v38, v138
	v_fmac_f32_e32 v222, v39, v139
	v_fmac_f32_e32 v223, v40, v140
	v_fmac_f32_e32 v224, v41, v141
	ds_read_b128 v[138:141], v219 offset:38560
	s_waitcnt lgkmcnt(11)
	v_fmac_f32_e32 v221, v42, v142
	ds_read_b128 v[142:145], v219 offset:38656
	v_add_f32_e32 v225, v222, v221
	v_add_f32_e32 v226, v223, v224
	v_add_f32_e32 v225, v226, v225
	v_fma_f32 v43, v107, v43, -v225
	v_cvt_pk_bf16_f32 v228, v43, v43
	global_store_short v220, v228, s[4:5] offset:2304
	s_waitcnt lgkmcnt(11)
	v_mul_f32_e32 v221, v2, v146
	v_mul_f32_e32 v222, v3, v147
	v_mul_f32_e32 v223, v4, v148
	v_mul_f32_e32 v224, v5, v149
	ds_read_b128 v[146:149], v219 offset:38672
	s_waitcnt lgkmcnt(11)
	v_fmac_f32_e32 v221, v6, v150
	v_fmac_f32_e32 v222, v7, v151
	v_fmac_f32_e32 v223, v8, v152
	v_fmac_f32_e32 v224, v9, v153
	ds_read_b128 v[150:153], v219 offset:38688
	s_waitcnt lgkmcnt(11)
	v_fmac_f32_e32 v221, v10, v154
	v_fmac_f32_e32 v222, v11, v155
	v_fmac_f32_e32 v223, v12, v156
	v_fmac_f32_e32 v224, v13, v157
	ds_read_b128 v[154:157], v219 offset:38704
	s_waitcnt lgkmcnt(11)
	v_fmac_f32_e32 v221, v14, v158
	v_fmac_f32_e32 v222, v15, v159
	v_fmac_f32_e32 v223, v16, v160
	v_fmac_f32_e32 v224, v17, v161
	ds_read_b128 v[158:161], v219 offset:38720
	s_waitcnt lgkmcnt(11)
	v_fmac_f32_e32 v221, v18, v162
	v_fmac_f32_e32 v222, v19, v163
	v_fmac_f32_e32 v223, v20, v164
	v_fmac_f32_e32 v224, v21, v165
	ds_read_b128 v[162:165], v219 offset:38736
	s_waitcnt lgkmcnt(11)
	v_fmac_f32_e32 v221, v22, v166
	v_fmac_f32_e32 v222, v23, v167
	v_fmac_f32_e32 v223, v24, v168
	v_fmac_f32_e32 v224, v25, v169
	ds_read_b128 v[166:169], v219 offset:38752
	s_waitcnt lgkmcnt(11)
	v_fmac_f32_e32 v221, v26, v170
	v_fmac_f32_e32 v222, v27, v171
	v_fmac_f32_e32 v223, v28, v172
	v_fmac_f32_e32 v224, v29, v173
	ds_read_b128 v[170:173], v219 offset:38768
	s_waitcnt lgkmcnt(11)
	v_fmac_f32_e32 v221, v30, v174
	v_fmac_f32_e32 v222, v31, v175
	v_fmac_f32_e32 v223, v32, v176
	v_fmac_f32_e32 v224, v33, v177
	ds_read_b128 v[174:177], v219 offset:38784
	s_waitcnt lgkmcnt(11)
	v_fmac_f32_e32 v221, v34, v178
	v_fmac_f32_e32 v222, v35, v179
	v_fmac_f32_e32 v223, v36, v180
	v_fmac_f32_e32 v224, v37, v181
	ds_read_b128 v[178:181], v219 offset:38800
	s_waitcnt lgkmcnt(11)
	v_fmac_f32_e32 v221, v38, v134
	v_fmac_f32_e32 v222, v39, v135
	v_fmac_f32_e32 v223, v40, v136
	v_fmac_f32_e32 v224, v41, v137
	ds_read_b128 v[134:137], v219 offset:38816
	s_waitcnt lgkmcnt(11)
	v_fmac_f32_e32 v221, v42, v138
	v_fmac_f32_e32 v222, v43, v139
	ds_read_b128 v[138:141], v219 offset:38912
	v_add_f32_e32 v225, v222, v221
	v_add_f32_e32 v226, v223, v224
	v_add_f32_e32 v225, v226, v225
	v_fma_f32 v44, v108, v44, -v225
	v_cvt_pk_bf16_f32 v229, v44, v44
	global_store_short v220, v229, s[4:5] offset:2560
	s_waitcnt lgkmcnt(11)
	v_mul_f32_e32 v221, v2, v142
	v_mul_f32_e32 v222, v3, v143
	v_mul_f32_e32 v223, v4, v144
	v_mul_f32_e32 v224, v5, v145
	ds_read_b128 v[142:145], v219 offset:38928
	s_waitcnt lgkmcnt(11)
	v_fmac_f32_e32 v221, v6, v146
	v_fmac_f32_e32 v222, v7, v147
	v_fmac_f32_e32 v223, v8, v148
	v_fmac_f32_e32 v224, v9, v149
	ds_read_b128 v[146:149], v219 offset:38944
	s_waitcnt lgkmcnt(11)
	v_fmac_f32_e32 v221, v10, v150
	v_fmac_f32_e32 v222, v11, v151
	v_fmac_f32_e32 v223, v12, v152
	v_fmac_f32_e32 v224, v13, v153
	ds_read_b128 v[150:153], v219 offset:38960
	s_waitcnt lgkmcnt(11)
	v_fmac_f32_e32 v221, v14, v154
	v_fmac_f32_e32 v222, v15, v155
	v_fmac_f32_e32 v223, v16, v156
	v_fmac_f32_e32 v224, v17, v157
	ds_read_b128 v[154:157], v219 offset:38976
	s_waitcnt lgkmcnt(11)
	v_fmac_f32_e32 v221, v18, v158
	v_fmac_f32_e32 v222, v19, v159
	v_fmac_f32_e32 v223, v20, v160
	v_fmac_f32_e32 v224, v21, v161
	ds_read_b128 v[158:161], v219 offset:38992
	s_waitcnt lgkmcnt(11)
	v_fmac_f32_e32 v221, v22, v162
	v_fmac_f32_e32 v222, v23, v163
	v_fmac_f32_e32 v223, v24, v164
	v_fmac_f32_e32 v224, v25, v165
	ds_read_b128 v[162:165], v219 offset:39008
	s_waitcnt lgkmcnt(11)
	v_fmac_f32_e32 v221, v26, v166
	v_fmac_f32_e32 v222, v27, v167
	v_fmac_f32_e32 v223, v28, v168
	v_fmac_f32_e32 v224, v29, v169
	ds_read_b128 v[166:169], v219 offset:39024
	s_waitcnt lgkmcnt(11)
	v_fmac_f32_e32 v221, v30, v170
	v_fmac_f32_e32 v222, v31, v171
	v_fmac_f32_e32 v223, v32, v172
	v_fmac_f32_e32 v224, v33, v173
	ds_read_b128 v[170:173], v219 offset:39040
	s_waitcnt lgkmcnt(11)
	v_fmac_f32_e32 v221, v34, v174
	v_fmac_f32_e32 v222, v35, v175
	v_fmac_f32_e32 v223, v36, v176
	v_fmac_f32_e32 v224, v37, v177
	ds_read_b128 v[174:177], v219 offset:39056
	s_waitcnt lgkmcnt(11)
	v_fmac_f32_e32 v221, v38, v178
	v_fmac_f32_e32 v222, v39, v179
	v_fmac_f32_e32 v223, v40, v180
	v_fmac_f32_e32 v224, v41, v181
	ds_read_b128 v[178:181], v219 offset:39072
	s_waitcnt lgkmcnt(11)
	v_fmac_f32_e32 v221, v42, v134
	v_fmac_f32_e32 v222, v43, v135
	v_fmac_f32_e32 v223, v44, v136
	ds_read_b128 v[134:137], v219 offset:39168
	v_add_f32_e32 v225, v222, v221
	v_add_f32_e32 v226, v223, v224
	v_add_f32_e32 v225, v226, v225
	v_fma_f32 v45, v109, v45, -v225
	v_cvt_pk_bf16_f32 v230, v45, v45
	global_store_short v220, v230, s[4:5] offset:2816
	s_waitcnt lgkmcnt(11)
	v_mul_f32_e32 v221, v2, v138
	v_mul_f32_e32 v222, v3, v139
	v_mul_f32_e32 v223, v4, v140
	v_mul_f32_e32 v224, v5, v141
	ds_read_b128 v[138:141], v219 offset:39184
	s_waitcnt lgkmcnt(11)
	v_fmac_f32_e32 v221, v6, v142
	v_fmac_f32_e32 v222, v7, v143
	v_fmac_f32_e32 v223, v8, v144
	v_fmac_f32_e32 v224, v9, v145
	ds_read_b128 v[142:145], v219 offset:39200
	s_waitcnt lgkmcnt(11)
	v_fmac_f32_e32 v221, v10, v146
	v_fmac_f32_e32 v222, v11, v147
	v_fmac_f32_e32 v223, v12, v148
	v_fmac_f32_e32 v224, v13, v149
	ds_read_b128 v[146:149], v219 offset:39216
	s_waitcnt lgkmcnt(11)
	v_fmac_f32_e32 v221, v14, v150
	v_fmac_f32_e32 v222, v15, v151
	v_fmac_f32_e32 v223, v16, v152
	v_fmac_f32_e32 v224, v17, v153
	ds_read_b128 v[150:153], v219 offset:39232
	s_waitcnt lgkmcnt(11)
	v_fmac_f32_e32 v221, v18, v154
	v_fmac_f32_e32 v222, v19, v155
	v_fmac_f32_e32 v223, v20, v156
	v_fmac_f32_e32 v224, v21, v157
	ds_read_b128 v[154:157], v219 offset:39248
	s_waitcnt lgkmcnt(11)
	v_fmac_f32_e32 v221, v22, v158
	v_fmac_f32_e32 v222, v23, v159
	v_fmac_f32_e32 v223, v24, v160
	v_fmac_f32_e32 v224, v25, v161
	ds_read_b128 v[158:161], v219 offset:39264
	s_waitcnt lgkmcnt(11)
	v_fmac_f32_e32 v221, v26, v162
	v_fmac_f32_e32 v222, v27, v163
	v_fmac_f32_e32 v223, v28, v164
	v_fmac_f32_e32 v224, v29, v165
	ds_read_b128 v[162:165], v219 offset:39280
	s_waitcnt lgkmcnt(11)
	v_fmac_f32_e32 v221, v30, v166
	v_fmac_f32_e32 v222, v31, v167
	v_fmac_f32_e32 v223, v32, v168
	v_fmac_f32_e32 v224, v33, v169
	ds_read_b128 v[166:169], v219 offset:39296
	s_waitcnt lgkmcnt(11)
	v_fmac_f32_e32 v221, v34, v170
	v_fmac_f32_e32 v222, v35, v171
	v_fmac_f32_e32 v223, v36, v172
	v_fmac_f32_e32 v224, v37, v173
	ds_read_b128 v[170:173], v219 offset:39312
	s_waitcnt lgkmcnt(11)
	v_fmac_f32_e32 v221, v38, v174
	v_fmac_f32_e32 v222, v39, v175
	v_fmac_f32_e32 v223, v40, v176
	v_fmac_f32_e32 v224, v41, v177
	ds_read_b128 v[174:177], v219 offset:39328
	s_waitcnt lgkmcnt(11)
	v_fmac_f32_e32 v221, v42, v178
	v_fmac_f32_e32 v222, v43, v179
	v_fmac_f32_e32 v223, v44, v180
	v_fmac_f32_e32 v224, v45, v181
	ds_read_b128 v[178:181], v219 offset:39344
	v_add_f32_e32 v225, v222, v221
	v_add_f32_e32 v226, v223, v224
	v_add_f32_e32 v225, v226, v225
	v_fma_f32 v46, v110, v46, -v225
	v_cvt_pk_bf16_f32 v227, v46, v46
	global_store_short v220, v227, s[4:5] offset:3072
	s_waitcnt lgkmcnt(11)
	v_mul_f32_e32 v221, v2, v134
	v_mul_f32_e32 v222, v3, v135
	v_mul_f32_e32 v223, v4, v136
	v_mul_f32_e32 v224, v5, v137
	ds_read_b128 v[134:137], v219 offset:39424
	s_waitcnt lgkmcnt(11)
	v_fmac_f32_e32 v221, v6, v138
	v_fmac_f32_e32 v222, v7, v139
	v_fmac_f32_e32 v223, v8, v140
	v_fmac_f32_e32 v224, v9, v141
	ds_read_b128 v[138:141], v219 offset:39440
	s_waitcnt lgkmcnt(11)
	v_fmac_f32_e32 v221, v10, v142
	v_fmac_f32_e32 v222, v11, v143
	v_fmac_f32_e32 v223, v12, v144
	v_fmac_f32_e32 v224, v13, v145
	ds_read_b128 v[142:145], v219 offset:39456
	s_waitcnt lgkmcnt(11)
	v_fmac_f32_e32 v221, v14, v146
	v_fmac_f32_e32 v222, v15, v147
	v_fmac_f32_e32 v223, v16, v148
	v_fmac_f32_e32 v224, v17, v149
	ds_read_b128 v[146:149], v219 offset:39472
	s_waitcnt lgkmcnt(11)
	v_fmac_f32_e32 v221, v18, v150
	v_fmac_f32_e32 v222, v19, v151
	v_fmac_f32_e32 v223, v20, v152
	v_fmac_f32_e32 v224, v21, v153
	ds_read_b128 v[150:153], v219 offset:39488
	s_waitcnt lgkmcnt(11)
	v_fmac_f32_e32 v221, v22, v154
	v_fmac_f32_e32 v222, v23, v155
	v_fmac_f32_e32 v223, v24, v156
	v_fmac_f32_e32 v224, v25, v157
	ds_read_b128 v[154:157], v219 offset:39504
	s_waitcnt lgkmcnt(11)
	v_fmac_f32_e32 v221, v26, v158
	v_fmac_f32_e32 v222, v27, v159
	v_fmac_f32_e32 v223, v28, v160
	v_fmac_f32_e32 v224, v29, v161
	ds_read_b128 v[158:161], v219 offset:39520
	s_waitcnt lgkmcnt(11)
	v_fmac_f32_e32 v221, v30, v162
	v_fmac_f32_e32 v222, v31, v163
	v_fmac_f32_e32 v223, v32, v164
	v_fmac_f32_e32 v224, v33, v165
	ds_read_b128 v[162:165], v219 offset:39536
	s_waitcnt lgkmcnt(11)
	v_fmac_f32_e32 v221, v34, v166
	v_fmac_f32_e32 v222, v35, v167
	v_fmac_f32_e32 v223, v36, v168
	v_fmac_f32_e32 v224, v37, v169
	ds_read_b128 v[166:169], v219 offset:39552
	s_waitcnt lgkmcnt(11)
	v_fmac_f32_e32 v221, v38, v170
	v_fmac_f32_e32 v222, v39, v171
	v_fmac_f32_e32 v223, v40, v172
	v_fmac_f32_e32 v224, v41, v173
	ds_read_b128 v[170:173], v219 offset:39568
	s_waitcnt lgkmcnt(11)
	v_fmac_f32_e32 v221, v42, v174
	v_fmac_f32_e32 v222, v43, v175
	v_fmac_f32_e32 v223, v44, v176
	v_fmac_f32_e32 v224, v45, v177
	ds_read_b128 v[174:177], v219 offset:39584
	s_waitcnt lgkmcnt(11)
	v_fmac_f32_e32 v221, v46, v178
	ds_read_b128 v[178:181], v219 offset:39600
	v_add_f32_e32 v225, v222, v221
	v_add_f32_e32 v226, v223, v224
	v_add_f32_e32 v225, v226, v225
	v_fma_f32 v47, v111, v47, -v225
	v_cvt_pk_bf16_f32 v228, v47, v47
	global_store_short v220, v228, s[4:5] offset:3328
	s_waitcnt lgkmcnt(11)
	v_mul_f32_e32 v221, v2, v134
	v_mul_f32_e32 v222, v3, v135
	v_mul_f32_e32 v223, v4, v136
	v_mul_f32_e32 v224, v5, v137
	ds_read_b128 v[134:137], v219 offset:39680
	s_waitcnt lgkmcnt(11)
	v_fmac_f32_e32 v221, v6, v138
	v_fmac_f32_e32 v222, v7, v139
	v_fmac_f32_e32 v223, v8, v140
	v_fmac_f32_e32 v224, v9, v141
	ds_read_b128 v[138:141], v219 offset:39696
	s_waitcnt lgkmcnt(11)
	v_fmac_f32_e32 v221, v10, v142
	v_fmac_f32_e32 v222, v11, v143
	v_fmac_f32_e32 v223, v12, v144
	v_fmac_f32_e32 v224, v13, v145
	ds_read_b128 v[142:145], v219 offset:39712
	s_waitcnt lgkmcnt(11)
	v_fmac_f32_e32 v221, v14, v146
	v_fmac_f32_e32 v222, v15, v147
	v_fmac_f32_e32 v223, v16, v148
	v_fmac_f32_e32 v224, v17, v149
	ds_read_b128 v[146:149], v219 offset:39728
	s_waitcnt lgkmcnt(11)
	v_fmac_f32_e32 v221, v18, v150
	v_fmac_f32_e32 v222, v19, v151
	v_fmac_f32_e32 v223, v20, v152
	v_fmac_f32_e32 v224, v21, v153
	ds_read_b128 v[150:153], v219 offset:39744
	s_waitcnt lgkmcnt(11)
	v_fmac_f32_e32 v221, v22, v154
	v_fmac_f32_e32 v222, v23, v155
	v_fmac_f32_e32 v223, v24, v156
	v_fmac_f32_e32 v224, v25, v157
	ds_read_b128 v[154:157], v219 offset:39760
	s_waitcnt lgkmcnt(11)
	v_fmac_f32_e32 v221, v26, v158
	v_fmac_f32_e32 v222, v27, v159
	v_fmac_f32_e32 v223, v28, v160
	v_fmac_f32_e32 v224, v29, v161
	ds_read_b128 v[158:161], v219 offset:39776
	s_waitcnt lgkmcnt(11)
	v_fmac_f32_e32 v221, v30, v162
	v_fmac_f32_e32 v222, v31, v163
	v_fmac_f32_e32 v223, v32, v164
	v_fmac_f32_e32 v224, v33, v165
	ds_read_b128 v[162:165], v219 offset:39792
	s_waitcnt lgkmcnt(11)
	v_fmac_f32_e32 v221, v34, v166
	v_fmac_f32_e32 v222, v35, v167
	v_fmac_f32_e32 v223, v36, v168
	v_fmac_f32_e32 v224, v37, v169
	ds_read_b128 v[166:169], v219 offset:39808
	s_waitcnt lgkmcnt(11)
	v_fmac_f32_e32 v221, v38, v170
	v_fmac_f32_e32 v222, v39, v171
	v_fmac_f32_e32 v223, v40, v172
	v_fmac_f32_e32 v224, v41, v173
	ds_read_b128 v[170:173], v219 offset:39824
	s_waitcnt lgkmcnt(11)
	v_fmac_f32_e32 v221, v42, v174
	v_fmac_f32_e32 v222, v43, v175
	v_fmac_f32_e32 v223, v44, v176
	v_fmac_f32_e32 v224, v45, v177
	ds_read_b128 v[174:177], v219 offset:39840
	s_waitcnt lgkmcnt(11)
	v_fmac_f32_e32 v221, v46, v178
	v_fmac_f32_e32 v222, v47, v179
	ds_read_b128 v[178:181], v219 offset:39856
	v_add_f32_e32 v225, v222, v221
	v_add_f32_e32 v226, v223, v224
	v_add_f32_e32 v225, v226, v225
	v_fma_f32 v48, v112, v48, -v225
	v_cvt_pk_bf16_f32 v229, v48, v48
	global_store_short v220, v229, s[4:5] offset:3584
	s_waitcnt lgkmcnt(11)
	v_mul_f32_e32 v221, v2, v134
	v_mul_f32_e32 v222, v3, v135
	v_mul_f32_e32 v223, v4, v136
	v_mul_f32_e32 v224, v5, v137
	ds_read_b128 v[134:137], v219 offset:39936
	s_waitcnt lgkmcnt(11)
	v_fmac_f32_e32 v221, v6, v138
	v_fmac_f32_e32 v222, v7, v139
	v_fmac_f32_e32 v223, v8, v140
	v_fmac_f32_e32 v224, v9, v141
	ds_read_b128 v[138:141], v219 offset:39952
	s_waitcnt lgkmcnt(11)
	v_fmac_f32_e32 v221, v10, v142
	v_fmac_f32_e32 v222, v11, v143
	v_fmac_f32_e32 v223, v12, v144
	v_fmac_f32_e32 v224, v13, v145
	ds_read_b128 v[142:145], v219 offset:39968
	s_waitcnt lgkmcnt(11)
	v_fmac_f32_e32 v221, v14, v146
	v_fmac_f32_e32 v222, v15, v147
	v_fmac_f32_e32 v223, v16, v148
	v_fmac_f32_e32 v224, v17, v149
	ds_read_b128 v[146:149], v219 offset:39984
	s_waitcnt lgkmcnt(11)
	v_fmac_f32_e32 v221, v18, v150
	v_fmac_f32_e32 v222, v19, v151
	v_fmac_f32_e32 v223, v20, v152
	v_fmac_f32_e32 v224, v21, v153
	ds_read_b128 v[150:153], v219 offset:40000
	s_waitcnt lgkmcnt(11)
	v_fmac_f32_e32 v221, v22, v154
	v_fmac_f32_e32 v222, v23, v155
	v_fmac_f32_e32 v223, v24, v156
	v_fmac_f32_e32 v224, v25, v157
	ds_read_b128 v[154:157], v219 offset:40016
	s_waitcnt lgkmcnt(11)
	v_fmac_f32_e32 v221, v26, v158
	v_fmac_f32_e32 v222, v27, v159
	v_fmac_f32_e32 v223, v28, v160
	v_fmac_f32_e32 v224, v29, v161
	ds_read_b128 v[158:161], v219 offset:40032
	s_waitcnt lgkmcnt(11)
	v_fmac_f32_e32 v221, v30, v162
	v_fmac_f32_e32 v222, v31, v163
	v_fmac_f32_e32 v223, v32, v164
	v_fmac_f32_e32 v224, v33, v165
	ds_read_b128 v[162:165], v219 offset:40048
	s_waitcnt lgkmcnt(11)
	v_fmac_f32_e32 v221, v34, v166
	v_fmac_f32_e32 v222, v35, v167
	v_fmac_f32_e32 v223, v36, v168
	v_fmac_f32_e32 v224, v37, v169
	ds_read_b128 v[166:169], v219 offset:40064
	s_waitcnt lgkmcnt(11)
	v_fmac_f32_e32 v221, v38, v170
	v_fmac_f32_e32 v222, v39, v171
	v_fmac_f32_e32 v223, v40, v172
	v_fmac_f32_e32 v224, v41, v173
	ds_read_b128 v[170:173], v219 offset:40080
	s_waitcnt lgkmcnt(11)
	v_fmac_f32_e32 v221, v42, v174
	v_fmac_f32_e32 v222, v43, v175
	v_fmac_f32_e32 v223, v44, v176
	v_fmac_f32_e32 v224, v45, v177
	ds_read_b128 v[174:177], v219 offset:40096
	s_waitcnt lgkmcnt(11)
	v_fmac_f32_e32 v221, v46, v178
	v_fmac_f32_e32 v222, v47, v179
	v_fmac_f32_e32 v223, v48, v180
	ds_read_b128 v[178:181], v219 offset:40112
	v_add_f32_e32 v225, v222, v221
	v_add_f32_e32 v226, v223, v224
	v_add_f32_e32 v225, v226, v225
	v_fma_f32 v49, v113, v49, -v225
	v_cvt_pk_bf16_f32 v230, v49, v49
	global_store_short v220, v230, s[4:5] offset:3840
	s_waitcnt lgkmcnt(11)
	v_mul_f32_e32 v221, v2, v134
	v_mul_f32_e32 v222, v3, v135
	v_mul_f32_e32 v223, v4, v136
	v_mul_f32_e32 v224, v5, v137
	ds_read_b128 v[134:137], v219 offset:40192
	s_waitcnt lgkmcnt(11)
	v_fmac_f32_e32 v221, v6, v138
	v_fmac_f32_e32 v222, v7, v139
	v_fmac_f32_e32 v223, v8, v140
	v_fmac_f32_e32 v224, v9, v141
	ds_read_b128 v[138:141], v219 offset:40208
	s_waitcnt lgkmcnt(11)
	v_fmac_f32_e32 v221, v10, v142
	v_fmac_f32_e32 v222, v11, v143
	v_fmac_f32_e32 v223, v12, v144
	v_fmac_f32_e32 v224, v13, v145
	ds_read_b128 v[142:145], v219 offset:40224
	s_waitcnt lgkmcnt(11)
	v_fmac_f32_e32 v221, v14, v146
	v_fmac_f32_e32 v222, v15, v147
	v_fmac_f32_e32 v223, v16, v148
	v_fmac_f32_e32 v224, v17, v149
	ds_read_b128 v[146:149], v219 offset:40240
	s_waitcnt lgkmcnt(11)
	v_fmac_f32_e32 v221, v18, v150
	v_fmac_f32_e32 v222, v19, v151
	v_fmac_f32_e32 v223, v20, v152
	v_fmac_f32_e32 v224, v21, v153
	ds_read_b128 v[150:153], v219 offset:40256
	s_waitcnt lgkmcnt(11)
	v_fmac_f32_e32 v221, v22, v154
	v_fmac_f32_e32 v222, v23, v155
	v_fmac_f32_e32 v223, v24, v156
	v_fmac_f32_e32 v224, v25, v157
	ds_read_b128 v[154:157], v219 offset:40272
	s_waitcnt lgkmcnt(11)
	v_fmac_f32_e32 v221, v26, v158
	v_fmac_f32_e32 v222, v27, v159
	v_fmac_f32_e32 v223, v28, v160
	v_fmac_f32_e32 v224, v29, v161
	ds_read_b128 v[158:161], v219 offset:40288
	s_waitcnt lgkmcnt(11)
	v_fmac_f32_e32 v221, v30, v162
	v_fmac_f32_e32 v222, v31, v163
	v_fmac_f32_e32 v223, v32, v164
	v_fmac_f32_e32 v224, v33, v165
	ds_read_b128 v[162:165], v219 offset:40304
	s_waitcnt lgkmcnt(11)
	v_fmac_f32_e32 v221, v34, v166
	v_fmac_f32_e32 v222, v35, v167
	v_fmac_f32_e32 v223, v36, v168
	v_fmac_f32_e32 v224, v37, v169
	ds_read_b128 v[166:169], v219 offset:40320
	s_waitcnt lgkmcnt(11)
	v_fmac_f32_e32 v221, v38, v170
	v_fmac_f32_e32 v222, v39, v171
	v_fmac_f32_e32 v223, v40, v172
	v_fmac_f32_e32 v224, v41, v173
	ds_read_b128 v[170:173], v219 offset:40336
	s_waitcnt lgkmcnt(11)
	v_fmac_f32_e32 v221, v42, v174
	v_fmac_f32_e32 v222, v43, v175
	v_fmac_f32_e32 v223, v44, v176
	v_fmac_f32_e32 v224, v45, v177
	ds_read_b128 v[174:177], v219 offset:40352
	s_waitcnt lgkmcnt(11)
	v_fmac_f32_e32 v221, v46, v178
	v_fmac_f32_e32 v222, v47, v179
	v_fmac_f32_e32 v223, v48, v180
	v_fmac_f32_e32 v224, v49, v181
	ds_read_b128 v[178:181], v219 offset:40368
	v_add_f32_e32 v225, v222, v221
	v_add_f32_e32 v226, v223, v224
	v_add_f32_e32 v225, v226, v225
	v_fma_f32 v50, v114, v50, -v225
	v_add_u32_e32 v220, 0x1000, v220
	v_cvt_pk_bf16_f32 v227, v50, v50
	global_store_short v220, v227, s[4:5]
	s_waitcnt lgkmcnt(11)
	v_mul_f32_e32 v221, v2, v134
	v_mul_f32_e32 v222, v3, v135
	v_mul_f32_e32 v223, v4, v136
	v_mul_f32_e32 v224, v5, v137
	ds_read_b128 v[134:137], v219 offset:40384
	s_waitcnt lgkmcnt(11)
	v_fmac_f32_e32 v221, v6, v138
	v_fmac_f32_e32 v222, v7, v139
	v_fmac_f32_e32 v223, v8, v140
	v_fmac_f32_e32 v224, v9, v141
	ds_read_b128 v[138:141], v219 offset:40448
	s_waitcnt lgkmcnt(11)
	v_fmac_f32_e32 v221, v10, v142
	v_fmac_f32_e32 v222, v11, v143
	v_fmac_f32_e32 v223, v12, v144
	v_fmac_f32_e32 v224, v13, v145
	ds_read_b128 v[142:145], v219 offset:40464
	s_waitcnt lgkmcnt(11)
	v_fmac_f32_e32 v221, v14, v146
	v_fmac_f32_e32 v222, v15, v147
	v_fmac_f32_e32 v223, v16, v148
	v_fmac_f32_e32 v224, v17, v149
	ds_read_b128 v[146:149], v219 offset:40480
	s_waitcnt lgkmcnt(11)
	v_fmac_f32_e32 v221, v18, v150
	v_fmac_f32_e32 v222, v19, v151
	v_fmac_f32_e32 v223, v20, v152
	v_fmac_f32_e32 v224, v21, v153
	ds_read_b128 v[150:153], v219 offset:40496
	s_waitcnt lgkmcnt(11)
	v_fmac_f32_e32 v221, v22, v154
	v_fmac_f32_e32 v222, v23, v155
	v_fmac_f32_e32 v223, v24, v156
	v_fmac_f32_e32 v224, v25, v157
	ds_read_b128 v[154:157], v219 offset:40512
	s_waitcnt lgkmcnt(11)
	v_fmac_f32_e32 v221, v26, v158
	v_fmac_f32_e32 v222, v27, v159
	v_fmac_f32_e32 v223, v28, v160
	v_fmac_f32_e32 v224, v29, v161
	ds_read_b128 v[158:161], v219 offset:40528
	s_waitcnt lgkmcnt(11)
	v_fmac_f32_e32 v221, v30, v162
	v_fmac_f32_e32 v222, v31, v163
	v_fmac_f32_e32 v223, v32, v164
	v_fmac_f32_e32 v224, v33, v165
	ds_read_b128 v[162:165], v219 offset:40544
	s_waitcnt lgkmcnt(11)
	v_fmac_f32_e32 v221, v34, v166
	v_fmac_f32_e32 v222, v35, v167
	v_fmac_f32_e32 v223, v36, v168
	v_fmac_f32_e32 v224, v37, v169
	ds_read_b128 v[166:169], v219 offset:40560
	s_waitcnt lgkmcnt(11)
	v_fmac_f32_e32 v221, v38, v170
	v_fmac_f32_e32 v222, v39, v171
	v_fmac_f32_e32 v223, v40, v172
	v_fmac_f32_e32 v224, v41, v173
	ds_read_b128 v[170:173], v219 offset:40576
	s_waitcnt lgkmcnt(11)
	v_fmac_f32_e32 v221, v42, v174
	v_fmac_f32_e32 v222, v43, v175
	v_fmac_f32_e32 v223, v44, v176
	v_fmac_f32_e32 v224, v45, v177
	ds_read_b128 v[174:177], v219 offset:40592
	s_waitcnt lgkmcnt(11)
	v_fmac_f32_e32 v221, v46, v178
	v_fmac_f32_e32 v222, v47, v179
	v_fmac_f32_e32 v223, v48, v180
	v_fmac_f32_e32 v224, v49, v181
	ds_read_b128 v[178:181], v219 offset:40608
	s_waitcnt lgkmcnt(11)
	v_fmac_f32_e32 v221, v50, v134
	ds_read_b128 v[134:137], v219 offset:40624
	v_add_f32_e32 v225, v222, v221
	v_add_f32_e32 v226, v223, v224
	v_add_f32_e32 v225, v226, v225
	v_fma_f32 v51, v115, v51, -v225
	v_cvt_pk_bf16_f32 v228, v51, v51
	global_store_short v220, v228, s[4:5] offset:256
	s_waitcnt lgkmcnt(11)
	v_mul_f32_e32 v221, v2, v138
	v_mul_f32_e32 v222, v3, v139
	v_mul_f32_e32 v223, v4, v140
	v_mul_f32_e32 v224, v5, v141
	ds_read_b128 v[138:141], v219 offset:40640
	s_waitcnt lgkmcnt(11)
	v_fmac_f32_e32 v221, v6, v142
	v_fmac_f32_e32 v222, v7, v143
	v_fmac_f32_e32 v223, v8, v144
	v_fmac_f32_e32 v224, v9, v145
	ds_read_b128 v[142:145], v219 offset:40704
	s_waitcnt lgkmcnt(11)
	v_fmac_f32_e32 v221, v10, v146
	v_fmac_f32_e32 v222, v11, v147
	v_fmac_f32_e32 v223, v12, v148
	v_fmac_f32_e32 v224, v13, v149
	ds_read_b128 v[146:149], v219 offset:40720
	s_waitcnt lgkmcnt(11)
	v_fmac_f32_e32 v221, v14, v150
	v_fmac_f32_e32 v222, v15, v151
	v_fmac_f32_e32 v223, v16, v152
	v_fmac_f32_e32 v224, v17, v153
	ds_read_b128 v[150:153], v219 offset:40736
	s_waitcnt lgkmcnt(11)
	v_fmac_f32_e32 v221, v18, v154
	v_fmac_f32_e32 v222, v19, v155
	v_fmac_f32_e32 v223, v20, v156
	v_fmac_f32_e32 v224, v21, v157
	ds_read_b128 v[154:157], v219 offset:40752
	s_waitcnt lgkmcnt(11)
	v_fmac_f32_e32 v221, v22, v158
	v_fmac_f32_e32 v222, v23, v159
	v_fmac_f32_e32 v223, v24, v160
	v_fmac_f32_e32 v224, v25, v161
	ds_read_b128 v[158:161], v219 offset:40768
	s_waitcnt lgkmcnt(11)
	v_fmac_f32_e32 v221, v26, v162
	v_fmac_f32_e32 v222, v27, v163
	v_fmac_f32_e32 v223, v28, v164
	v_fmac_f32_e32 v224, v29, v165
	ds_read_b128 v[162:165], v219 offset:40784
	s_waitcnt lgkmcnt(11)
	v_fmac_f32_e32 v221, v30, v166
	v_fmac_f32_e32 v222, v31, v167
	v_fmac_f32_e32 v223, v32, v168
	v_fmac_f32_e32 v224, v33, v169
	ds_read_b128 v[166:169], v219 offset:40800
	s_waitcnt lgkmcnt(11)
	v_fmac_f32_e32 v221, v34, v170
	v_fmac_f32_e32 v222, v35, v171
	v_fmac_f32_e32 v223, v36, v172
	v_fmac_f32_e32 v224, v37, v173
	ds_read_b128 v[170:173], v219 offset:40816
	s_waitcnt lgkmcnt(11)
	v_fmac_f32_e32 v221, v38, v174
	v_fmac_f32_e32 v222, v39, v175
	v_fmac_f32_e32 v223, v40, v176
	v_fmac_f32_e32 v224, v41, v177
	ds_read_b128 v[174:177], v219 offset:40832
	s_waitcnt lgkmcnt(11)
	v_fmac_f32_e32 v221, v42, v178
	v_fmac_f32_e32 v222, v43, v179
	v_fmac_f32_e32 v223, v44, v180
	v_fmac_f32_e32 v224, v45, v181
	ds_read_b128 v[178:181], v219 offset:40848
	s_waitcnt lgkmcnt(11)
	v_fmac_f32_e32 v221, v46, v134
	v_fmac_f32_e32 v222, v47, v135
	v_fmac_f32_e32 v223, v48, v136
	v_fmac_f32_e32 v224, v49, v137
	ds_read_b128 v[134:137], v219 offset:40864
	s_waitcnt lgkmcnt(11)
	v_fmac_f32_e32 v221, v50, v138
	v_fmac_f32_e32 v222, v51, v139
	ds_read_b128 v[138:141], v219 offset:40880
	v_add_f32_e32 v225, v222, v221
	v_add_f32_e32 v226, v223, v224
	v_add_f32_e32 v225, v226, v225
	v_fma_f32 v52, v116, v52, -v225
	v_cvt_pk_bf16_f32 v229, v52, v52
	global_store_short v220, v229, s[4:5] offset:512
	s_waitcnt lgkmcnt(11)
	v_mul_f32_e32 v221, v2, v142
	v_mul_f32_e32 v222, v3, v143
	v_mul_f32_e32 v223, v4, v144
	v_mul_f32_e32 v224, v5, v145
	ds_read_b128 v[142:145], v219 offset:40896
	s_waitcnt lgkmcnt(11)
	v_fmac_f32_e32 v221, v6, v146
	v_fmac_f32_e32 v222, v7, v147
	v_fmac_f32_e32 v223, v8, v148
	v_fmac_f32_e32 v224, v9, v149
	ds_read_b128 v[146:149], v219 offset:40960
	s_waitcnt lgkmcnt(11)
	v_fmac_f32_e32 v221, v10, v150
	v_fmac_f32_e32 v222, v11, v151
	v_fmac_f32_e32 v223, v12, v152
	v_fmac_f32_e32 v224, v13, v153
	ds_read_b128 v[150:153], v219 offset:40976
	s_waitcnt lgkmcnt(11)
	v_fmac_f32_e32 v221, v14, v154
	v_fmac_f32_e32 v222, v15, v155
	v_fmac_f32_e32 v223, v16, v156
	v_fmac_f32_e32 v224, v17, v157
	ds_read_b128 v[154:157], v219 offset:40992
	s_waitcnt lgkmcnt(11)
	v_fmac_f32_e32 v221, v18, v158
	v_fmac_f32_e32 v222, v19, v159
	v_fmac_f32_e32 v223, v20, v160
	v_fmac_f32_e32 v224, v21, v161
	ds_read_b128 v[158:161], v219 offset:41008
	s_waitcnt lgkmcnt(11)
	v_fmac_f32_e32 v221, v22, v162
	v_fmac_f32_e32 v222, v23, v163
	v_fmac_f32_e32 v223, v24, v164
	v_fmac_f32_e32 v224, v25, v165
	ds_read_b128 v[162:165], v219 offset:41024
	s_waitcnt lgkmcnt(11)
	v_fmac_f32_e32 v221, v26, v166
	v_fmac_f32_e32 v222, v27, v167
	v_fmac_f32_e32 v223, v28, v168
	v_fmac_f32_e32 v224, v29, v169
	ds_read_b128 v[166:169], v219 offset:41040
	s_waitcnt lgkmcnt(11)
	v_fmac_f32_e32 v221, v30, v170
	v_fmac_f32_e32 v222, v31, v171
	v_fmac_f32_e32 v223, v32, v172
	v_fmac_f32_e32 v224, v33, v173
	ds_read_b128 v[170:173], v219 offset:41056
	s_waitcnt lgkmcnt(11)
	v_fmac_f32_e32 v221, v34, v174
	v_fmac_f32_e32 v222, v35, v175
	v_fmac_f32_e32 v223, v36, v176
	v_fmac_f32_e32 v224, v37, v177
	ds_read_b128 v[174:177], v219 offset:41072
	s_waitcnt lgkmcnt(11)
	v_fmac_f32_e32 v221, v38, v178
	v_fmac_f32_e32 v222, v39, v179
	v_fmac_f32_e32 v223, v40, v180
	v_fmac_f32_e32 v224, v41, v181
	ds_read_b128 v[178:181], v219 offset:41088
	s_waitcnt lgkmcnt(11)
	v_fmac_f32_e32 v221, v42, v134
	v_fmac_f32_e32 v222, v43, v135
	v_fmac_f32_e32 v223, v44, v136
	v_fmac_f32_e32 v224, v45, v137
	ds_read_b128 v[134:137], v219 offset:41104
	s_waitcnt lgkmcnt(11)
	v_fmac_f32_e32 v221, v46, v138
	v_fmac_f32_e32 v222, v47, v139
	v_fmac_f32_e32 v223, v48, v140
	v_fmac_f32_e32 v224, v49, v141
	ds_read_b128 v[138:141], v219 offset:41120
	s_waitcnt lgkmcnt(11)
	v_fmac_f32_e32 v221, v50, v142
	v_fmac_f32_e32 v222, v51, v143
	v_fmac_f32_e32 v223, v52, v144
	ds_read_b128 v[142:145], v219 offset:41136
	v_add_f32_e32 v225, v222, v221
	v_add_f32_e32 v226, v223, v224
	v_add_f32_e32 v225, v226, v225
	v_fma_f32 v53, v117, v53, -v225
	v_cvt_pk_bf16_f32 v230, v53, v53
	global_store_short v220, v230, s[4:5] offset:768
	s_waitcnt lgkmcnt(11)
	v_mul_f32_e32 v221, v2, v146
	v_mul_f32_e32 v222, v3, v147
	v_mul_f32_e32 v223, v4, v148
	v_mul_f32_e32 v224, v5, v149
	ds_read_b128 v[146:149], v219 offset:41152
	s_waitcnt lgkmcnt(11)
	v_fmac_f32_e32 v221, v6, v150
	v_fmac_f32_e32 v222, v7, v151
	v_fmac_f32_e32 v223, v8, v152
	v_fmac_f32_e32 v224, v9, v153
	ds_read_b128 v[150:153], v219 offset:41216
	s_waitcnt lgkmcnt(11)
	v_fmac_f32_e32 v221, v10, v154
	v_fmac_f32_e32 v222, v11, v155
	v_fmac_f32_e32 v223, v12, v156
	v_fmac_f32_e32 v224, v13, v157
	ds_read_b128 v[154:157], v219 offset:41232
	s_waitcnt lgkmcnt(11)
	v_fmac_f32_e32 v221, v14, v158
	v_fmac_f32_e32 v222, v15, v159
	v_fmac_f32_e32 v223, v16, v160
	v_fmac_f32_e32 v224, v17, v161
	ds_read_b128 v[158:161], v219 offset:41248
	s_waitcnt lgkmcnt(11)
	v_fmac_f32_e32 v221, v18, v162
	v_fmac_f32_e32 v222, v19, v163
	v_fmac_f32_e32 v223, v20, v164
	v_fmac_f32_e32 v224, v21, v165
	ds_read_b128 v[162:165], v219 offset:41264
	s_waitcnt lgkmcnt(11)
	v_fmac_f32_e32 v221, v22, v166
	v_fmac_f32_e32 v222, v23, v167
	v_fmac_f32_e32 v223, v24, v168
	v_fmac_f32_e32 v224, v25, v169
	ds_read_b128 v[166:169], v219 offset:41280
	s_waitcnt lgkmcnt(11)
	v_fmac_f32_e32 v221, v26, v170
	v_fmac_f32_e32 v222, v27, v171
	v_fmac_f32_e32 v223, v28, v172
	v_fmac_f32_e32 v224, v29, v173
	ds_read_b128 v[170:173], v219 offset:41296
	s_waitcnt lgkmcnt(11)
	v_fmac_f32_e32 v221, v30, v174
	v_fmac_f32_e32 v222, v31, v175
	v_fmac_f32_e32 v223, v32, v176
	v_fmac_f32_e32 v224, v33, v177
	ds_read_b128 v[174:177], v219 offset:41312
	s_waitcnt lgkmcnt(11)
	v_fmac_f32_e32 v221, v34, v178
	v_fmac_f32_e32 v222, v35, v179
	v_fmac_f32_e32 v223, v36, v180
	v_fmac_f32_e32 v224, v37, v181
	ds_read_b128 v[178:181], v219 offset:41328
	s_waitcnt lgkmcnt(11)
	v_fmac_f32_e32 v221, v38, v134
	v_fmac_f32_e32 v222, v39, v135
	v_fmac_f32_e32 v223, v40, v136
	v_fmac_f32_e32 v224, v41, v137
	ds_read_b128 v[134:137], v219 offset:41344
	s_waitcnt lgkmcnt(11)
	v_fmac_f32_e32 v221, v42, v138
	v_fmac_f32_e32 v222, v43, v139
	v_fmac_f32_e32 v223, v44, v140
	v_fmac_f32_e32 v224, v45, v141
	ds_read_b128 v[138:141], v219 offset:41360
	s_waitcnt lgkmcnt(11)
	v_fmac_f32_e32 v221, v46, v142
	v_fmac_f32_e32 v222, v47, v143
	v_fmac_f32_e32 v223, v48, v144
	v_fmac_f32_e32 v224, v49, v145
	ds_read_b128 v[142:145], v219 offset:41376
	s_waitcnt lgkmcnt(11)
	v_fmac_f32_e32 v221, v50, v146
	v_fmac_f32_e32 v222, v51, v147
	v_fmac_f32_e32 v223, v52, v148
	v_fmac_f32_e32 v224, v53, v149
	ds_read_b128 v[146:149], v219 offset:41392
	v_add_f32_e32 v225, v222, v221
	v_add_f32_e32 v226, v223, v224
	v_add_f32_e32 v225, v226, v225
	v_fma_f32 v54, v118, v54, -v225
	v_cvt_pk_bf16_f32 v227, v54, v54
	global_store_short v220, v227, s[4:5] offset:1024
	s_waitcnt lgkmcnt(11)
	v_mul_f32_e32 v221, v2, v150
	v_mul_f32_e32 v222, v3, v151
	v_mul_f32_e32 v223, v4, v152
	v_mul_f32_e32 v224, v5, v153
	ds_read_b128 v[150:153], v219 offset:41408
	s_waitcnt lgkmcnt(11)
	v_fmac_f32_e32 v221, v6, v154
	v_fmac_f32_e32 v222, v7, v155
	v_fmac_f32_e32 v223, v8, v156
	v_fmac_f32_e32 v224, v9, v157
	ds_read_b128 v[154:157], v219 offset:41424
	s_waitcnt lgkmcnt(11)
	v_fmac_f32_e32 v221, v10, v158
	v_fmac_f32_e32 v222, v11, v159
	v_fmac_f32_e32 v223, v12, v160
	v_fmac_f32_e32 v224, v13, v161
	ds_read_b128 v[158:161], v219 offset:41472
	s_waitcnt lgkmcnt(11)
	v_fmac_f32_e32 v221, v14, v162
	v_fmac_f32_e32 v222, v15, v163
	v_fmac_f32_e32 v223, v16, v164
	v_fmac_f32_e32 v224, v17, v165
	ds_read_b128 v[162:165], v219 offset:41488
	s_waitcnt lgkmcnt(11)
	v_fmac_f32_e32 v221, v18, v166
	v_fmac_f32_e32 v222, v19, v167
	v_fmac_f32_e32 v223, v20, v168
	v_fmac_f32_e32 v224, v21, v169
	ds_read_b128 v[166:169], v219 offset:41504
	s_waitcnt lgkmcnt(11)
	v_fmac_f32_e32 v221, v22, v170
	v_fmac_f32_e32 v222, v23, v171
	v_fmac_f32_e32 v223, v24, v172
	v_fmac_f32_e32 v224, v25, v173
	ds_read_b128 v[170:173], v219 offset:41520
	s_waitcnt lgkmcnt(11)
	v_fmac_f32_e32 v221, v26, v174
	v_fmac_f32_e32 v222, v27, v175
	v_fmac_f32_e32 v223, v28, v176
	v_fmac_f32_e32 v224, v29, v177
	ds_read_b128 v[174:177], v219 offset:41536
	s_waitcnt lgkmcnt(11)
	v_fmac_f32_e32 v221, v30, v178
	v_fmac_f32_e32 v222, v31, v179
	v_fmac_f32_e32 v223, v32, v180
	v_fmac_f32_e32 v224, v33, v181
	ds_read_b128 v[178:181], v219 offset:41552
	s_waitcnt lgkmcnt(11)
	v_fmac_f32_e32 v221, v34, v134
	v_fmac_f32_e32 v222, v35, v135
	v_fmac_f32_e32 v223, v36, v136
	v_fmac_f32_e32 v224, v37, v137
	ds_read_b128 v[134:137], v219 offset:41568
	s_waitcnt lgkmcnt(11)
	v_fmac_f32_e32 v221, v38, v138
	v_fmac_f32_e32 v222, v39, v139
	v_fmac_f32_e32 v223, v40, v140
	v_fmac_f32_e32 v224, v41, v141
	ds_read_b128 v[138:141], v219 offset:41584
	s_waitcnt lgkmcnt(11)
	v_fmac_f32_e32 v221, v42, v142
	v_fmac_f32_e32 v222, v43, v143
	v_fmac_f32_e32 v223, v44, v144
	v_fmac_f32_e32 v224, v45, v145
	ds_read_b128 v[142:145], v219 offset:41600
	s_waitcnt lgkmcnt(11)
	v_fmac_f32_e32 v221, v46, v146
	v_fmac_f32_e32 v222, v47, v147
	v_fmac_f32_e32 v223, v48, v148
	v_fmac_f32_e32 v224, v49, v149
	ds_read_b128 v[146:149], v219 offset:41616
	s_waitcnt lgkmcnt(11)
	v_fmac_f32_e32 v221, v50, v150
	v_fmac_f32_e32 v222, v51, v151
	v_fmac_f32_e32 v223, v52, v152
	v_fmac_f32_e32 v224, v53, v153
	ds_read_b128 v[150:153], v219 offset:41632
	s_waitcnt lgkmcnt(11)
	v_fmac_f32_e32 v221, v54, v154
	ds_read_b128 v[154:157], v219 offset:41648
	v_add_f32_e32 v225, v222, v221
	v_add_f32_e32 v226, v223, v224
	v_add_f32_e32 v225, v226, v225
	v_fma_f32 v55, v119, v55, -v225
	v_cvt_pk_bf16_f32 v228, v55, v55
	global_store_short v220, v228, s[4:5] offset:1280
	s_waitcnt lgkmcnt(11)
	v_mul_f32_e32 v221, v2, v158
	v_mul_f32_e32 v222, v3, v159
	v_mul_f32_e32 v223, v4, v160
	v_mul_f32_e32 v224, v5, v161
	ds_read_b128 v[158:161], v219 offset:41664
	s_waitcnt lgkmcnt(11)
	v_fmac_f32_e32 v221, v6, v162
	v_fmac_f32_e32 v222, v7, v163
	v_fmac_f32_e32 v223, v8, v164
	v_fmac_f32_e32 v224, v9, v165
	ds_read_b128 v[162:165], v219 offset:41680
	s_waitcnt lgkmcnt(11)
	v_fmac_f32_e32 v221, v10, v166
	v_fmac_f32_e32 v222, v11, v167
	v_fmac_f32_e32 v223, v12, v168
	v_fmac_f32_e32 v224, v13, v169
	ds_read_b128 v[166:169], v219 offset:41728
	s_waitcnt lgkmcnt(11)
	v_fmac_f32_e32 v221, v14, v170
	v_fmac_f32_e32 v222, v15, v171
	v_fmac_f32_e32 v223, v16, v172
	v_fmac_f32_e32 v224, v17, v173
	ds_read_b128 v[170:173], v219 offset:41744
	s_waitcnt lgkmcnt(11)
	v_fmac_f32_e32 v221, v18, v174
	v_fmac_f32_e32 v222, v19, v175
	v_fmac_f32_e32 v223, v20, v176
	v_fmac_f32_e32 v224, v21, v177
	ds_read_b128 v[174:177], v219 offset:41760
	s_waitcnt lgkmcnt(11)
	v_fmac_f32_e32 v221, v22, v178
	v_fmac_f32_e32 v222, v23, v179
	v_fmac_f32_e32 v223, v24, v180
	v_fmac_f32_e32 v224, v25, v181
	ds_read_b128 v[178:181], v219 offset:41776
	s_waitcnt lgkmcnt(11)
	v_fmac_f32_e32 v221, v26, v134
	v_fmac_f32_e32 v222, v27, v135
	v_fmac_f32_e32 v223, v28, v136
	v_fmac_f32_e32 v224, v29, v137
	ds_read_b128 v[134:137], v219 offset:41792
	s_waitcnt lgkmcnt(11)
	v_fmac_f32_e32 v221, v30, v138
	v_fmac_f32_e32 v222, v31, v139
	v_fmac_f32_e32 v223, v32, v140
	v_fmac_f32_e32 v224, v33, v141
	ds_read_b128 v[138:141], v219 offset:41808
	s_waitcnt lgkmcnt(11)
	v_fmac_f32_e32 v221, v34, v142
	v_fmac_f32_e32 v222, v35, v143
	v_fmac_f32_e32 v223, v36, v144
	v_fmac_f32_e32 v224, v37, v145
	ds_read_b128 v[142:145], v219 offset:41824
	s_waitcnt lgkmcnt(11)
	v_fmac_f32_e32 v221, v38, v146
	v_fmac_f32_e32 v222, v39, v147
	v_fmac_f32_e32 v223, v40, v148
	v_fmac_f32_e32 v224, v41, v149
	ds_read_b128 v[146:149], v219 offset:41840
	s_waitcnt lgkmcnt(11)
	v_fmac_f32_e32 v221, v42, v150
	v_fmac_f32_e32 v222, v43, v151
	v_fmac_f32_e32 v223, v44, v152
	v_fmac_f32_e32 v224, v45, v153
	ds_read_b128 v[150:153], v219 offset:41856
	s_waitcnt lgkmcnt(11)
	v_fmac_f32_e32 v221, v46, v154
	v_fmac_f32_e32 v222, v47, v155
	v_fmac_f32_e32 v223, v48, v156
	v_fmac_f32_e32 v224, v49, v157
	ds_read_b128 v[154:157], v219 offset:41872
	s_waitcnt lgkmcnt(11)
	v_fmac_f32_e32 v221, v50, v158
	v_fmac_f32_e32 v222, v51, v159
	v_fmac_f32_e32 v223, v52, v160
	v_fmac_f32_e32 v224, v53, v161
	ds_read_b128 v[158:161], v219 offset:41888
	s_waitcnt lgkmcnt(11)
	v_fmac_f32_e32 v221, v54, v162
	v_fmac_f32_e32 v222, v55, v163
	ds_read_b128 v[162:165], v219 offset:41904
	v_add_f32_e32 v225, v222, v221
	v_add_f32_e32 v226, v223, v224
	v_add_f32_e32 v225, v226, v225
	v_fma_f32 v56, v120, v56, -v225
	v_cvt_pk_bf16_f32 v229, v56, v56
	global_store_short v220, v229, s[4:5] offset:1536
	s_waitcnt lgkmcnt(11)
	v_mul_f32_e32 v221, v2, v166
	v_mul_f32_e32 v222, v3, v167
	v_mul_f32_e32 v223, v4, v168
	v_mul_f32_e32 v224, v5, v169
	ds_read_b128 v[166:169], v219 offset:41920
	s_waitcnt lgkmcnt(11)
	v_fmac_f32_e32 v221, v6, v170
	v_fmac_f32_e32 v222, v7, v171
	v_fmac_f32_e32 v223, v8, v172
	v_fmac_f32_e32 v224, v9, v173
	ds_read_b128 v[170:173], v219 offset:41936
	s_waitcnt lgkmcnt(11)
	v_fmac_f32_e32 v221, v10, v174
	v_fmac_f32_e32 v222, v11, v175
	v_fmac_f32_e32 v223, v12, v176
	v_fmac_f32_e32 v224, v13, v177
	ds_read_b128 v[174:177], v219 offset:41984
	s_waitcnt lgkmcnt(11)
	v_fmac_f32_e32 v221, v14, v178
	v_fmac_f32_e32 v222, v15, v179
	v_fmac_f32_e32 v223, v16, v180
	v_fmac_f32_e32 v224, v17, v181
	ds_read_b128 v[178:181], v219 offset:42000
	s_waitcnt lgkmcnt(11)
	v_fmac_f32_e32 v221, v18, v134
	v_fmac_f32_e32 v222, v19, v135
	v_fmac_f32_e32 v223, v20, v136
	v_fmac_f32_e32 v224, v21, v137
	ds_read_b128 v[134:137], v219 offset:42016
	s_waitcnt lgkmcnt(11)
	v_fmac_f32_e32 v221, v22, v138
	v_fmac_f32_e32 v222, v23, v139
	v_fmac_f32_e32 v223, v24, v140
	v_fmac_f32_e32 v224, v25, v141
	ds_read_b128 v[138:141], v219 offset:42032
	s_waitcnt lgkmcnt(11)
	v_fmac_f32_e32 v221, v26, v142
	v_fmac_f32_e32 v222, v27, v143
	v_fmac_f32_e32 v223, v28, v144
	v_fmac_f32_e32 v224, v29, v145
	ds_read_b128 v[142:145], v219 offset:42048
	s_waitcnt lgkmcnt(11)
	v_fmac_f32_e32 v221, v30, v146
	v_fmac_f32_e32 v222, v31, v147
	v_fmac_f32_e32 v223, v32, v148
	v_fmac_f32_e32 v224, v33, v149
	ds_read_b128 v[146:149], v219 offset:42064
	s_waitcnt lgkmcnt(11)
	v_fmac_f32_e32 v221, v34, v150
	v_fmac_f32_e32 v222, v35, v151
	v_fmac_f32_e32 v223, v36, v152
	v_fmac_f32_e32 v224, v37, v153
	ds_read_b128 v[150:153], v219 offset:42080
	s_waitcnt lgkmcnt(11)
	v_fmac_f32_e32 v221, v38, v154
	v_fmac_f32_e32 v222, v39, v155
	v_fmac_f32_e32 v223, v40, v156
	v_fmac_f32_e32 v224, v41, v157
	ds_read_b128 v[154:157], v219 offset:42096
	s_waitcnt lgkmcnt(11)
	v_fmac_f32_e32 v221, v42, v158
	v_fmac_f32_e32 v222, v43, v159
	v_fmac_f32_e32 v223, v44, v160
	v_fmac_f32_e32 v224, v45, v161
	ds_read_b128 v[158:161], v219 offset:42112
	s_waitcnt lgkmcnt(11)
	v_fmac_f32_e32 v221, v46, v162
	v_fmac_f32_e32 v222, v47, v163
	v_fmac_f32_e32 v223, v48, v164
	v_fmac_f32_e32 v224, v49, v165
	ds_read_b128 v[162:165], v219 offset:42128
	s_waitcnt lgkmcnt(11)
	v_fmac_f32_e32 v221, v50, v166
	v_fmac_f32_e32 v222, v51, v167
	v_fmac_f32_e32 v223, v52, v168
	v_fmac_f32_e32 v224, v53, v169
	ds_read_b128 v[166:169], v219 offset:42144
	s_waitcnt lgkmcnt(11)
	v_fmac_f32_e32 v221, v54, v170
	v_fmac_f32_e32 v222, v55, v171
	v_fmac_f32_e32 v223, v56, v172
	ds_read_b128 v[170:173], v219 offset:42160
	v_add_f32_e32 v225, v222, v221
	v_add_f32_e32 v226, v223, v224
	v_add_f32_e32 v225, v226, v225
	v_fma_f32 v57, v121, v57, -v225
	v_cvt_pk_bf16_f32 v230, v57, v57
	global_store_short v220, v230, s[4:5] offset:1792
	s_waitcnt lgkmcnt(11)
	v_mul_f32_e32 v221, v2, v174
	v_mul_f32_e32 v222, v3, v175
	v_mul_f32_e32 v223, v4, v176
	v_mul_f32_e32 v224, v5, v177
	ds_read_b128 v[174:177], v219 offset:42176
	s_waitcnt lgkmcnt(11)
	v_fmac_f32_e32 v221, v6, v178
	v_fmac_f32_e32 v222, v7, v179
	v_fmac_f32_e32 v223, v8, v180
	v_fmac_f32_e32 v224, v9, v181
	ds_read_b128 v[178:181], v219 offset:42192
	s_waitcnt lgkmcnt(11)
	v_fmac_f32_e32 v221, v10, v134
	v_fmac_f32_e32 v222, v11, v135
	v_fmac_f32_e32 v223, v12, v136
	v_fmac_f32_e32 v224, v13, v137
	ds_read_b128 v[134:137], v219 offset:42240
	s_waitcnt lgkmcnt(11)
	v_fmac_f32_e32 v221, v14, v138
	v_fmac_f32_e32 v222, v15, v139
	v_fmac_f32_e32 v223, v16, v140
	v_fmac_f32_e32 v224, v17, v141
	ds_read_b128 v[138:141], v219 offset:42256
	s_waitcnt lgkmcnt(11)
	v_fmac_f32_e32 v221, v18, v142
	v_fmac_f32_e32 v222, v19, v143
	v_fmac_f32_e32 v223, v20, v144
	v_fmac_f32_e32 v224, v21, v145
	ds_read_b128 v[142:145], v219 offset:42272
	s_waitcnt lgkmcnt(11)
	v_fmac_f32_e32 v221, v22, v146
	v_fmac_f32_e32 v222, v23, v147
	v_fmac_f32_e32 v223, v24, v148
	v_fmac_f32_e32 v224, v25, v149
	ds_read_b128 v[146:149], v219 offset:42288
	s_waitcnt lgkmcnt(11)
	v_fmac_f32_e32 v221, v26, v150
	v_fmac_f32_e32 v222, v27, v151
	v_fmac_f32_e32 v223, v28, v152
	v_fmac_f32_e32 v224, v29, v153
	ds_read_b128 v[150:153], v219 offset:42304
	s_waitcnt lgkmcnt(11)
	v_fmac_f32_e32 v221, v30, v154
	v_fmac_f32_e32 v222, v31, v155
	v_fmac_f32_e32 v223, v32, v156
	v_fmac_f32_e32 v224, v33, v157
	ds_read_b128 v[154:157], v219 offset:42320
	s_waitcnt lgkmcnt(11)
	v_fmac_f32_e32 v221, v34, v158
	v_fmac_f32_e32 v222, v35, v159
	v_fmac_f32_e32 v223, v36, v160
	v_fmac_f32_e32 v224, v37, v161
	ds_read_b128 v[158:161], v219 offset:42336
	s_waitcnt lgkmcnt(11)
	v_fmac_f32_e32 v221, v38, v162
	v_fmac_f32_e32 v222, v39, v163
	v_fmac_f32_e32 v223, v40, v164
	v_fmac_f32_e32 v224, v41, v165
	ds_read_b128 v[162:165], v219 offset:42352
	s_waitcnt lgkmcnt(11)
	v_fmac_f32_e32 v221, v42, v166
	v_fmac_f32_e32 v222, v43, v167
	v_fmac_f32_e32 v223, v44, v168
	v_fmac_f32_e32 v224, v45, v169
	ds_read_b128 v[166:169], v219 offset:42368
	s_waitcnt lgkmcnt(11)
	v_fmac_f32_e32 v221, v46, v170
	v_fmac_f32_e32 v222, v47, v171
	v_fmac_f32_e32 v223, v48, v172
	v_fmac_f32_e32 v224, v49, v173
	ds_read_b128 v[170:173], v219 offset:42384
	s_waitcnt lgkmcnt(11)
	v_fmac_f32_e32 v221, v50, v174
	v_fmac_f32_e32 v222, v51, v175
	v_fmac_f32_e32 v223, v52, v176
	v_fmac_f32_e32 v224, v53, v177
	ds_read_b128 v[174:177], v219 offset:42400
	s_waitcnt lgkmcnt(11)
	v_fmac_f32_e32 v221, v54, v178
	v_fmac_f32_e32 v222, v55, v179
	v_fmac_f32_e32 v223, v56, v180
	v_fmac_f32_e32 v224, v57, v181
	ds_read_b128 v[178:181], v219 offset:42416
	v_add_f32_e32 v225, v222, v221
	v_add_f32_e32 v226, v223, v224
	v_add_f32_e32 v225, v226, v225
	v_fma_f32 v58, v122, v58, -v225
	v_cvt_pk_bf16_f32 v227, v58, v58
	global_store_short v220, v227, s[4:5] offset:2048
	s_waitcnt lgkmcnt(11)
	v_mul_f32_e32 v221, v2, v134
	v_mul_f32_e32 v222, v3, v135
	v_mul_f32_e32 v223, v4, v136
	v_mul_f32_e32 v224, v5, v137
	ds_read_b128 v[134:137], v219 offset:42432
	s_waitcnt lgkmcnt(11)
	v_fmac_f32_e32 v221, v6, v138
	v_fmac_f32_e32 v222, v7, v139
	v_fmac_f32_e32 v223, v8, v140
	v_fmac_f32_e32 v224, v9, v141
	ds_read_b128 v[138:141], v219 offset:42448
	s_waitcnt lgkmcnt(11)
	v_fmac_f32_e32 v221, v10, v142
	v_fmac_f32_e32 v222, v11, v143
	v_fmac_f32_e32 v223, v12, v144
	v_fmac_f32_e32 v224, v13, v145
	ds_read_b128 v[142:145], v219 offset:42464
	s_waitcnt lgkmcnt(11)
	v_fmac_f32_e32 v221, v14, v146
	v_fmac_f32_e32 v222, v15, v147
	v_fmac_f32_e32 v223, v16, v148
	v_fmac_f32_e32 v224, v17, v149
	ds_read_b128 v[146:149], v219 offset:42496
	s_waitcnt lgkmcnt(11)
	v_fmac_f32_e32 v221, v18, v150
	v_fmac_f32_e32 v222, v19, v151
	v_fmac_f32_e32 v223, v20, v152
	v_fmac_f32_e32 v224, v21, v153
	ds_read_b128 v[150:153], v219 offset:42512
	s_waitcnt lgkmcnt(11)
	v_fmac_f32_e32 v221, v22, v154
	v_fmac_f32_e32 v222, v23, v155
	v_fmac_f32_e32 v223, v24, v156
	v_fmac_f32_e32 v224, v25, v157
	ds_read_b128 v[154:157], v219 offset:42528
	s_waitcnt lgkmcnt(11)
	v_fmac_f32_e32 v221, v26, v158
	v_fmac_f32_e32 v222, v27, v159
	v_fmac_f32_e32 v223, v28, v160
	v_fmac_f32_e32 v224, v29, v161
	ds_read_b128 v[158:161], v219 offset:42544
	s_waitcnt lgkmcnt(11)
	v_fmac_f32_e32 v221, v30, v162
	v_fmac_f32_e32 v222, v31, v163
	v_fmac_f32_e32 v223, v32, v164
	v_fmac_f32_e32 v224, v33, v165
	ds_read_b128 v[162:165], v219 offset:42560
	s_waitcnt lgkmcnt(11)
	v_fmac_f32_e32 v221, v34, v166
	v_fmac_f32_e32 v222, v35, v167
	v_fmac_f32_e32 v223, v36, v168
	v_fmac_f32_e32 v224, v37, v169
	ds_read_b128 v[166:169], v219 offset:42576
	s_waitcnt lgkmcnt(11)
	v_fmac_f32_e32 v221, v38, v170
	v_fmac_f32_e32 v222, v39, v171
	v_fmac_f32_e32 v223, v40, v172
	v_fmac_f32_e32 v224, v41, v173
	ds_read_b128 v[170:173], v219 offset:42592
	s_waitcnt lgkmcnt(11)
	v_fmac_f32_e32 v221, v42, v174
	v_fmac_f32_e32 v222, v43, v175
	v_fmac_f32_e32 v223, v44, v176
	v_fmac_f32_e32 v224, v45, v177
	ds_read_b128 v[174:177], v219 offset:42608
	s_waitcnt lgkmcnt(11)
	v_fmac_f32_e32 v221, v46, v178
	v_fmac_f32_e32 v222, v47, v179
	v_fmac_f32_e32 v223, v48, v180
	v_fmac_f32_e32 v224, v49, v181
	ds_read_b128 v[178:181], v219 offset:42624
	s_waitcnt lgkmcnt(11)
	v_fmac_f32_e32 v221, v50, v134
	v_fmac_f32_e32 v222, v51, v135
	v_fmac_f32_e32 v223, v52, v136
	v_fmac_f32_e32 v224, v53, v137
	ds_read_b128 v[134:137], v219 offset:42640
	s_waitcnt lgkmcnt(11)
	v_fmac_f32_e32 v221, v54, v138
	v_fmac_f32_e32 v222, v55, v139
	v_fmac_f32_e32 v223, v56, v140
	v_fmac_f32_e32 v224, v57, v141
	ds_read_b128 v[138:141], v219 offset:42656
	s_waitcnt lgkmcnt(11)
	v_fmac_f32_e32 v221, v58, v142
	ds_read_b128 v[142:145], v219 offset:42672
	v_add_f32_e32 v225, v222, v221
	v_add_f32_e32 v226, v223, v224
	v_add_f32_e32 v225, v226, v225
	v_fma_f32 v59, v123, v59, -v225
	v_cvt_pk_bf16_f32 v228, v59, v59
	global_store_short v220, v228, s[4:5] offset:2304
	s_waitcnt lgkmcnt(11)
	v_mul_f32_e32 v221, v2, v146
	v_mul_f32_e32 v222, v3, v147
	v_mul_f32_e32 v223, v4, v148
	v_mul_f32_e32 v224, v5, v149
	ds_read_b128 v[146:149], v219 offset:42688
	s_waitcnt lgkmcnt(11)
	v_fmac_f32_e32 v221, v6, v150
	v_fmac_f32_e32 v222, v7, v151
	v_fmac_f32_e32 v223, v8, v152
	v_fmac_f32_e32 v224, v9, v153
	ds_read_b128 v[150:153], v219 offset:42704
	s_waitcnt lgkmcnt(11)
	v_fmac_f32_e32 v221, v10, v154
	v_fmac_f32_e32 v222, v11, v155
	v_fmac_f32_e32 v223, v12, v156
	v_fmac_f32_e32 v224, v13, v157
	ds_read_b128 v[154:157], v219 offset:42720
	s_waitcnt lgkmcnt(11)
	v_fmac_f32_e32 v221, v14, v158
	v_fmac_f32_e32 v222, v15, v159
	v_fmac_f32_e32 v223, v16, v160
	v_fmac_f32_e32 v224, v17, v161
	ds_read_b128 v[158:161], v219 offset:42752
	s_waitcnt lgkmcnt(11)
	v_fmac_f32_e32 v221, v18, v162
	v_fmac_f32_e32 v222, v19, v163
	v_fmac_f32_e32 v223, v20, v164
	v_fmac_f32_e32 v224, v21, v165
	ds_read_b128 v[162:165], v219 offset:42768
	s_waitcnt lgkmcnt(11)
	v_fmac_f32_e32 v221, v22, v166
	v_fmac_f32_e32 v222, v23, v167
	v_fmac_f32_e32 v223, v24, v168
	v_fmac_f32_e32 v224, v25, v169
	ds_read_b128 v[166:169], v219 offset:42784
	s_waitcnt lgkmcnt(11)
	v_fmac_f32_e32 v221, v26, v170
	v_fmac_f32_e32 v222, v27, v171
	v_fmac_f32_e32 v223, v28, v172
	v_fmac_f32_e32 v224, v29, v173
	ds_read_b128 v[170:173], v219 offset:42800
	s_waitcnt lgkmcnt(11)
	v_fmac_f32_e32 v221, v30, v174
	v_fmac_f32_e32 v222, v31, v175
	v_fmac_f32_e32 v223, v32, v176
	v_fmac_f32_e32 v224, v33, v177
	ds_read_b128 v[174:177], v219 offset:42816
	s_waitcnt lgkmcnt(11)
	v_fmac_f32_e32 v221, v34, v178
	v_fmac_f32_e32 v222, v35, v179
	v_fmac_f32_e32 v223, v36, v180
	v_fmac_f32_e32 v224, v37, v181
	ds_read_b128 v[178:181], v219 offset:42832
	s_waitcnt lgkmcnt(11)
	v_fmac_f32_e32 v221, v38, v134
	v_fmac_f32_e32 v222, v39, v135
	v_fmac_f32_e32 v223, v40, v136
	v_fmac_f32_e32 v224, v41, v137
	ds_read_b128 v[134:137], v219 offset:42848
	s_waitcnt lgkmcnt(11)
	v_fmac_f32_e32 v221, v42, v138
	v_fmac_f32_e32 v222, v43, v139
	v_fmac_f32_e32 v223, v44, v140
	v_fmac_f32_e32 v224, v45, v141
	ds_read_b128 v[138:141], v219 offset:42864
	s_waitcnt lgkmcnt(11)
	v_fmac_f32_e32 v221, v46, v142
	v_fmac_f32_e32 v222, v47, v143
	v_fmac_f32_e32 v223, v48, v144
	v_fmac_f32_e32 v224, v49, v145
	ds_read_b128 v[142:145], v219 offset:42880
	s_waitcnt lgkmcnt(11)
	v_fmac_f32_e32 v221, v50, v146
	v_fmac_f32_e32 v222, v51, v147
	v_fmac_f32_e32 v223, v52, v148
	v_fmac_f32_e32 v224, v53, v149
	ds_read_b128 v[146:149], v219 offset:42896
	s_waitcnt lgkmcnt(11)
	v_fmac_f32_e32 v221, v54, v150
	v_fmac_f32_e32 v222, v55, v151
	v_fmac_f32_e32 v223, v56, v152
	v_fmac_f32_e32 v224, v57, v153
	ds_read_b128 v[150:153], v219 offset:42912
	s_waitcnt lgkmcnt(11)
	v_fmac_f32_e32 v221, v58, v154
	v_fmac_f32_e32 v222, v59, v155
	ds_read_b128 v[154:157], v219 offset:42928
	v_add_f32_e32 v225, v222, v221
	v_add_f32_e32 v226, v223, v224
	v_add_f32_e32 v225, v226, v225
	v_fma_f32 v60, v124, v60, -v225
	v_cvt_pk_bf16_f32 v229, v60, v60
	global_store_short v220, v229, s[4:5] offset:2560
	s_waitcnt lgkmcnt(11)
	v_mul_f32_e32 v221, v2, v158
	v_mul_f32_e32 v222, v3, v159
	v_mul_f32_e32 v223, v4, v160
	v_mul_f32_e32 v224, v5, v161
	ds_read_b128 v[158:161], v219 offset:42944
	s_waitcnt lgkmcnt(11)
	v_fmac_f32_e32 v221, v6, v162
	v_fmac_f32_e32 v222, v7, v163
	v_fmac_f32_e32 v223, v8, v164
	v_fmac_f32_e32 v224, v9, v165
	ds_read_b128 v[162:165], v219 offset:42960
	s_waitcnt lgkmcnt(11)
	v_fmac_f32_e32 v221, v10, v166
	v_fmac_f32_e32 v222, v11, v167
	v_fmac_f32_e32 v223, v12, v168
	v_fmac_f32_e32 v224, v13, v169
	ds_read_b128 v[166:169], v219 offset:42976
	s_waitcnt lgkmcnt(11)
	v_fmac_f32_e32 v221, v14, v170
	v_fmac_f32_e32 v222, v15, v171
	v_fmac_f32_e32 v223, v16, v172
	v_fmac_f32_e32 v224, v17, v173
	ds_read_b128 v[170:173], v219 offset:43008
	s_waitcnt lgkmcnt(11)
	v_fmac_f32_e32 v221, v18, v174
	v_fmac_f32_e32 v222, v19, v175
	v_fmac_f32_e32 v223, v20, v176
	v_fmac_f32_e32 v224, v21, v177
	ds_read_b128 v[174:177], v219 offset:43024
	s_waitcnt lgkmcnt(11)
	v_fmac_f32_e32 v221, v22, v178
	v_fmac_f32_e32 v222, v23, v179
	v_fmac_f32_e32 v223, v24, v180
	v_fmac_f32_e32 v224, v25, v181
	ds_read_b128 v[178:181], v219 offset:43040
	s_waitcnt lgkmcnt(11)
	v_fmac_f32_e32 v221, v26, v134
	v_fmac_f32_e32 v222, v27, v135
	v_fmac_f32_e32 v223, v28, v136
	v_fmac_f32_e32 v224, v29, v137
	ds_read_b128 v[134:137], v219 offset:43056
	s_waitcnt lgkmcnt(11)
	v_fmac_f32_e32 v221, v30, v138
	v_fmac_f32_e32 v222, v31, v139
	v_fmac_f32_e32 v223, v32, v140
	v_fmac_f32_e32 v224, v33, v141
	ds_read_b128 v[138:141], v219 offset:43072
	s_waitcnt lgkmcnt(11)
	v_fmac_f32_e32 v221, v34, v142
	v_fmac_f32_e32 v222, v35, v143
	v_fmac_f32_e32 v223, v36, v144
	v_fmac_f32_e32 v224, v37, v145
	ds_read_b128 v[142:145], v219 offset:43088
	s_waitcnt lgkmcnt(11)
	v_fmac_f32_e32 v221, v38, v146
	v_fmac_f32_e32 v222, v39, v147
	v_fmac_f32_e32 v223, v40, v148
	v_fmac_f32_e32 v224, v41, v149
	ds_read_b128 v[146:149], v219 offset:43104
	s_waitcnt lgkmcnt(11)
	v_fmac_f32_e32 v221, v42, v150
	v_fmac_f32_e32 v222, v43, v151
	v_fmac_f32_e32 v223, v44, v152
	v_fmac_f32_e32 v224, v45, v153
	ds_read_b128 v[150:153], v219 offset:43120
	s_waitcnt lgkmcnt(11)
	v_fmac_f32_e32 v221, v46, v154
	v_fmac_f32_e32 v222, v47, v155
	v_fmac_f32_e32 v223, v48, v156
	v_fmac_f32_e32 v224, v49, v157
	ds_read_b128 v[154:157], v219 offset:43136
	s_waitcnt lgkmcnt(11)
	v_fmac_f32_e32 v221, v50, v158
	v_fmac_f32_e32 v222, v51, v159
	v_fmac_f32_e32 v223, v52, v160
	v_fmac_f32_e32 v224, v53, v161
	ds_read_b128 v[158:161], v219 offset:43152
	s_waitcnt lgkmcnt(11)
	v_fmac_f32_e32 v221, v54, v162
	v_fmac_f32_e32 v222, v55, v163
	v_fmac_f32_e32 v223, v56, v164
	v_fmac_f32_e32 v224, v57, v165
	ds_read_b128 v[162:165], v219 offset:43168
	s_waitcnt lgkmcnt(11)
	v_fmac_f32_e32 v221, v58, v166
	v_fmac_f32_e32 v222, v59, v167
	v_fmac_f32_e32 v223, v60, v168
	ds_read_b128 v[166:169], v219 offset:43184
	v_add_f32_e32 v225, v222, v221
	v_add_f32_e32 v226, v223, v224
	v_add_f32_e32 v225, v226, v225
	v_fma_f32 v61, v125, v61, -v225
	v_cvt_pk_bf16_f32 v230, v61, v61
	global_store_short v220, v230, s[4:5] offset:2816
	s_waitcnt lgkmcnt(11)
	v_mul_f32_e32 v221, v2, v170
	v_mul_f32_e32 v222, v3, v171
	v_mul_f32_e32 v223, v4, v172
	v_mul_f32_e32 v224, v5, v173
	ds_read_b128 v[170:173], v219 offset:43200
	s_waitcnt lgkmcnt(11)
	v_fmac_f32_e32 v221, v6, v174
	v_fmac_f32_e32 v222, v7, v175
	v_fmac_f32_e32 v223, v8, v176
	v_fmac_f32_e32 v224, v9, v177
	ds_read_b128 v[174:177], v219 offset:43216
	s_waitcnt lgkmcnt(11)
	v_fmac_f32_e32 v221, v10, v178
	v_fmac_f32_e32 v222, v11, v179
	v_fmac_f32_e32 v223, v12, v180
	v_fmac_f32_e32 v224, v13, v181
	ds_read_b128 v[178:181], v219 offset:43232
	s_waitcnt lgkmcnt(11)
	v_fmac_f32_e32 v221, v14, v134
	v_fmac_f32_e32 v222, v15, v135
	v_fmac_f32_e32 v223, v16, v136
	v_fmac_f32_e32 v224, v17, v137
	ds_read_b128 v[134:137], v219 offset:43264
	s_waitcnt lgkmcnt(11)
	v_fmac_f32_e32 v221, v18, v138
	v_fmac_f32_e32 v222, v19, v139
	v_fmac_f32_e32 v223, v20, v140
	v_fmac_f32_e32 v224, v21, v141
	ds_read_b128 v[138:141], v219 offset:43280
	s_waitcnt lgkmcnt(11)
	v_fmac_f32_e32 v221, v22, v142
	v_fmac_f32_e32 v222, v23, v143
	v_fmac_f32_e32 v223, v24, v144
	v_fmac_f32_e32 v224, v25, v145
	ds_read_b128 v[142:145], v219 offset:43296
	s_waitcnt lgkmcnt(11)
	v_fmac_f32_e32 v221, v26, v146
	v_fmac_f32_e32 v222, v27, v147
	v_fmac_f32_e32 v223, v28, v148
	v_fmac_f32_e32 v224, v29, v149
	ds_read_b128 v[146:149], v219 offset:43312
	s_waitcnt lgkmcnt(11)
	v_fmac_f32_e32 v221, v30, v150
	v_fmac_f32_e32 v222, v31, v151
	v_fmac_f32_e32 v223, v32, v152
	v_fmac_f32_e32 v224, v33, v153
	ds_read_b128 v[150:153], v219 offset:43328
	s_waitcnt lgkmcnt(11)
	v_fmac_f32_e32 v221, v34, v154
	v_fmac_f32_e32 v222, v35, v155
	v_fmac_f32_e32 v223, v36, v156
	v_fmac_f32_e32 v224, v37, v157
	ds_read_b128 v[154:157], v219 offset:43344
	s_waitcnt lgkmcnt(11)
	v_fmac_f32_e32 v221, v38, v158
	v_fmac_f32_e32 v222, v39, v159
	v_fmac_f32_e32 v223, v40, v160
	v_fmac_f32_e32 v224, v41, v161
	ds_read_b128 v[158:161], v219 offset:43360
	s_waitcnt lgkmcnt(11)
	v_fmac_f32_e32 v221, v42, v162
	v_fmac_f32_e32 v222, v43, v163
	v_fmac_f32_e32 v223, v44, v164
	v_fmac_f32_e32 v224, v45, v165
	ds_read_b128 v[162:165], v219 offset:43376
	s_waitcnt lgkmcnt(11)
	v_fmac_f32_e32 v221, v46, v166
	v_fmac_f32_e32 v222, v47, v167
	v_fmac_f32_e32 v223, v48, v168
	v_fmac_f32_e32 v224, v49, v169
	ds_read_b128 v[166:169], v219 offset:43392
	s_waitcnt lgkmcnt(11)
	v_fmac_f32_e32 v221, v50, v170
	v_fmac_f32_e32 v222, v51, v171
	v_fmac_f32_e32 v223, v52, v172
	v_fmac_f32_e32 v224, v53, v173
	ds_read_b128 v[170:173], v219 offset:43408
	s_waitcnt lgkmcnt(11)
	v_fmac_f32_e32 v221, v54, v174
	v_fmac_f32_e32 v222, v55, v175
	v_fmac_f32_e32 v223, v56, v176
	v_fmac_f32_e32 v224, v57, v177
	ds_read_b128 v[174:177], v219 offset:43424
	s_waitcnt lgkmcnt(11)
	v_fmac_f32_e32 v221, v58, v178
	v_fmac_f32_e32 v222, v59, v179
	v_fmac_f32_e32 v223, v60, v180
	v_fmac_f32_e32 v224, v61, v181
	ds_read_b128 v[178:181], v219 offset:43440
	v_add_f32_e32 v225, v222, v221
	v_add_f32_e32 v226, v223, v224
	v_add_f32_e32 v225, v226, v225
	v_fma_f32 v62, v126, v62, -v225
	v_cvt_pk_bf16_f32 v227, v62, v62
	global_store_short v220, v227, s[4:5] offset:3072
	s_waitcnt lgkmcnt(11)
	v_mul_f32_e32 v221, v2, v134
	v_mul_f32_e32 v222, v3, v135
	v_mul_f32_e32 v223, v4, v136
	v_mul_f32_e32 v224, v5, v137
	ds_read_b128 v[134:137], v219 offset:43456
	s_waitcnt lgkmcnt(11)
	v_fmac_f32_e32 v221, v6, v138
	v_fmac_f32_e32 v222, v7, v139
	v_fmac_f32_e32 v223, v8, v140
	v_fmac_f32_e32 v224, v9, v141
	ds_read_b128 v[138:141], v219 offset:43472
	s_waitcnt lgkmcnt(11)
	v_fmac_f32_e32 v221, v10, v142
	v_fmac_f32_e32 v222, v11, v143
	v_fmac_f32_e32 v223, v12, v144
	v_fmac_f32_e32 v224, v13, v145
	ds_read_b128 v[142:145], v219 offset:43488
	s_waitcnt lgkmcnt(11)
	v_fmac_f32_e32 v221, v14, v146
	v_fmac_f32_e32 v222, v15, v147
	v_fmac_f32_e32 v223, v16, v148
	v_fmac_f32_e32 v224, v17, v149
	ds_read_b128 v[146:149], v219 offset:43504
	s_waitcnt lgkmcnt(11)
	v_fmac_f32_e32 v221, v18, v150
	v_fmac_f32_e32 v222, v19, v151
	v_fmac_f32_e32 v223, v20, v152
	v_fmac_f32_e32 v224, v21, v153
	ds_read_b128 v[150:153], v219 offset:43520
	s_waitcnt lgkmcnt(11)
	v_fmac_f32_e32 v221, v22, v154
	v_fmac_f32_e32 v222, v23, v155
	v_fmac_f32_e32 v223, v24, v156
	v_fmac_f32_e32 v224, v25, v157
	ds_read_b128 v[154:157], v219 offset:43536
	s_waitcnt lgkmcnt(11)
	v_fmac_f32_e32 v221, v26, v158
	v_fmac_f32_e32 v222, v27, v159
	v_fmac_f32_e32 v223, v28, v160
	v_fmac_f32_e32 v224, v29, v161
	ds_read_b128 v[158:161], v219 offset:43552
	s_waitcnt lgkmcnt(11)
	v_fmac_f32_e32 v221, v30, v162
	v_fmac_f32_e32 v222, v31, v163
	v_fmac_f32_e32 v223, v32, v164
	v_fmac_f32_e32 v224, v33, v165
	ds_read_b128 v[162:165], v219 offset:43568
	s_waitcnt lgkmcnt(11)
	v_fmac_f32_e32 v221, v34, v166
	v_fmac_f32_e32 v222, v35, v167
	v_fmac_f32_e32 v223, v36, v168
	v_fmac_f32_e32 v224, v37, v169
	ds_read_b128 v[166:169], v219 offset:43584
	s_waitcnt lgkmcnt(11)
	v_fmac_f32_e32 v221, v38, v170
	v_fmac_f32_e32 v222, v39, v171
	v_fmac_f32_e32 v223, v40, v172
	v_fmac_f32_e32 v224, v41, v173
	ds_read_b128 v[170:173], v219 offset:43600
	s_waitcnt lgkmcnt(11)
	v_fmac_f32_e32 v221, v42, v174
	v_fmac_f32_e32 v222, v43, v175
	v_fmac_f32_e32 v223, v44, v176
	v_fmac_f32_e32 v224, v45, v177
	ds_read_b128 v[174:177], v219 offset:43616
	s_waitcnt lgkmcnt(11)
	v_fmac_f32_e32 v221, v46, v178
	v_fmac_f32_e32 v222, v47, v179
	v_fmac_f32_e32 v223, v48, v180
	v_fmac_f32_e32 v224, v49, v181
	ds_read_b128 v[178:181], v219 offset:43632
	s_waitcnt lgkmcnt(11)
	v_fmac_f32_e32 v221, v50, v134
	v_fmac_f32_e32 v222, v51, v135
	v_fmac_f32_e32 v223, v52, v136
	v_fmac_f32_e32 v224, v53, v137
	ds_read_b128 v[134:137], v219 offset:43648
	s_waitcnt lgkmcnt(11)
	v_fmac_f32_e32 v221, v54, v138
	v_fmac_f32_e32 v222, v55, v139
	v_fmac_f32_e32 v223, v56, v140
	v_fmac_f32_e32 v224, v57, v141
	ds_read_b128 v[138:141], v219 offset:43664
	s_waitcnt lgkmcnt(11)
	v_fmac_f32_e32 v221, v58, v142
	v_fmac_f32_e32 v222, v59, v143
	v_fmac_f32_e32 v223, v60, v144
	v_fmac_f32_e32 v224, v61, v145
	ds_read_b128 v[142:145], v219 offset:43680
	s_waitcnt lgkmcnt(11)
	v_fmac_f32_e32 v221, v62, v146
	ds_read_b128 v[146:149], v219 offset:43696
	v_add_f32_e32 v225, v222, v221
	v_add_f32_e32 v226, v223, v224
	v_add_f32_e32 v225, v226, v225
	v_fma_f32 v63, v127, v63, -v225
	v_cvt_pk_bf16_f32 v228, v63, v63
	global_store_short v220, v228, s[4:5] offset:3328
	s_waitcnt lgkmcnt(11)
	v_mul_f32_e32 v221, v2, v150
	v_mul_f32_e32 v222, v3, v151
	v_mul_f32_e32 v223, v4, v152
	v_mul_f32_e32 v224, v5, v153
	ds_read_b128 v[150:153], v219 offset:43712
	s_waitcnt lgkmcnt(11)
	v_fmac_f32_e32 v221, v6, v154
	v_fmac_f32_e32 v222, v7, v155
	v_fmac_f32_e32 v223, v8, v156
	v_fmac_f32_e32 v224, v9, v157
	ds_read_b128 v[154:157], v219 offset:43728
	s_waitcnt lgkmcnt(11)
	v_fmac_f32_e32 v221, v10, v158
	v_fmac_f32_e32 v222, v11, v159
	v_fmac_f32_e32 v223, v12, v160
	v_fmac_f32_e32 v224, v13, v161
	ds_read_b128 v[158:161], v219 offset:43744
	s_waitcnt lgkmcnt(11)
	v_fmac_f32_e32 v221, v14, v162
	v_fmac_f32_e32 v222, v15, v163
	v_fmac_f32_e32 v223, v16, v164
	v_fmac_f32_e32 v224, v17, v165
	ds_read_b128 v[162:165], v219 offset:43760
	s_waitcnt lgkmcnt(11)
	v_fmac_f32_e32 v221, v18, v166
	v_fmac_f32_e32 v222, v19, v167
	v_fmac_f32_e32 v223, v20, v168
	v_fmac_f32_e32 v224, v21, v169
	ds_read_b128 v[166:169], v219 offset:43776
	s_waitcnt lgkmcnt(11)
	v_fmac_f32_e32 v221, v22, v170
	v_fmac_f32_e32 v222, v23, v171
	v_fmac_f32_e32 v223, v24, v172
	v_fmac_f32_e32 v224, v25, v173
	ds_read_b128 v[170:173], v219 offset:43792
	s_waitcnt lgkmcnt(11)
	v_fmac_f32_e32 v221, v26, v174
	v_fmac_f32_e32 v222, v27, v175
	v_fmac_f32_e32 v223, v28, v176
	v_fmac_f32_e32 v224, v29, v177
	ds_read_b128 v[174:177], v219 offset:43808
	s_waitcnt lgkmcnt(11)
	v_fmac_f32_e32 v221, v30, v178
	v_fmac_f32_e32 v222, v31, v179
	v_fmac_f32_e32 v223, v32, v180
	v_fmac_f32_e32 v224, v33, v181
	ds_read_b128 v[178:181], v219 offset:43824
	s_waitcnt lgkmcnt(11)
	v_fmac_f32_e32 v221, v34, v134
	v_fmac_f32_e32 v222, v35, v135
	v_fmac_f32_e32 v223, v36, v136
	v_fmac_f32_e32 v224, v37, v137
	ds_read_b128 v[134:137], v219 offset:43840
	s_waitcnt lgkmcnt(11)
	v_fmac_f32_e32 v221, v38, v138
	v_fmac_f32_e32 v222, v39, v139
	v_fmac_f32_e32 v223, v40, v140
	v_fmac_f32_e32 v224, v41, v141
	ds_read_b128 v[138:141], v219 offset:43856
	s_waitcnt lgkmcnt(11)
	v_fmac_f32_e32 v221, v42, v142
	v_fmac_f32_e32 v222, v43, v143
	v_fmac_f32_e32 v223, v44, v144
	v_fmac_f32_e32 v224, v45, v145
	ds_read_b128 v[142:145], v219 offset:43872
	s_waitcnt lgkmcnt(11)
	v_fmac_f32_e32 v221, v46, v146
	v_fmac_f32_e32 v222, v47, v147
	v_fmac_f32_e32 v223, v48, v148
	v_fmac_f32_e32 v224, v49, v149
	ds_read_b128 v[146:149], v219 offset:43888
	s_waitcnt lgkmcnt(11)
	v_fmac_f32_e32 v221, v50, v150
	v_fmac_f32_e32 v222, v51, v151
	v_fmac_f32_e32 v223, v52, v152
	v_fmac_f32_e32 v224, v53, v153
	ds_read_b128 v[150:153], v219 offset:43904
	s_waitcnt lgkmcnt(11)
	v_fmac_f32_e32 v221, v54, v154
	v_fmac_f32_e32 v222, v55, v155
	v_fmac_f32_e32 v223, v56, v156
	v_fmac_f32_e32 v224, v57, v157
	ds_read_b128 v[154:157], v219 offset:43920
	s_waitcnt lgkmcnt(11)
	v_fmac_f32_e32 v221, v58, v158
	v_fmac_f32_e32 v222, v59, v159
	v_fmac_f32_e32 v223, v60, v160
	v_fmac_f32_e32 v224, v61, v161
	ds_read_b128 v[158:161], v219 offset:43936
	s_waitcnt lgkmcnt(11)
	v_fmac_f32_e32 v221, v62, v162
	v_fmac_f32_e32 v222, v63, v163
	ds_read_b128 v[162:165], v219 offset:43952
	v_add_f32_e32 v225, v222, v221
	v_add_f32_e32 v226, v223, v224
	v_add_f32_e32 v225, v226, v225
	v_fma_f32 v64, v128, v64, -v225
	v_cvt_pk_bf16_f32 v229, v64, v64
	global_store_short v220, v229, s[4:5] offset:3584
	s_waitcnt lgkmcnt(11)
	v_mul_f32_e32 v221, v2, v166
	v_mul_f32_e32 v222, v3, v167
	v_mul_f32_e32 v223, v4, v168
	v_mul_f32_e32 v224, v5, v169
	ds_read_b128 v[166:169], v219 offset:43968
	s_waitcnt lgkmcnt(11)
	v_fmac_f32_e32 v221, v6, v170
	v_fmac_f32_e32 v222, v7, v171
	v_fmac_f32_e32 v223, v8, v172
	v_fmac_f32_e32 v224, v9, v173
	ds_read_b128 v[170:173], v219 offset:43984
	s_waitcnt lgkmcnt(11)
	v_fmac_f32_e32 v221, v10, v174
	v_fmac_f32_e32 v222, v11, v175
	v_fmac_f32_e32 v223, v12, v176
	v_fmac_f32_e32 v224, v13, v177
	ds_read_b128 v[174:177], v219 offset:44000
	s_waitcnt lgkmcnt(11)
	v_fmac_f32_e32 v221, v14, v178
	v_fmac_f32_e32 v222, v15, v179
	v_fmac_f32_e32 v223, v16, v180
	v_fmac_f32_e32 v224, v17, v181
	ds_read_b128 v[178:181], v219 offset:44016
	s_waitcnt lgkmcnt(11)
	v_fmac_f32_e32 v221, v18, v134
	v_fmac_f32_e32 v222, v19, v135
	v_fmac_f32_e32 v223, v20, v136
	v_fmac_f32_e32 v224, v21, v137
	s_waitcnt lgkmcnt(10)
	v_fmac_f32_e32 v221, v22, v138
	v_fmac_f32_e32 v222, v23, v139
	v_fmac_f32_e32 v223, v24, v140
	v_fmac_f32_e32 v224, v25, v141
	s_waitcnt lgkmcnt(9)
	v_fmac_f32_e32 v221, v26, v142
	v_fmac_f32_e32 v222, v27, v143
	v_fmac_f32_e32 v223, v28, v144
	v_fmac_f32_e32 v224, v29, v145
	s_waitcnt lgkmcnt(8)
	v_fmac_f32_e32 v221, v30, v146
	v_fmac_f32_e32 v222, v31, v147
	v_fmac_f32_e32 v223, v32, v148
	v_fmac_f32_e32 v224, v33, v149
	s_waitcnt lgkmcnt(7)
	v_fmac_f32_e32 v221, v34, v150
	v_fmac_f32_e32 v222, v35, v151
	v_fmac_f32_e32 v223, v36, v152
	v_fmac_f32_e32 v224, v37, v153
	s_waitcnt lgkmcnt(6)
	v_fmac_f32_e32 v221, v38, v154
	v_fmac_f32_e32 v222, v39, v155
	v_fmac_f32_e32 v223, v40, v156
	v_fmac_f32_e32 v224, v41, v157
	s_waitcnt lgkmcnt(5)
	v_fmac_f32_e32 v221, v42, v158
	v_fmac_f32_e32 v222, v43, v159
	v_fmac_f32_e32 v223, v44, v160
	v_fmac_f32_e32 v224, v45, v161
	s_waitcnt lgkmcnt(4)
	v_fmac_f32_e32 v221, v46, v162
	v_fmac_f32_e32 v222, v47, v163
	v_fmac_f32_e32 v223, v48, v164
	v_fmac_f32_e32 v224, v49, v165
	s_waitcnt lgkmcnt(3)
	v_fmac_f32_e32 v221, v50, v166
	v_fmac_f32_e32 v222, v51, v167
	v_fmac_f32_e32 v223, v52, v168
	v_fmac_f32_e32 v224, v53, v169
	s_waitcnt lgkmcnt(2)
	v_fmac_f32_e32 v221, v54, v170
	v_fmac_f32_e32 v222, v55, v171
	v_fmac_f32_e32 v223, v56, v172
	v_fmac_f32_e32 v224, v57, v173
	s_waitcnt lgkmcnt(1)
	v_fmac_f32_e32 v221, v58, v174
	v_fmac_f32_e32 v222, v59, v175
	v_fmac_f32_e32 v223, v60, v176
	v_fmac_f32_e32 v224, v61, v177
	s_waitcnt lgkmcnt(0)
	v_fmac_f32_e32 v221, v62, v178
	v_fmac_f32_e32 v222, v63, v179
	v_fmac_f32_e32 v223, v64, v180
	v_add_f32_e32 v225, v222, v221
	v_add_f32_e32 v226, v223, v224
	v_add_f32_e32 v225, v226, v225
	v_fma_f32 v65, v129, v65, -v225
	v_cvt_pk_bf16_f32 v230, v65, v65
	global_store_short v220, v230, s[4:5] offset:3840
	s_waitcnt lgkmcnt(0)
	s_barrier
	s_branch .LBB0_393
